# GEMM K-loops: per-segment counted waits vmcnt(10) (5 phases of lead per DMA piece) instead of two vmcnt(6) per iteration
# baseline (speedup 1.0000x reference)
.LBB0_34:
	ds_read_b128 v[164:167], v151
	ds_read_b128 v[168:171], v151 offset:1024
	ds_read_b128 v[172:175], v151 offset:2048
	ds_read_b128 v[176:179], v151 offset:3072
	v_add_u32_e32 v162, 0xc000, v147
	v_lshl_add_u64 v[204:205], v[138:139], 0, s[12:13]
	v_readfirstlane_b32 s1, v162
	v_lshl_add_u64 v[210:211], v[204:205], 0, s[60:61]
	s_mov_b32 m0, s1
	v_add_u32_e32 v163, 0xe000, v147
	ds_read_b128 v[180:183], v0
	ds_read_b128 v[184:187], v0 offset:1024
	ds_read_b128 v[188:191], v0 offset:2048
	ds_read_b128 v[192:195], v0 offset:3072
	ds_read_b128 v[196:199], v0 offset:4096
	ds_read_b128 v[200:203], v0 offset:5120
	ds_read_b128 v[222:225], v0 offset:6144
	ds_read_b128 v[232:235], v0 offset:7168
	global_load_lds_dwordx4 v[210:211], off
	v_lshl_add_u64 v[210:211], v[140:141], 0, s[12:13]
	v_readfirstlane_b32 s1, v163
	v_lshl_add_u64 v[216:217], v[210:211], 0, s[60:61]
	s_mov_b32 m0, s1
	s_nop 0
	global_load_lds_dwordx4 v[216:217], off
	s_waitcnt lgkmcnt(8)
	s_waitcnt vmcnt(10)
	s_barrier
	s_waitcnt lgkmcnt(0)
	s_setprio 1
	s_waitcnt lgkmcnt(0)
	v_mfma_f32_16x16x32_bf16 v[126:129], v[164:167], v[180:183], v[126:129]
	v_mfma_f32_16x16x32_bf16 v[122:125], v[172:175], v[180:183], v[122:125]
	v_mfma_f32_16x16x32_bf16 v[118:121], v[164:167], v[188:191], v[118:121]
	v_mfma_f32_16x16x32_bf16 v[114:117], v[172:175], v[188:191], v[114:117]
	v_mfma_f32_16x16x32_bf16 v[110:113], v[164:167], v[196:199], v[110:113]
	v_mfma_f32_16x16x32_bf16 v[106:109], v[172:175], v[196:199], v[106:109]
	v_mfma_f32_16x16x32_bf16 v[102:105], v[164:167], v[222:225], v[102:105]
	v_mfma_f32_16x16x32_bf16 v[98:101], v[172:175], v[222:225], v[98:101]
	v_mfma_f32_16x16x32_bf16 v[126:129], v[168:171], v[184:187], v[126:129]
	v_mfma_f32_16x16x32_bf16 v[122:125], v[176:179], v[184:187], v[122:125]
	v_mfma_f32_16x16x32_bf16 v[118:121], v[168:171], v[192:195], v[118:121]
	v_mfma_f32_16x16x32_bf16 v[114:117], v[176:179], v[192:195], v[114:117]
	v_mfma_f32_16x16x32_bf16 v[110:113], v[168:171], v[200:203], v[110:113]
	v_mfma_f32_16x16x32_bf16 v[106:109], v[176:179], v[200:203], v[106:109]
	v_mfma_f32_16x16x32_bf16 v[102:105], v[168:171], v[232:235], v[102:105]
	v_mfma_f32_16x16x32_bf16 v[98:101], v[176:179], v[232:235], v[98:101]
	s_setprio 0
	s_barrier
	v_lshl_add_u64 v[216:217], v[134:135], 0, s[12:13]
	v_readfirstlane_b32 s1, v149
	v_lshl_add_u64 v[218:219], v[216:217], 0, s[74:75]
	s_mov_b32 m0, s1
	ds_read_b128 v[236:239], v151 offset:16384
	ds_read_b128 v[240:243], v151 offset:17408
	ds_read_b128 v[244:247], v151 offset:18432
	ds_read_b128 v[248:251], v151 offset:19456
	global_load_lds_dwordx4 v[218:219], off
	v_lshl_add_u64 v[218:219], v[136:137], 0, s[12:13]
	v_readfirstlane_b32 s1, v150
	v_lshl_add_u64 v[228:229], v[218:219], 0, s[74:75]
	s_mov_b32 m0, s1
	s_nop 0
	global_load_lds_dwordx4 v[228:229], off
	s_waitcnt vmcnt(10)
	s_barrier
	s_waitcnt lgkmcnt(0)
	s_setprio 1
	s_waitcnt lgkmcnt(0)
	v_mfma_f32_16x16x32_bf16 v[94:97], v[236:239], v[180:183], v[94:97]
	v_mfma_f32_16x16x32_bf16 v[90:93], v[244:247], v[180:183], v[90:93]
	v_mfma_f32_16x16x32_bf16 v[86:89], v[236:239], v[188:191], v[86:89]
	v_mfma_f32_16x16x32_bf16 v[70:73], v[244:247], v[188:191], v[70:73]
	v_mfma_f32_16x16x32_bf16 v[62:65], v[236:239], v[196:199], v[62:65]
	v_mfma_f32_16x16x32_bf16 v[58:61], v[244:247], v[196:199], v[58:61]
	v_mfma_f32_16x16x32_bf16 v[54:57], v[236:239], v[222:225], v[54:57]
	v_mfma_f32_16x16x32_bf16 v[50:53], v[244:247], v[222:225], v[50:53]
	v_mfma_f32_16x16x32_bf16 v[94:97], v[240:243], v[184:187], v[94:97]
	v_mfma_f32_16x16x32_bf16 v[90:93], v[248:251], v[184:187], v[90:93]
	v_mfma_f32_16x16x32_bf16 v[86:89], v[240:243], v[192:195], v[86:89]
	v_mfma_f32_16x16x32_bf16 v[70:73], v[248:251], v[192:195], v[70:73]
	v_mfma_f32_16x16x32_bf16 v[62:65], v[240:243], v[200:203], v[62:65]
	v_mfma_f32_16x16x32_bf16 v[58:61], v[248:251], v[200:203], v[58:61]
	v_mfma_f32_16x16x32_bf16 v[54:57], v[240:243], v[232:235], v[54:57]
	v_mfma_f32_16x16x32_bf16 v[50:53], v[248:251], v[232:235], v[50:53]
	s_setprio 0
	v_readfirstlane_b32 s1, v147
	v_lshl_add_u64 v[228:229], v[204:205], 0, s[74:75]
	s_mov_b32 m0, s1
	v_readfirstlane_b32 s1, v148
	s_barrier
	ds_read_b128 v[180:183], v0 offset:16384
	ds_read_b128 v[184:187], v0 offset:17408
	ds_read_b128 v[188:191], v0 offset:18432
	ds_read_b128 v[192:195], v0 offset:19456
	ds_read_b128 v[196:199], v0 offset:20480
	ds_read_b128 v[200:203], v0 offset:21504
	ds_read_b128 v[222:225], v0 offset:22528
	ds_read_b128 v[232:235], v0 offset:23552
	global_load_lds_dwordx4 v[228:229], off
	v_lshl_add_u64 v[228:229], v[210:211], 0, s[74:75]
	s_mov_b32 m0, s1
	s_nop 0
	global_load_lds_dwordx4 v[228:229], off
	s_barrier
	s_waitcnt lgkmcnt(0)
	s_setprio 1
	s_waitcnt lgkmcnt(0)
	v_mfma_f32_16x16x32_bf16 v[46:49], v[164:167], v[180:183], v[46:49]
	v_mfma_f32_16x16x32_bf16 v[42:45], v[172:175], v[180:183], v[42:45]
	v_mfma_f32_16x16x32_bf16 v[38:41], v[164:167], v[188:191], v[38:41]
	v_mfma_f32_16x16x32_bf16 v[34:37], v[172:175], v[188:191], v[34:37]
	v_mfma_f32_16x16x32_bf16 v[30:33], v[164:167], v[196:199], v[30:33]
	v_mfma_f32_16x16x32_bf16 v[26:29], v[172:175], v[196:199], v[26:29]
	v_mfma_f32_16x16x32_bf16 v[22:25], v[164:167], v[222:225], v[22:25]
	v_mfma_f32_16x16x32_bf16 v[18:21], v[172:175], v[222:225], v[18:21]
	v_mfma_f32_16x16x32_bf16 v[46:49], v[168:171], v[184:187], v[46:49]
	v_mfma_f32_16x16x32_bf16 v[42:45], v[176:179], v[184:187], v[42:45]
	v_mfma_f32_16x16x32_bf16 v[38:41], v[168:171], v[192:195], v[38:41]
	v_mfma_f32_16x16x32_bf16 v[34:37], v[176:179], v[192:195], v[34:37]
	v_mfma_f32_16x16x32_bf16 v[30:33], v[168:171], v[200:203], v[30:33]
	v_mfma_f32_16x16x32_bf16 v[26:29], v[176:179], v[200:203], v[26:29]
	v_mfma_f32_16x16x32_bf16 v[22:25], v[168:171], v[232:235], v[22:25]
	v_mfma_f32_16x16x32_bf16 v[18:21], v[176:179], v[232:235], v[18:21]
	s_setprio 0
	s_barrier
	v_readfirstlane_b32 s1, v152
	v_lshl_add_u64 v[164:165], v[216:217], 0, s[18:19]
	s_mov_b32 m0, s1
	v_readfirstlane_b32 s1, v153
	global_load_lds_dwordx4 v[164:165], off
	v_lshl_add_u64 v[164:165], v[218:219], 0, s[18:19]
	s_mov_b32 m0, s1
	s_nop 0
	global_load_lds_dwordx4 v[164:165], off
	s_waitcnt vmcnt(10)
	s_barrier
	s_setprio 1
	v_mfma_f32_16x16x32_bf16 v[14:17], v[236:239], v[180:183], v[14:17]
	v_mfma_f32_16x16x32_bf16 v[10:13], v[244:247], v[180:183], v[10:13]
	v_mfma_f32_16x16x32_bf16 v[6:9], v[236:239], v[188:191], v[6:9]
	v_mfma_f32_16x16x32_bf16 v[2:5], v[244:247], v[188:191], v[2:5]
	v_mfma_f32_16x16x32_bf16 v[66:69], v[236:239], v[196:199], v[66:69]
	v_mfma_f32_16x16x32_bf16 v[74:77], v[244:247], v[196:199], v[74:77]
	v_mfma_f32_16x16x32_bf16 v[78:81], v[236:239], v[222:225], v[78:81]
	v_mfma_f32_16x16x32_bf16 v[82:85], v[244:247], v[222:225], v[82:85]
	v_mfma_f32_16x16x32_bf16 v[14:17], v[240:243], v[184:187], v[14:17]
	v_mfma_f32_16x16x32_bf16 v[10:13], v[248:251], v[184:187], v[10:13]
	v_mfma_f32_16x16x32_bf16 v[6:9], v[240:243], v[192:195], v[6:9]
	v_mfma_f32_16x16x32_bf16 v[2:5], v[248:251], v[192:195], v[2:5]
	v_mfma_f32_16x16x32_bf16 v[66:69], v[240:243], v[200:203], v[66:69]
	v_mfma_f32_16x16x32_bf16 v[74:77], v[248:251], v[200:203], v[74:77]
	v_mfma_f32_16x16x32_bf16 v[78:81], v[240:243], v[232:235], v[78:81]
	v_mfma_f32_16x16x32_bf16 v[82:85], v[248:251], v[232:235], v[82:85]
	s_setprio 0
	s_barrier
	ds_read_b128 v[164:167], v151 offset:32768
	ds_read_b128 v[168:171], v151 offset:33792
	ds_read_b128 v[172:175], v151 offset:34816
	ds_read_b128 v[176:179], v151 offset:35840
	v_readfirstlane_b32 s1, v154
	v_lshl_add_u64 v[228:229], v[204:205], 0, s[18:19]
	s_mov_b32 m0, s1
	v_readfirstlane_b32 s1, v155
	ds_read_b128 v[180:183], v0 offset:32768
	ds_read_b128 v[184:187], v0 offset:33792
	ds_read_b128 v[188:191], v0 offset:34816
	ds_read_b128 v[192:195], v0 offset:35840
	ds_read_b128 v[196:199], v0 offset:36864
	ds_read_b128 v[200:203], v0 offset:37888
	ds_read_b128 v[222:225], v0 offset:38912
	ds_read_b128 v[232:235], v0 offset:39936
	global_load_lds_dwordx4 v[228:229], off
	v_lshl_add_u64 v[228:229], v[210:211], 0, s[18:19]
	s_mov_b32 m0, s1
	s_nop 0
	global_load_lds_dwordx4 v[228:229], off
	s_waitcnt lgkmcnt(8)
	s_waitcnt vmcnt(10)
	s_barrier
	s_waitcnt lgkmcnt(0)
	s_setprio 1
	s_waitcnt lgkmcnt(0)
	v_mfma_f32_16x16x32_bf16 v[126:129], v[164:167], v[180:183], v[126:129]
	v_mfma_f32_16x16x32_bf16 v[122:125], v[172:175], v[180:183], v[122:125]
	v_mfma_f32_16x16x32_bf16 v[118:121], v[164:167], v[188:191], v[118:121]
	v_mfma_f32_16x16x32_bf16 v[114:117], v[172:175], v[188:191], v[114:117]
	v_mfma_f32_16x16x32_bf16 v[110:113], v[164:167], v[196:199], v[110:113]
	v_mfma_f32_16x16x32_bf16 v[106:109], v[172:175], v[196:199], v[106:109]
	v_mfma_f32_16x16x32_bf16 v[102:105], v[164:167], v[222:225], v[102:105]
	v_mfma_f32_16x16x32_bf16 v[98:101], v[172:175], v[222:225], v[98:101]
	v_mfma_f32_16x16x32_bf16 v[126:129], v[168:171], v[184:187], v[126:129]
	v_mfma_f32_16x16x32_bf16 v[122:125], v[176:179], v[184:187], v[122:125]
	v_mfma_f32_16x16x32_bf16 v[118:121], v[168:171], v[192:195], v[118:121]
	v_mfma_f32_16x16x32_bf16 v[114:117], v[176:179], v[192:195], v[114:117]
	v_mfma_f32_16x16x32_bf16 v[110:113], v[168:171], v[200:203], v[110:113]
	v_mfma_f32_16x16x32_bf16 v[106:109], v[176:179], v[200:203], v[106:109]
	v_mfma_f32_16x16x32_bf16 v[102:105], v[168:171], v[232:235], v[102:105]
	v_mfma_f32_16x16x32_bf16 v[98:101], v[176:179], v[232:235], v[98:101]
	s_setprio 0
	s_barrier
	v_readfirstlane_b32 s1, v156
	v_lshl_add_u64 v[228:229], v[216:217], 0, s[28:29]
	s_mov_b32 m0, s1
	v_readfirstlane_b32 s1, v157
	ds_read_b128 v[236:239], v151 offset:49152
	ds_read_b128 v[240:243], v151 offset:50176
	ds_read_b128 v[244:247], v151 offset:51200
	ds_read_b128 v[248:251], v151 offset:52224
	global_load_lds_dwordx4 v[228:229], off
	v_lshl_add_u64 v[228:229], v[218:219], 0, s[28:29]
	s_mov_b32 m0, s1
	s_nop 0
	global_load_lds_dwordx4 v[228:229], off
	s_waitcnt vmcnt(10)
	s_barrier
	s_waitcnt lgkmcnt(0)
	s_setprio 1
	s_waitcnt lgkmcnt(0)
	v_mfma_f32_16x16x32_bf16 v[94:97], v[236:239], v[180:183], v[94:97]
	v_mfma_f32_16x16x32_bf16 v[90:93], v[244:247], v[180:183], v[90:93]
	v_mfma_f32_16x16x32_bf16 v[86:89], v[236:239], v[188:191], v[86:89]
	v_mfma_f32_16x16x32_bf16 v[70:73], v[244:247], v[188:191], v[70:73]
	v_mfma_f32_16x16x32_bf16 v[62:65], v[236:239], v[196:199], v[62:65]
	v_mfma_f32_16x16x32_bf16 v[58:61], v[244:247], v[196:199], v[58:61]
	v_mfma_f32_16x16x32_bf16 v[54:57], v[236:239], v[222:225], v[54:57]
	v_mfma_f32_16x16x32_bf16 v[50:53], v[244:247], v[222:225], v[50:53]
	v_mfma_f32_16x16x32_bf16 v[94:97], v[240:243], v[184:187], v[94:97]
	v_mfma_f32_16x16x32_bf16 v[90:93], v[248:251], v[184:187], v[90:93]
	v_mfma_f32_16x16x32_bf16 v[86:89], v[240:243], v[192:195], v[86:89]
	v_mfma_f32_16x16x32_bf16 v[70:73], v[248:251], v[192:195], v[70:73]
	v_mfma_f32_16x16x32_bf16 v[62:65], v[240:243], v[200:203], v[62:65]
	v_mfma_f32_16x16x32_bf16 v[58:61], v[248:251], v[200:203], v[58:61]
	v_mfma_f32_16x16x32_bf16 v[54:57], v[240:243], v[232:235], v[54:57]
	v_mfma_f32_16x16x32_bf16 v[50:53], v[248:251], v[232:235], v[50:53]
	s_setprio 0
	v_readfirstlane_b32 s1, v158
	v_lshl_add_u64 v[204:205], v[204:205], 0, s[28:29]
	s_mov_b32 m0, s1
	v_readfirstlane_b32 s1, v159
	s_barrier
	ds_read_b128 v[180:183], v0 offset:49152
	ds_read_b128 v[184:187], v0 offset:50176
	ds_read_b128 v[188:191], v0 offset:51200
	ds_read_b128 v[192:195], v0 offset:52224
	ds_read_b128 v[196:199], v0 offset:53248
	ds_read_b128 v[200:203], v0 offset:54272
	ds_read_b128 v[222:225], v0 offset:55296
	ds_read_b128 v[232:235], v0 offset:56320
	global_load_lds_dwordx4 v[204:205], off
	v_lshl_add_u64 v[204:205], v[210:211], 0, s[28:29]
	s_mov_b32 m0, s1
	s_nop 0
	global_load_lds_dwordx4 v[204:205], off
	s_barrier
	s_waitcnt lgkmcnt(0)
	s_setprio 1
	s_waitcnt lgkmcnt(0)
	v_mfma_f32_16x16x32_bf16 v[46:49], v[164:167], v[180:183], v[46:49]
	v_mfma_f32_16x16x32_bf16 v[42:45], v[172:175], v[180:183], v[42:45]
	v_mfma_f32_16x16x32_bf16 v[38:41], v[164:167], v[188:191], v[38:41]
	v_mfma_f32_16x16x32_bf16 v[34:37], v[172:175], v[188:191], v[34:37]
	v_mfma_f32_16x16x32_bf16 v[30:33], v[164:167], v[196:199], v[30:33]
	v_mfma_f32_16x16x32_bf16 v[26:29], v[172:175], v[196:199], v[26:29]
	v_mfma_f32_16x16x32_bf16 v[22:25], v[164:167], v[222:225], v[22:25]
	v_mfma_f32_16x16x32_bf16 v[18:21], v[172:175], v[222:225], v[18:21]
	v_mfma_f32_16x16x32_bf16 v[46:49], v[168:171], v[184:187], v[46:49]
	v_mfma_f32_16x16x32_bf16 v[42:45], v[176:179], v[184:187], v[42:45]
	v_mfma_f32_16x16x32_bf16 v[38:41], v[168:171], v[192:195], v[38:41]
	v_mfma_f32_16x16x32_bf16 v[34:37], v[176:179], v[192:195], v[34:37]
	v_mfma_f32_16x16x32_bf16 v[30:33], v[168:171], v[200:203], v[30:33]
	v_mfma_f32_16x16x32_bf16 v[26:29], v[176:179], v[200:203], v[26:29]
	v_mfma_f32_16x16x32_bf16 v[22:25], v[168:171], v[232:235], v[22:25]
	v_mfma_f32_16x16x32_bf16 v[18:21], v[176:179], v[232:235], v[18:21]
	s_setprio 0
	s_barrier
	v_readfirstlane_b32 s1, v160
	v_lshl_add_u64 v[164:165], v[216:217], 0, s[30:31]
	s_mov_b32 m0, s1
	v_readfirstlane_b32 s1, v161
	global_load_lds_dwordx4 v[164:165], off
	v_lshl_add_u64 v[164:165], v[218:219], 0, s[30:31]
	s_mov_b32 m0, s1
	s_nop 0
	global_load_lds_dwordx4 v[164:165], off
	s_waitcnt vmcnt(10)
	s_barrier
	s_setprio 1
	v_mfma_f32_16x16x32_bf16 v[14:17], v[236:239], v[180:183], v[14:17]
	v_mfma_f32_16x16x32_bf16 v[10:13], v[244:247], v[180:183], v[10:13]
	v_mfma_f32_16x16x32_bf16 v[6:9], v[236:239], v[188:191], v[6:9]
	v_mfma_f32_16x16x32_bf16 v[2:5], v[244:247], v[188:191], v[2:5]
	v_mfma_f32_16x16x32_bf16 v[66:69], v[236:239], v[196:199], v[66:69]
	v_mfma_f32_16x16x32_bf16 v[74:77], v[244:247], v[196:199], v[74:77]
	v_mfma_f32_16x16x32_bf16 v[78:81], v[236:239], v[222:225], v[78:81]
	v_mfma_f32_16x16x32_bf16 v[82:85], v[244:247], v[222:225], v[82:85]
	v_mfma_f32_16x16x32_bf16 v[14:17], v[240:243], v[184:187], v[14:17]
	v_mfma_f32_16x16x32_bf16 v[10:13], v[248:251], v[184:187], v[10:13]
	v_mfma_f32_16x16x32_bf16 v[6:9], v[240:243], v[192:195], v[6:9]
	v_mfma_f32_16x16x32_bf16 v[2:5], v[248:251], v[192:195], v[2:5]
	v_mfma_f32_16x16x32_bf16 v[66:69], v[240:243], v[200:203], v[66:69]
	v_mfma_f32_16x16x32_bf16 v[74:77], v[248:251], v[200:203], v[74:77]
	v_mfma_f32_16x16x32_bf16 v[78:81], v[240:243], v[232:235], v[78:81]
	v_mfma_f32_16x16x32_bf16 v[82:85], v[248:251], v[232:235], v[82:85]
	s_setprio 0
	s_add_i32 s0, s0, 2
	s_add_u32 s12, s12, 0x100
	s_addc_u32 s13, s13, 0
	s_cmp_lt_u32 s0, 28
	s_barrier
	s_cbranch_scc1 .LBB0_34
	s_mov_b64 s[12:13], 0xf80
	v_readfirstlane_b32 s0, v162
	v_lshl_add_u64 v[132:133], v[132:133], 0, s[12:13]
	s_mov_b32 m0, s0
	v_readfirstlane_b32 s0, v163
	ds_read_b128 v[134:137], v151
	ds_read_b128 v[138:141], v151 offset:1024
	ds_read_b128 v[152:155], v151 offset:2048
	ds_read_b128 v[156:159], v151 offset:3072
	ds_read_b128 v[164:167], v0
	ds_read_b128 v[168:171], v0 offset:1024
	ds_read_b128 v[172:175], v0 offset:2048
	ds_read_b128 v[176:179], v0 offset:3072
	ds_read_b128 v[180:183], v0 offset:4096
	ds_read_b128 v[184:187], v0 offset:5120
	ds_read_b128 v[188:191], v0 offset:6144
	ds_read_b128 v[192:195], v0 offset:7168
	global_load_lds_dwordx4 v[132:133], off
	v_lshl_add_u64 v[130:131], v[130:131], 0, s[12:13]
	s_mov_b32 m0, s0
	s_nop 0
	global_load_lds_dwordx4 v[130:131], off
	s_barrier
	s_waitcnt lgkmcnt(0)
	s_setprio 1
	s_waitcnt lgkmcnt(0)
	v_mfma_f32_16x16x32_bf16 v[122:125], v[152:155], v[164:167], v[122:125]
	v_mfma_f32_16x16x32_bf16 v[118:121], v[134:137], v[172:175], v[118:121]
	v_mfma_f32_16x16x32_bf16 v[114:117], v[152:155], v[172:175], v[114:117]
	v_mfma_f32_16x16x32_bf16 v[102:105], v[134:137], v[188:191], v[102:105]
	v_mfma_f32_16x16x32_bf16 v[98:101], v[152:155], v[188:191], v[98:101]
	v_mfma_f32_16x16x32_bf16 v[126:129], v[134:137], v[164:167], v[126:129]
	v_mfma_f32_16x16x32_bf16 v[122:125], v[156:159], v[168:171], v[122:125]
	v_mfma_f32_16x16x32_bf16 v[118:121], v[138:141], v[176:179], v[118:121]
	v_mfma_f32_16x16x32_bf16 v[114:117], v[156:159], v[176:179], v[114:117]
	v_mfma_f32_16x16x32_bf16 v[110:113], v[134:137], v[180:183], v[110:113]
	v_mfma_f32_16x16x32_bf16 v[106:109], v[152:155], v[180:183], v[106:109]
	v_mfma_f32_16x16x32_bf16 v[102:105], v[138:141], v[192:195], v[102:105]
	v_mfma_f32_16x16x32_bf16 v[98:101], v[156:159], v[192:195], v[98:101]
	v_mfma_f32_16x16x32_bf16 v[126:129], v[138:141], v[168:171], v[126:129]
	v_mfma_f32_16x16x32_bf16 v[130:133], v[138:141], v[184:187], v[110:113]
	v_mfma_f32_16x16x32_bf16 v[160:163], v[156:159], v[184:187], v[106:109]
	s_setprio 0
	s_barrier
	ds_read_b128 v[106:109], v151 offset:16384
	ds_read_b128 v[110:113], v151 offset:17408
	ds_read_b128 v[196:199], v151 offset:18432
	ds_read_b128 v[200:203], v151 offset:19456
	s_barrier
	s_waitcnt lgkmcnt(0)
	s_setprio 1
	s_waitcnt lgkmcnt(3)
	v_mfma_f32_16x16x32_bf16 v[86:89], v[106:109], v[172:175], v[86:89]
	s_waitcnt lgkmcnt(1)
	v_mfma_f32_16x16x32_bf16 v[70:73], v[196:199], v[172:175], v[70:73]
	v_mfma_f32_16x16x32_bf16 v[62:65], v[106:109], v[180:183], v[62:65]
	v_mfma_f32_16x16x32_bf16 v[58:61], v[196:199], v[180:183], v[58:61]
	v_mfma_f32_16x16x32_bf16 v[54:57], v[106:109], v[188:191], v[54:57]
	v_mfma_f32_16x16x32_bf16 v[50:53], v[196:199], v[188:191], v[50:53]
	v_mfma_f32_16x16x32_bf16 v[94:97], v[106:109], v[164:167], v[94:97]
	v_mfma_f32_16x16x32_bf16 v[90:93], v[196:199], v[164:167], v[90:93]
	v_mfma_f32_16x16x32_bf16 v[86:89], v[110:113], v[176:179], v[86:89]
	s_waitcnt lgkmcnt(0)
	v_mfma_f32_16x16x32_bf16 v[70:73], v[200:203], v[176:179], v[70:73]
	v_mfma_f32_16x16x32_bf16 v[62:65], v[110:113], v[184:187], v[62:65]
	v_mfma_f32_16x16x32_bf16 v[58:61], v[200:203], v[184:187], v[58:61]
	v_mfma_f32_16x16x32_bf16 v[54:57], v[110:113], v[192:195], v[54:57]
	v_mfma_f32_16x16x32_bf16 v[50:53], v[200:203], v[192:195], v[50:53]
	v_mfma_f32_16x16x32_bf16 v[222:225], v[110:113], v[168:171], v[94:97]
	v_mfma_f32_16x16x32_bf16 v[164:167], v[200:203], v[168:171], v[90:93]
	s_setprio 0
	s_barrier
	s_nop 0
	ds_read_b128 v[90:93], v0 offset:16384
	ds_read_b128 v[94:97], v0 offset:17408
	ds_read_b128 v[168:171], v0 offset:18432
	ds_read_b128 v[172:175], v0 offset:19456
	ds_read_b128 v[176:179], v0 offset:20480
	ds_read_b128 v[180:183], v0 offset:21504
	ds_read_b128 v[184:187], v0 offset:22528
	ds_read_b128 v[188:191], v0 offset:23552
	s_waitcnt vmcnt(4)
	s_barrier
	s_waitcnt lgkmcnt(0)
	s_setprio 1
	s_waitcnt lgkmcnt(7)
	v_mfma_f32_16x16x32_bf16 v[46:49], v[134:137], v[90:93], v[46:49]
	v_mfma_f32_16x16x32_bf16 v[42:45], v[152:155], v[90:93], v[42:45]
	s_waitcnt lgkmcnt(5)
	v_mfma_f32_16x16x32_bf16 v[38:41], v[134:137], v[168:171], v[38:41]
	v_mfma_f32_16x16x32_bf16 v[34:37], v[152:155], v[168:171], v[34:37]
	s_waitcnt lgkmcnt(3)
	v_mfma_f32_16x16x32_bf16 v[30:33], v[134:137], v[176:179], v[30:33]
	v_mfma_f32_16x16x32_bf16 v[26:29], v[152:155], v[176:179], v[26:29]
	s_waitcnt lgkmcnt(1)
	v_mfma_f32_16x16x32_bf16 v[22:25], v[134:137], v[184:187], v[22:25]
	v_mfma_f32_16x16x32_bf16 v[18:21], v[152:155], v[184:187], v[18:21]
	v_mfma_f32_16x16x32_bf16 v[46:49], v[138:141], v[94:97], v[46:49]
	v_mfma_f32_16x16x32_bf16 v[42:45], v[156:159], v[94:97], v[42:45]
	v_mfma_f32_16x16x32_bf16 v[38:41], v[138:141], v[172:175], v[38:41]
	v_mfma_f32_16x16x32_bf16 v[34:37], v[156:159], v[172:175], v[34:37]
	v_mfma_f32_16x16x32_bf16 v[30:33], v[138:141], v[180:183], v[30:33]
	v_mfma_f32_16x16x32_bf16 v[26:29], v[156:159], v[180:183], v[26:29]
	s_waitcnt lgkmcnt(0)
	v_mfma_f32_16x16x32_bf16 v[22:25], v[138:141], v[188:191], v[22:25]
	v_mfma_f32_16x16x32_bf16 v[18:21], v[156:159], v[188:191], v[18:21]
	s_setprio 0
	s_setprio 1
	v_mfma_f32_16x16x32_bf16 v[10:13], v[196:199], v[90:93], v[10:13]
	v_mfma_f32_16x16x32_bf16 v[152:155], v[200:203], v[94:97], v[10:13]
	v_mfma_f32_16x16x32_bf16 v[10:13], v[106:109], v[176:179], v[66:69]
	v_mfma_f32_16x16x32_bf16 v[156:159], v[110:113], v[180:183], v[10:13]
	v_mfma_f32_16x16x32_bf16 v[10:13], v[196:199], v[176:179], v[74:77]
	v_mfma_f32_16x16x32_bf16 v[6:9], v[106:109], v[168:171], v[6:9]
	v_mfma_f32_16x16x32_bf16 v[2:5], v[196:199], v[168:171], v[2:5]
	v_mfma_f32_16x16x32_bf16 v[168:171], v[200:203], v[180:183], v[10:13]
	v_mfma_f32_16x16x32_bf16 v[10:13], v[106:109], v[184:187], v[78:81]
	v_mfma_f32_16x16x32_bf16 v[14:17], v[106:109], v[90:93], v[14:17]
	v_mfma_f32_16x16x32_bf16 v[6:9], v[110:113], v[172:175], v[6:9]
	v_mfma_f32_16x16x32_bf16 v[2:5], v[200:203], v[172:175], v[2:5]
	v_mfma_f32_16x16x32_bf16 v[172:175], v[110:113], v[188:191], v[10:13]
	v_mfma_f32_16x16x32_bf16 v[10:13], v[196:199], v[184:187], v[82:85]
	v_mfma_f32_16x16x32_bf16 v[134:137], v[110:113], v[94:97], v[14:17]
	v_mfma_f32_16x16x32_bf16 v[176:179], v[200:203], v[188:191], v[10:13]
	s_setprio 0
	s_barrier
	s_nop 3
	ds_read_b128 v[10:13], v151 offset:32768
	ds_read_b128 v[14:17], v151 offset:33792
	ds_read_b128 v[180:183], v151 offset:34816
	ds_read_b128 v[184:187], v151 offset:35840
	ds_read_b128 v[66:69], v0 offset:32768
	ds_read_b128 v[82:85], v0 offset:33792
	ds_read_b128 v[188:191], v0 offset:34816
	ds_read_b128 v[192:195], v0 offset:35840
	ds_read_b128 v[196:199], v0 offset:36864
	ds_read_b128 v[200:203], v0 offset:37888
	ds_read_b128 v[232:235], v0 offset:38912
	ds_read_b128 v[236:239], v0 offset:39936
	s_waitcnt vmcnt(2)
	s_barrier
	s_waitcnt lgkmcnt(0)
	s_setprio 1
	s_waitcnt lgkmcnt(7)
	v_mfma_f32_16x16x32_bf16 v[74:77], v[10:13], v[66:69], v[126:129]
	s_waitcnt lgkmcnt(6)
	v_mfma_f32_16x16x32_bf16 v[138:141], v[14:17], v[82:85], v[74:77]
	v_mfma_f32_16x16x32_bf16 v[74:77], v[180:183], v[66:69], v[122:125]
	v_mfma_f32_16x16x32_bf16 v[122:125], v[184:187], v[82:85], v[74:77]
	s_waitcnt lgkmcnt(5)
	v_mfma_f32_16x16x32_bf16 v[74:77], v[10:13], v[188:191], v[118:121]
	s_waitcnt lgkmcnt(4)
	v_mfma_f32_16x16x32_bf16 v[110:113], v[14:17], v[192:195], v[74:77]
	v_mfma_f32_16x16x32_bf16 v[74:77], v[180:183], v[188:191], v[114:117]
	v_mfma_f32_16x16x32_bf16 v[106:109], v[184:187], v[192:195], v[74:77]
	s_waitcnt lgkmcnt(3)
	v_mfma_f32_16x16x32_bf16 v[74:77], v[10:13], v[196:199], v[130:133]
	s_waitcnt lgkmcnt(2)
	v_mfma_f32_16x16x32_bf16 v[94:97], v[14:17], v[200:203], v[74:77]
	v_mfma_f32_16x16x32_bf16 v[74:77], v[180:183], v[196:199], v[160:163]
	v_mfma_f32_16x16x32_bf16 v[90:93], v[184:187], v[200:203], v[74:77]
	s_waitcnt lgkmcnt(1)
	v_mfma_f32_16x16x32_bf16 v[74:77], v[10:13], v[232:235], v[102:105]
	s_waitcnt lgkmcnt(0)
	v_mfma_f32_16x16x32_bf16 v[78:81], v[14:17], v[236:239], v[74:77]
	v_mfma_f32_16x16x32_bf16 v[74:77], v[180:183], v[232:235], v[98:101]
	v_mfma_f32_16x16x32_bf16 v[74:77], v[184:187], v[236:239], v[74:77]
	s_setprio 0
	s_barrier
	ds_read_b128 v[126:129], v151 offset:49152
	ds_read_b128 v[130:133], v151 offset:50176
	ds_read_b128 v[160:163], v151 offset:51200
	ds_read_b128 v[148:151], v151 offset:52224
	s_waitcnt vmcnt(0)
	s_barrier
	s_waitcnt lgkmcnt(0)
	s_setprio 1
	s_waitcnt lgkmcnt(3)
	v_mfma_f32_16x16x32_bf16 v[98:101], v[126:129], v[66:69], v[222:225]
	s_waitcnt lgkmcnt(1)
	v_mfma_f32_16x16x32_bf16 v[66:69], v[160:163], v[66:69], v[164:167]
	s_waitcnt lgkmcnt(0)
	v_mfma_f32_16x16x32_bf16 v[114:117], v[148:151], v[82:85], v[66:69]
	v_mfma_f32_16x16x32_bf16 v[66:69], v[126:129], v[188:191], v[86:89]
	v_mfma_f32_16x16x32_bf16 v[102:105], v[130:133], v[192:195], v[66:69]
	v_mfma_f32_16x16x32_bf16 v[66:69], v[160:163], v[188:191], v[70:73]
	v_mfma_f32_16x16x32_bf16 v[62:65], v[126:129], v[196:199], v[62:65]
	v_mfma_f32_16x16x32_bf16 v[58:61], v[160:163], v[196:199], v[58:61]
	v_mfma_f32_16x16x32_bf16 v[54:57], v[126:129], v[232:235], v[54:57]
	v_mfma_f32_16x16x32_bf16 v[50:53], v[160:163], v[232:235], v[50:53]
	v_mfma_f32_16x16x32_bf16 v[118:121], v[130:133], v[82:85], v[98:101]
	v_mfma_f32_16x16x32_bf16 v[98:101], v[148:151], v[192:195], v[66:69]
	v_mfma_f32_16x16x32_bf16 v[86:89], v[130:133], v[200:203], v[62:65]
	v_mfma_f32_16x16x32_bf16 v[82:85], v[148:151], v[200:203], v[58:61]
	v_mfma_f32_16x16x32_bf16 v[70:73], v[130:133], v[236:239], v[54:57]
	v_mfma_f32_16x16x32_bf16 v[66:69], v[148:151], v[236:239], v[50:53]
	s_setprio 0
	s_barrier
	s_nop 0
	ds_read_b128 v[50:53], v0 offset:49152
	ds_read_b128 v[164:167], v0 offset:50176
	ds_read_b128 v[188:191], v0 offset:51200
	ds_read_b128 v[192:195], v0 offset:52224
	ds_read_b128 v[196:199], v0 offset:53248
	ds_read_b128 v[200:203], v0 offset:54272
	ds_read_b128 v[222:225], v0 offset:55296
	ds_read_b128 v[232:235], v0 offset:56320
	s_barrier
	s_waitcnt lgkmcnt(0)
	s_setprio 1
	s_waitcnt lgkmcnt(7)
	v_mfma_f32_16x16x32_bf16 v[46:49], v[10:13], v[50:53], v[46:49]
	s_waitcnt lgkmcnt(5)
	v_mfma_f32_16x16x32_bf16 v[38:41], v[10:13], v[188:191], v[38:41]
	s_waitcnt lgkmcnt(3)
	v_mfma_f32_16x16x32_bf16 v[30:33], v[10:13], v[196:199], v[30:33]
	s_waitcnt lgkmcnt(1)
	v_mfma_f32_16x16x32_bf16 v[10:13], v[10:13], v[222:225], v[22:25]
	v_mfma_f32_16x16x32_bf16 v[62:65], v[14:17], v[164:167], v[46:49]
	v_mfma_f32_16x16x32_bf16 v[42:45], v[180:183], v[50:53], v[42:45]
	v_mfma_f32_16x16x32_bf16 v[46:49], v[14:17], v[192:195], v[38:41]
	v_mfma_f32_16x16x32_bf16 v[34:37], v[180:183], v[188:191], v[34:37]
	v_mfma_f32_16x16x32_bf16 v[30:33], v[14:17], v[200:203], v[30:33]
	v_mfma_f32_16x16x32_bf16 v[26:29], v[180:183], v[196:199], v[26:29]
	s_waitcnt lgkmcnt(0)
	v_mfma_f32_16x16x32_bf16 v[14:17], v[14:17], v[232:235], v[10:13]
	v_mfma_f32_16x16x32_bf16 v[10:13], v[180:183], v[222:225], v[18:21]
	v_mfma_f32_16x16x32_bf16 v[58:61], v[184:187], v[164:167], v[42:45]
	v_mfma_f32_16x16x32_bf16 v[42:45], v[184:187], v[192:195], v[34:37]
	v_mfma_f32_16x16x32_bf16 v[26:29], v[184:187], v[200:203], v[26:29]
	v_mfma_f32_16x16x32_bf16 v[10:13], v[184:187], v[232:235], v[10:13]
	s_setprio 0
	s_setprio 1
	v_mfma_f32_16x16x32_bf16 v[2:5], v[160:163], v[188:191], v[2:5]
	v_mfma_f32_16x16x32_bf16 v[18:21], v[126:129], v[50:53], v[134:137]
	v_mfma_f32_16x16x32_bf16 v[34:37], v[148:151], v[192:195], v[2:5]
	v_mfma_f32_16x16x32_bf16 v[2:5], v[126:129], v[196:199], v[156:159]
	v_mfma_f32_16x16x32_bf16 v[54:57], v[130:133], v[164:167], v[18:21]
	v_mfma_f32_16x16x32_bf16 v[18:21], v[160:163], v[50:53], v[152:155]
	v_mfma_f32_16x16x32_bf16 v[22:25], v[130:133], v[200:203], v[2:5]
	v_mfma_f32_16x16x32_bf16 v[2:5], v[160:163], v[196:199], v[168:171]
	v_mfma_f32_16x16x32_bf16 v[50:53], v[148:151], v[164:167], v[18:21]
	v_mfma_f32_16x16x32_bf16 v[6:9], v[126:129], v[188:191], v[6:9]
	v_mfma_f32_16x16x32_bf16 v[18:21], v[148:151], v[200:203], v[2:5]
	v_mfma_f32_16x16x32_bf16 v[2:5], v[126:129], v[222:225], v[172:175]
	v_mfma_f32_16x16x32_bf16 v[38:41], v[130:133], v[192:195], v[6:9]
	v_mfma_f32_16x16x32_bf16 v[6:9], v[130:133], v[232:235], v[2:5]
	v_mfma_f32_16x16x32_bf16 v[2:5], v[160:163], v[222:225], v[176:179]
	v_mfma_f32_16x16x32_bf16 v[2:5], v[148:151], v[232:235], v[2:5]
	s_setprio 0
	s_movk_i32 s0, 0x100
	v_cmp_gt_u32_e32 vcc, s0, v142
	s_barrier
	s_and_saveexec_b64 s[0:1], vcc
	s_cbranch_execz .LBB0_37
	s_barrier

.LBB0_85:
	ds_read_b128 v[164:167], v151
	ds_read_b128 v[168:171], v151 offset:1024
	ds_read_b128 v[172:175], v151 offset:2048
	ds_read_b128 v[176:179], v151 offset:3072
	v_add_u32_e32 v162, 0xc000, v147
	v_lshl_add_u64 v[204:205], v[138:139], 0, s[10:11]
	v_readfirstlane_b32 s1, v162
	v_lshl_add_u64 v[210:211], v[204:205], 0, s[60:61]
	s_mov_b32 m0, s1
	v_add_u32_e32 v163, 0xe000, v147
	ds_read_b128 v[180:183], v0
	ds_read_b128 v[184:187], v0 offset:1024
	ds_read_b128 v[188:191], v0 offset:2048
	ds_read_b128 v[192:195], v0 offset:3072
	ds_read_b128 v[196:199], v0 offset:4096
	ds_read_b128 v[200:203], v0 offset:5120
	ds_read_b128 v[222:225], v0 offset:6144
	ds_read_b128 v[232:235], v0 offset:7168
	global_load_lds_dwordx4 v[210:211], off
	v_lshl_add_u64 v[210:211], v[140:141], 0, s[10:11]
	v_readfirstlane_b32 s1, v163
	v_lshl_add_u64 v[216:217], v[210:211], 0, s[60:61]
	s_mov_b32 m0, s1
	s_nop 0
	global_load_lds_dwordx4 v[216:217], off
	s_waitcnt lgkmcnt(8)
	s_waitcnt vmcnt(10)
	s_barrier
	s_waitcnt lgkmcnt(0)
	s_setprio 1
	s_waitcnt lgkmcnt(0)
	v_mfma_f32_16x16x32_bf16 v[126:129], v[164:167], v[180:183], v[126:129]
	v_mfma_f32_16x16x32_bf16 v[122:125], v[172:175], v[180:183], v[122:125]
	v_mfma_f32_16x16x32_bf16 v[118:121], v[164:167], v[188:191], v[118:121]
	v_mfma_f32_16x16x32_bf16 v[114:117], v[172:175], v[188:191], v[114:117]
	v_mfma_f32_16x16x32_bf16 v[110:113], v[164:167], v[196:199], v[110:113]
	v_mfma_f32_16x16x32_bf16 v[106:109], v[172:175], v[196:199], v[106:109]
	v_mfma_f32_16x16x32_bf16 v[102:105], v[164:167], v[222:225], v[102:105]
	v_mfma_f32_16x16x32_bf16 v[98:101], v[172:175], v[222:225], v[98:101]
	v_mfma_f32_16x16x32_bf16 v[126:129], v[168:171], v[184:187], v[126:129]
	v_mfma_f32_16x16x32_bf16 v[122:125], v[176:179], v[184:187], v[122:125]
	v_mfma_f32_16x16x32_bf16 v[118:121], v[168:171], v[192:195], v[118:121]
	v_mfma_f32_16x16x32_bf16 v[114:117], v[176:179], v[192:195], v[114:117]
	v_mfma_f32_16x16x32_bf16 v[110:113], v[168:171], v[200:203], v[110:113]
	v_mfma_f32_16x16x32_bf16 v[106:109], v[176:179], v[200:203], v[106:109]
	v_mfma_f32_16x16x32_bf16 v[102:105], v[168:171], v[232:235], v[102:105]
	v_mfma_f32_16x16x32_bf16 v[98:101], v[176:179], v[232:235], v[98:101]
	s_setprio 0
	s_barrier
	v_lshl_add_u64 v[216:217], v[134:135], 0, s[10:11]
	v_readfirstlane_b32 s1, v149
	v_lshl_add_u64 v[218:219], v[216:217], 0, s[74:75]
	s_mov_b32 m0, s1
	ds_read_b128 v[236:239], v151 offset:16384
	ds_read_b128 v[240:243], v151 offset:17408
	ds_read_b128 v[244:247], v151 offset:18432
	ds_read_b128 v[248:251], v151 offset:19456
	global_load_lds_dwordx4 v[218:219], off
	v_lshl_add_u64 v[218:219], v[136:137], 0, s[10:11]
	v_readfirstlane_b32 s1, v150
	v_lshl_add_u64 v[228:229], v[218:219], 0, s[74:75]
	s_mov_b32 m0, s1
	s_nop 0
	global_load_lds_dwordx4 v[228:229], off
	s_waitcnt vmcnt(10)
	s_barrier
	s_waitcnt lgkmcnt(0)
	s_setprio 1
	s_waitcnt lgkmcnt(0)
	v_mfma_f32_16x16x32_bf16 v[94:97], v[236:239], v[180:183], v[94:97]
	v_mfma_f32_16x16x32_bf16 v[90:93], v[244:247], v[180:183], v[90:93]
	v_mfma_f32_16x16x32_bf16 v[86:89], v[236:239], v[188:191], v[86:89]
	v_mfma_f32_16x16x32_bf16 v[82:85], v[244:247], v[188:191], v[82:85]
	v_mfma_f32_16x16x32_bf16 v[78:81], v[236:239], v[196:199], v[78:81]
	v_mfma_f32_16x16x32_bf16 v[74:77], v[244:247], v[196:199], v[74:77]
	v_mfma_f32_16x16x32_bf16 v[70:73], v[236:239], v[222:225], v[70:73]
	v_mfma_f32_16x16x32_bf16 v[66:69], v[244:247], v[222:225], v[66:69]
	v_mfma_f32_16x16x32_bf16 v[94:97], v[240:243], v[184:187], v[94:97]
	v_mfma_f32_16x16x32_bf16 v[90:93], v[248:251], v[184:187], v[90:93]
	v_mfma_f32_16x16x32_bf16 v[86:89], v[240:243], v[192:195], v[86:89]
	v_mfma_f32_16x16x32_bf16 v[82:85], v[248:251], v[192:195], v[82:85]
	v_mfma_f32_16x16x32_bf16 v[78:81], v[240:243], v[200:203], v[78:81]
	v_mfma_f32_16x16x32_bf16 v[74:77], v[248:251], v[200:203], v[74:77]
	v_mfma_f32_16x16x32_bf16 v[70:73], v[240:243], v[232:235], v[70:73]
	v_mfma_f32_16x16x32_bf16 v[66:69], v[248:251], v[232:235], v[66:69]
	s_setprio 0
	v_readfirstlane_b32 s1, v147
	v_lshl_add_u64 v[228:229], v[204:205], 0, s[74:75]
	s_mov_b32 m0, s1
	v_readfirstlane_b32 s1, v148
	s_barrier
	ds_read_b128 v[180:183], v0 offset:16384
	ds_read_b128 v[184:187], v0 offset:17408
	ds_read_b128 v[188:191], v0 offset:18432
	ds_read_b128 v[192:195], v0 offset:19456
	ds_read_b128 v[196:199], v0 offset:20480
	ds_read_b128 v[200:203], v0 offset:21504
	ds_read_b128 v[222:225], v0 offset:22528
	ds_read_b128 v[232:235], v0 offset:23552
	global_load_lds_dwordx4 v[228:229], off
	v_lshl_add_u64 v[228:229], v[210:211], 0, s[74:75]
	s_mov_b32 m0, s1
	s_nop 0
	global_load_lds_dwordx4 v[228:229], off
	s_barrier
	s_waitcnt lgkmcnt(0)
	s_setprio 1
	s_waitcnt lgkmcnt(0)
	v_mfma_f32_16x16x32_bf16 v[62:65], v[164:167], v[180:183], v[62:65]
	v_mfma_f32_16x16x32_bf16 v[58:61], v[172:175], v[180:183], v[58:61]
	v_mfma_f32_16x16x32_bf16 v[54:57], v[164:167], v[188:191], v[54:57]
	v_mfma_f32_16x16x32_bf16 v[50:53], v[172:175], v[188:191], v[50:53]
	v_mfma_f32_16x16x32_bf16 v[46:49], v[164:167], v[196:199], v[46:49]
	v_mfma_f32_16x16x32_bf16 v[42:45], v[172:175], v[196:199], v[42:45]
	v_mfma_f32_16x16x32_bf16 v[38:41], v[164:167], v[222:225], v[38:41]
	v_mfma_f32_16x16x32_bf16 v[34:37], v[172:175], v[222:225], v[34:37]
	v_mfma_f32_16x16x32_bf16 v[62:65], v[168:171], v[184:187], v[62:65]
	v_mfma_f32_16x16x32_bf16 v[58:61], v[176:179], v[184:187], v[58:61]
	v_mfma_f32_16x16x32_bf16 v[54:57], v[168:171], v[192:195], v[54:57]
	v_mfma_f32_16x16x32_bf16 v[50:53], v[176:179], v[192:195], v[50:53]
	v_mfma_f32_16x16x32_bf16 v[46:49], v[168:171], v[200:203], v[46:49]
	v_mfma_f32_16x16x32_bf16 v[42:45], v[176:179], v[200:203], v[42:45]
	v_mfma_f32_16x16x32_bf16 v[38:41], v[168:171], v[232:235], v[38:41]
	v_mfma_f32_16x16x32_bf16 v[34:37], v[176:179], v[232:235], v[34:37]
	s_setprio 0
	s_barrier
	v_readfirstlane_b32 s1, v152
	v_lshl_add_u64 v[164:165], v[216:217], 0, s[18:19]
	s_mov_b32 m0, s1
	v_readfirstlane_b32 s1, v153
	global_load_lds_dwordx4 v[164:165], off
	v_lshl_add_u64 v[164:165], v[218:219], 0, s[18:19]
	s_mov_b32 m0, s1
	s_nop 0
	global_load_lds_dwordx4 v[164:165], off
	s_waitcnt vmcnt(10)
	s_barrier
	s_setprio 1
	v_mfma_f32_16x16x32_bf16 v[30:33], v[236:239], v[180:183], v[30:33]
	v_mfma_f32_16x16x32_bf16 v[26:29], v[244:247], v[180:183], v[26:29]
	v_mfma_f32_16x16x32_bf16 v[22:25], v[236:239], v[188:191], v[22:25]
	v_mfma_f32_16x16x32_bf16 v[18:21], v[244:247], v[188:191], v[18:21]
	v_mfma_f32_16x16x32_bf16 v[14:17], v[236:239], v[196:199], v[14:17]
	v_mfma_f32_16x16x32_bf16 v[10:13], v[244:247], v[196:199], v[10:13]
	v_mfma_f32_16x16x32_bf16 v[6:9], v[236:239], v[222:225], v[6:9]
	v_mfma_f32_16x16x32_bf16 v[2:5], v[244:247], v[222:225], v[2:5]
	v_mfma_f32_16x16x32_bf16 v[30:33], v[240:243], v[184:187], v[30:33]
	v_mfma_f32_16x16x32_bf16 v[26:29], v[248:251], v[184:187], v[26:29]
	v_mfma_f32_16x16x32_bf16 v[22:25], v[240:243], v[192:195], v[22:25]
	v_mfma_f32_16x16x32_bf16 v[18:21], v[248:251], v[192:195], v[18:21]
	v_mfma_f32_16x16x32_bf16 v[14:17], v[240:243], v[200:203], v[14:17]
	v_mfma_f32_16x16x32_bf16 v[10:13], v[248:251], v[200:203], v[10:13]
	v_mfma_f32_16x16x32_bf16 v[6:9], v[240:243], v[232:235], v[6:9]
	v_mfma_f32_16x16x32_bf16 v[2:5], v[248:251], v[232:235], v[2:5]
	s_setprio 0
	s_barrier
	ds_read_b128 v[164:167], v151 offset:32768
	ds_read_b128 v[168:171], v151 offset:33792
	ds_read_b128 v[172:175], v151 offset:34816
	ds_read_b128 v[176:179], v151 offset:35840
	v_readfirstlane_b32 s1, v154
	v_lshl_add_u64 v[228:229], v[204:205], 0, s[18:19]
	s_mov_b32 m0, s1
	v_readfirstlane_b32 s1, v155
	ds_read_b128 v[180:183], v0 offset:32768
	ds_read_b128 v[184:187], v0 offset:33792
	ds_read_b128 v[188:191], v0 offset:34816
	ds_read_b128 v[192:195], v0 offset:35840
	ds_read_b128 v[196:199], v0 offset:36864
	ds_read_b128 v[200:203], v0 offset:37888
	ds_read_b128 v[222:225], v0 offset:38912
	ds_read_b128 v[232:235], v0 offset:39936
	global_load_lds_dwordx4 v[228:229], off
	v_lshl_add_u64 v[228:229], v[210:211], 0, s[18:19]
	s_mov_b32 m0, s1
	s_nop 0
	global_load_lds_dwordx4 v[228:229], off
	s_waitcnt lgkmcnt(8)
	s_waitcnt vmcnt(10)
	s_barrier
	s_waitcnt lgkmcnt(0)
	s_setprio 1
	s_waitcnt lgkmcnt(0)
	v_mfma_f32_16x16x32_bf16 v[126:129], v[164:167], v[180:183], v[126:129]
	v_mfma_f32_16x16x32_bf16 v[122:125], v[172:175], v[180:183], v[122:125]
	v_mfma_f32_16x16x32_bf16 v[118:121], v[164:167], v[188:191], v[118:121]
	v_mfma_f32_16x16x32_bf16 v[114:117], v[172:175], v[188:191], v[114:117]
	v_mfma_f32_16x16x32_bf16 v[110:113], v[164:167], v[196:199], v[110:113]
	v_mfma_f32_16x16x32_bf16 v[106:109], v[172:175], v[196:199], v[106:109]
	v_mfma_f32_16x16x32_bf16 v[102:105], v[164:167], v[222:225], v[102:105]
	v_mfma_f32_16x16x32_bf16 v[98:101], v[172:175], v[222:225], v[98:101]
	v_mfma_f32_16x16x32_bf16 v[126:129], v[168:171], v[184:187], v[126:129]
	v_mfma_f32_16x16x32_bf16 v[122:125], v[176:179], v[184:187], v[122:125]
	v_mfma_f32_16x16x32_bf16 v[118:121], v[168:171], v[192:195], v[118:121]
	v_mfma_f32_16x16x32_bf16 v[114:117], v[176:179], v[192:195], v[114:117]
	v_mfma_f32_16x16x32_bf16 v[110:113], v[168:171], v[200:203], v[110:113]
	v_mfma_f32_16x16x32_bf16 v[106:109], v[176:179], v[200:203], v[106:109]
	v_mfma_f32_16x16x32_bf16 v[102:105], v[168:171], v[232:235], v[102:105]
	v_mfma_f32_16x16x32_bf16 v[98:101], v[176:179], v[232:235], v[98:101]
	s_setprio 0
	s_barrier
	v_readfirstlane_b32 s1, v156
	v_lshl_add_u64 v[228:229], v[216:217], 0, s[28:29]
	s_mov_b32 m0, s1
	v_readfirstlane_b32 s1, v157
	ds_read_b128 v[236:239], v151 offset:49152
	ds_read_b128 v[240:243], v151 offset:50176
	ds_read_b128 v[244:247], v151 offset:51200
	ds_read_b128 v[248:251], v151 offset:52224
	global_load_lds_dwordx4 v[228:229], off
	v_lshl_add_u64 v[228:229], v[218:219], 0, s[28:29]
	s_mov_b32 m0, s1
	s_nop 0
	global_load_lds_dwordx4 v[228:229], off
	s_waitcnt vmcnt(10)
	s_barrier
	s_waitcnt lgkmcnt(0)
	s_setprio 1
	s_waitcnt lgkmcnt(0)
	v_mfma_f32_16x16x32_bf16 v[94:97], v[236:239], v[180:183], v[94:97]
	v_mfma_f32_16x16x32_bf16 v[90:93], v[244:247], v[180:183], v[90:93]
	v_mfma_f32_16x16x32_bf16 v[86:89], v[236:239], v[188:191], v[86:89]
	v_mfma_f32_16x16x32_bf16 v[82:85], v[244:247], v[188:191], v[82:85]
	v_mfma_f32_16x16x32_bf16 v[78:81], v[236:239], v[196:199], v[78:81]
	v_mfma_f32_16x16x32_bf16 v[74:77], v[244:247], v[196:199], v[74:77]
	v_mfma_f32_16x16x32_bf16 v[70:73], v[236:239], v[222:225], v[70:73]
	v_mfma_f32_16x16x32_bf16 v[66:69], v[244:247], v[222:225], v[66:69]
	v_mfma_f32_16x16x32_bf16 v[94:97], v[240:243], v[184:187], v[94:97]
	v_mfma_f32_16x16x32_bf16 v[90:93], v[248:251], v[184:187], v[90:93]
	v_mfma_f32_16x16x32_bf16 v[86:89], v[240:243], v[192:195], v[86:89]
	v_mfma_f32_16x16x32_bf16 v[82:85], v[248:251], v[192:195], v[82:85]
	v_mfma_f32_16x16x32_bf16 v[78:81], v[240:243], v[200:203], v[78:81]
	v_mfma_f32_16x16x32_bf16 v[74:77], v[248:251], v[200:203], v[74:77]
	v_mfma_f32_16x16x32_bf16 v[70:73], v[240:243], v[232:235], v[70:73]
	v_mfma_f32_16x16x32_bf16 v[66:69], v[248:251], v[232:235], v[66:69]
	s_setprio 0
	v_readfirstlane_b32 s1, v158
	v_lshl_add_u64 v[204:205], v[204:205], 0, s[28:29]
	s_mov_b32 m0, s1
	v_readfirstlane_b32 s1, v159
	s_barrier
	ds_read_b128 v[180:183], v0 offset:49152
	ds_read_b128 v[184:187], v0 offset:50176
	ds_read_b128 v[188:191], v0 offset:51200
	ds_read_b128 v[192:195], v0 offset:52224
	ds_read_b128 v[196:199], v0 offset:53248
	ds_read_b128 v[200:203], v0 offset:54272
	ds_read_b128 v[222:225], v0 offset:55296
	ds_read_b128 v[232:235], v0 offset:56320
	global_load_lds_dwordx4 v[204:205], off
	v_lshl_add_u64 v[204:205], v[210:211], 0, s[28:29]
	s_mov_b32 m0, s1
	s_nop 0
	global_load_lds_dwordx4 v[204:205], off
	s_barrier
	s_waitcnt lgkmcnt(0)
	s_setprio 1
	s_waitcnt lgkmcnt(0)
	v_mfma_f32_16x16x32_bf16 v[62:65], v[164:167], v[180:183], v[62:65]
	v_mfma_f32_16x16x32_bf16 v[58:61], v[172:175], v[180:183], v[58:61]
	v_mfma_f32_16x16x32_bf16 v[54:57], v[164:167], v[188:191], v[54:57]
	v_mfma_f32_16x16x32_bf16 v[50:53], v[172:175], v[188:191], v[50:53]
	v_mfma_f32_16x16x32_bf16 v[46:49], v[164:167], v[196:199], v[46:49]
	v_mfma_f32_16x16x32_bf16 v[42:45], v[172:175], v[196:199], v[42:45]
	v_mfma_f32_16x16x32_bf16 v[38:41], v[164:167], v[222:225], v[38:41]
	v_mfma_f32_16x16x32_bf16 v[34:37], v[172:175], v[222:225], v[34:37]
	v_mfma_f32_16x16x32_bf16 v[62:65], v[168:171], v[184:187], v[62:65]
	v_mfma_f32_16x16x32_bf16 v[58:61], v[176:179], v[184:187], v[58:61]
	v_mfma_f32_16x16x32_bf16 v[54:57], v[168:171], v[192:195], v[54:57]
	v_mfma_f32_16x16x32_bf16 v[50:53], v[176:179], v[192:195], v[50:53]
	v_mfma_f32_16x16x32_bf16 v[46:49], v[168:171], v[200:203], v[46:49]
	v_mfma_f32_16x16x32_bf16 v[42:45], v[176:179], v[200:203], v[42:45]
	v_mfma_f32_16x16x32_bf16 v[38:41], v[168:171], v[232:235], v[38:41]
	v_mfma_f32_16x16x32_bf16 v[34:37], v[176:179], v[232:235], v[34:37]
	s_setprio 0
	s_barrier
	v_readfirstlane_b32 s1, v160
	v_lshl_add_u64 v[164:165], v[216:217], 0, s[30:31]
	s_mov_b32 m0, s1
	v_readfirstlane_b32 s1, v161
	global_load_lds_dwordx4 v[164:165], off
	v_lshl_add_u64 v[164:165], v[218:219], 0, s[30:31]
	s_mov_b32 m0, s1
	s_nop 0
	global_load_lds_dwordx4 v[164:165], off
	s_waitcnt vmcnt(10)
	s_barrier
	s_setprio 1
	v_mfma_f32_16x16x32_bf16 v[30:33], v[236:239], v[180:183], v[30:33]
	v_mfma_f32_16x16x32_bf16 v[26:29], v[244:247], v[180:183], v[26:29]
	v_mfma_f32_16x16x32_bf16 v[22:25], v[236:239], v[188:191], v[22:25]
	v_mfma_f32_16x16x32_bf16 v[18:21], v[244:247], v[188:191], v[18:21]
	v_mfma_f32_16x16x32_bf16 v[14:17], v[236:239], v[196:199], v[14:17]
	v_mfma_f32_16x16x32_bf16 v[10:13], v[244:247], v[196:199], v[10:13]
	v_mfma_f32_16x16x32_bf16 v[6:9], v[236:239], v[222:225], v[6:9]
	v_mfma_f32_16x16x32_bf16 v[2:5], v[244:247], v[222:225], v[2:5]
	v_mfma_f32_16x16x32_bf16 v[30:33], v[240:243], v[184:187], v[30:33]
	v_mfma_f32_16x16x32_bf16 v[26:29], v[248:251], v[184:187], v[26:29]
	v_mfma_f32_16x16x32_bf16 v[22:25], v[240:243], v[192:195], v[22:25]
	v_mfma_f32_16x16x32_bf16 v[18:21], v[248:251], v[192:195], v[18:21]
	v_mfma_f32_16x16x32_bf16 v[14:17], v[240:243], v[200:203], v[14:17]
	v_mfma_f32_16x16x32_bf16 v[10:13], v[248:251], v[200:203], v[10:13]
	v_mfma_f32_16x16x32_bf16 v[6:9], v[240:243], v[232:235], v[6:9]
	v_mfma_f32_16x16x32_bf16 v[2:5], v[248:251], v[232:235], v[2:5]
	s_setprio 0
	s_add_i32 s0, s0, 2
	s_add_u32 s10, s10, 0x100
	s_addc_u32 s11, s11, 0
	s_cmp_lt_u32 s0, 28
	s_barrier
	s_cbranch_scc1 .LBB0_85
	s_mov_b64 s[10:11], 0xf80
	v_readfirstlane_b32 s0, v162
	v_lshl_add_u64 v[132:133], v[132:133], 0, s[10:11]
	s_mov_b32 m0, s0
	v_readfirstlane_b32 s0, v163
	ds_read_b128 v[134:137], v151
	ds_read_b128 v[138:141], v151 offset:1024
	ds_read_b128 v[152:155], v151 offset:2048
	ds_read_b128 v[156:159], v151 offset:3072
	ds_read_b128 v[164:167], v0
	ds_read_b128 v[168:171], v0 offset:1024
	ds_read_b128 v[172:175], v0 offset:2048
	ds_read_b128 v[176:179], v0 offset:3072
	ds_read_b128 v[180:183], v0 offset:4096
	ds_read_b128 v[184:187], v0 offset:5120
	ds_read_b128 v[188:191], v0 offset:6144
	ds_read_b128 v[192:195], v0 offset:7168
	global_load_lds_dwordx4 v[132:133], off
	v_lshl_add_u64 v[130:131], v[130:131], 0, s[10:11]
	s_mov_b32 m0, s0
	s_nop 0
	global_load_lds_dwordx4 v[130:131], off
	s_barrier
	s_waitcnt lgkmcnt(0)
	s_setprio 1
	s_waitcnt lgkmcnt(0)
	v_mfma_f32_16x16x32_bf16 v[126:129], v[134:137], v[164:167], v[126:129]
	v_mfma_f32_16x16x32_bf16 v[122:125], v[152:155], v[164:167], v[122:125]
	v_mfma_f32_16x16x32_bf16 v[114:117], v[152:155], v[172:175], v[114:117]
	v_mfma_f32_16x16x32_bf16 v[106:109], v[152:155], v[180:183], v[106:109]
	v_mfma_f32_16x16x32_bf16 v[98:101], v[152:155], v[188:191], v[98:101]
	v_mfma_f32_16x16x32_bf16 v[126:129], v[138:141], v[168:171], v[126:129]
	v_mfma_f32_16x16x32_bf16 v[122:125], v[156:159], v[168:171], v[122:125]
	v_mfma_f32_16x16x32_bf16 v[118:121], v[134:137], v[172:175], v[118:121]
	v_mfma_f32_16x16x32_bf16 v[114:117], v[156:159], v[176:179], v[114:117]
	v_mfma_f32_16x16x32_bf16 v[110:113], v[134:137], v[180:183], v[110:113]
	v_mfma_f32_16x16x32_bf16 v[106:109], v[156:159], v[184:187], v[106:109]
	v_mfma_f32_16x16x32_bf16 v[102:105], v[134:137], v[188:191], v[102:105]
	v_mfma_f32_16x16x32_bf16 v[98:101], v[156:159], v[192:195], v[98:101]
	v_mfma_f32_16x16x32_bf16 v[130:133], v[138:141], v[176:179], v[118:121]
	v_mfma_f32_16x16x32_bf16 v[160:163], v[138:141], v[184:187], v[110:113]
	v_mfma_f32_16x16x32_bf16 v[196:199], v[138:141], v[192:195], v[102:105]
	s_setprio 0
	s_barrier
	s_nop 0
	ds_read_b128 v[102:105], v151 offset:16384
	ds_read_b128 v[110:113], v151 offset:17408
	ds_read_b128 v[118:121], v151 offset:18432
	ds_read_b128 v[200:203], v151 offset:19456
	s_barrier
	s_waitcnt lgkmcnt(0)
	s_setprio 1
	s_waitcnt lgkmcnt(1)
	v_mfma_f32_16x16x32_bf16 v[90:93], v[118:121], v[164:167], v[90:93]
	v_mfma_f32_16x16x32_bf16 v[86:89], v[102:105], v[172:175], v[86:89]
	v_mfma_f32_16x16x32_bf16 v[82:85], v[118:121], v[172:175], v[82:85]
	v_mfma_f32_16x16x32_bf16 v[78:81], v[102:105], v[180:183], v[78:81]
	v_mfma_f32_16x16x32_bf16 v[70:73], v[102:105], v[188:191], v[70:73]
	v_mfma_f32_16x16x32_bf16 v[94:97], v[102:105], v[164:167], v[94:97]
	s_waitcnt lgkmcnt(0)
	v_mfma_f32_16x16x32_bf16 v[90:93], v[200:203], v[168:171], v[90:93]
	v_mfma_f32_16x16x32_bf16 v[86:89], v[110:113], v[176:179], v[86:89]
	v_mfma_f32_16x16x32_bf16 v[82:85], v[200:203], v[176:179], v[82:85]
	v_mfma_f32_16x16x32_bf16 v[78:81], v[110:113], v[184:187], v[78:81]
	v_mfma_f32_16x16x32_bf16 v[74:77], v[118:121], v[180:183], v[74:77]
	v_mfma_f32_16x16x32_bf16 v[70:73], v[110:113], v[192:195], v[70:73]
	v_mfma_f32_16x16x32_bf16 v[66:69], v[118:121], v[188:191], v[66:69]
	v_mfma_f32_16x16x32_bf16 v[222:225], v[110:113], v[168:171], v[94:97]
	v_mfma_f32_16x16x32_bf16 v[164:167], v[200:203], v[184:187], v[74:77]
	v_mfma_f32_16x16x32_bf16 v[168:171], v[200:203], v[192:195], v[66:69]
	s_setprio 0
	s_barrier
	s_nop 2
	ds_read_b128 v[66:69], v0 offset:16384
	ds_read_b128 v[74:77], v0 offset:17408
	ds_read_b128 v[94:97], v0 offset:18432
	ds_read_b128 v[172:175], v0 offset:19456
	ds_read_b128 v[176:179], v0 offset:20480
	ds_read_b128 v[180:183], v0 offset:21504
	ds_read_b128 v[184:187], v0 offset:22528
	ds_read_b128 v[188:191], v0 offset:23552
	s_waitcnt vmcnt(4)
	s_barrier
	s_waitcnt lgkmcnt(0)
	s_setprio 1
	s_waitcnt lgkmcnt(5)
	v_mfma_f32_16x16x32_bf16 v[54:57], v[134:137], v[94:97], v[54:57]
	v_mfma_f32_16x16x32_bf16 v[50:53], v[152:155], v[94:97], v[50:53]
	v_mfma_f32_16x16x32_bf16 v[62:65], v[134:137], v[66:69], v[62:65]
	v_mfma_f32_16x16x32_bf16 v[58:61], v[152:155], v[66:69], v[58:61]
	s_waitcnt lgkmcnt(4)
	v_mfma_f32_16x16x32_bf16 v[54:57], v[138:141], v[172:175], v[54:57]
	v_mfma_f32_16x16x32_bf16 v[50:53], v[156:159], v[172:175], v[50:53]
	s_waitcnt lgkmcnt(3)
	v_mfma_f32_16x16x32_bf16 v[46:49], v[134:137], v[176:179], v[46:49]
	v_mfma_f32_16x16x32_bf16 v[42:45], v[152:155], v[176:179], v[42:45]
	s_waitcnt lgkmcnt(1)
	v_mfma_f32_16x16x32_bf16 v[38:41], v[134:137], v[184:187], v[38:41]
	v_mfma_f32_16x16x32_bf16 v[34:37], v[152:155], v[184:187], v[34:37]
	v_mfma_f32_16x16x32_bf16 v[192:195], v[138:141], v[74:77], v[62:65]
	v_mfma_f32_16x16x32_bf16 v[232:235], v[156:159], v[74:77], v[58:61]
	v_mfma_f32_16x16x32_bf16 v[236:239], v[138:141], v[180:183], v[46:49]
	v_mfma_f32_16x16x32_bf16 v[240:243], v[156:159], v[180:183], v[42:45]
	s_waitcnt lgkmcnt(0)
	v_mfma_f32_16x16x32_bf16 v[134:137], v[138:141], v[188:191], v[38:41]
	v_mfma_f32_16x16x32_bf16 v[138:141], v[156:159], v[188:191], v[34:37]
	s_setprio 0
	s_setprio 1
	v_mfma_f32_16x16x32_bf16 v[30:33], v[102:105], v[66:69], v[30:33]
	v_mfma_f32_16x16x32_bf16 v[26:29], v[118:121], v[66:69], v[26:29]
	v_mfma_f32_16x16x32_bf16 v[14:17], v[102:105], v[176:179], v[14:17]
	v_mfma_f32_16x16x32_bf16 v[10:13], v[118:121], v[176:179], v[10:13]
	v_mfma_f32_16x16x32_bf16 v[30:33], v[110:113], v[74:77], v[30:33]
	v_mfma_f32_16x16x32_bf16 v[26:29], v[200:203], v[74:77], v[26:29]
	v_mfma_f32_16x16x32_bf16 v[22:25], v[102:105], v[94:97], v[22:25]
	v_mfma_f32_16x16x32_bf16 v[18:21], v[118:121], v[94:97], v[18:21]
	v_mfma_f32_16x16x32_bf16 v[14:17], v[110:113], v[180:183], v[14:17]
	v_mfma_f32_16x16x32_bf16 v[10:13], v[200:203], v[180:183], v[10:13]
	v_mfma_f32_16x16x32_bf16 v[6:9], v[102:105], v[184:187], v[6:9]
	v_mfma_f32_16x16x32_bf16 v[2:5], v[118:121], v[184:187], v[2:5]
	v_mfma_f32_16x16x32_bf16 v[152:155], v[110:113], v[172:175], v[22:25]
	v_mfma_f32_16x16x32_bf16 v[156:159], v[200:203], v[172:175], v[18:21]
	v_mfma_f32_16x16x32_bf16 v[172:175], v[110:113], v[188:191], v[6:9]
	v_mfma_f32_16x16x32_bf16 v[176:179], v[200:203], v[188:191], v[2:5]
	s_setprio 0
	s_barrier
	s_nop 1
	ds_read_b128 v[2:5], v151 offset:32768
	ds_read_b128 v[6:9], v151 offset:33792
	ds_read_b128 v[180:183], v151 offset:34816
	ds_read_b128 v[184:187], v151 offset:35840
	ds_read_b128 v[18:21], v0 offset:32768
	ds_read_b128 v[22:25], v0 offset:33792
	ds_read_b128 v[38:41], v0 offset:34816
	ds_read_b128 v[46:49], v0 offset:35840
	ds_read_b128 v[58:61], v0 offset:36864
	ds_read_b128 v[66:69], v0 offset:37888
	ds_read_b128 v[188:191], v0 offset:38912
	ds_read_b128 v[200:203], v0 offset:39936
	s_waitcnt vmcnt(2)
	s_barrier
	s_waitcnt lgkmcnt(0)
	s_setprio 1
	s_waitcnt lgkmcnt(7)
	v_mfma_f32_16x16x32_bf16 v[34:37], v[2:5], v[18:21], v[126:129]
	s_waitcnt lgkmcnt(6)
	v_mfma_f32_16x16x32_bf16 v[118:121], v[6:9], v[22:25], v[34:37]
	v_mfma_f32_16x16x32_bf16 v[34:37], v[180:183], v[18:21], v[122:125]
	v_mfma_f32_16x16x32_bf16 v[110:113], v[184:187], v[22:25], v[34:37]
	s_waitcnt lgkmcnt(5)
	v_mfma_f32_16x16x32_bf16 v[34:37], v[2:5], v[38:41], v[130:133]
	s_waitcnt lgkmcnt(4)
	v_mfma_f32_16x16x32_bf16 v[102:105], v[6:9], v[46:49], v[34:37]
	v_mfma_f32_16x16x32_bf16 v[34:37], v[180:183], v[38:41], v[114:117]
	v_mfma_f32_16x16x32_bf16 v[94:97], v[184:187], v[46:49], v[34:37]
	s_waitcnt lgkmcnt(3)
	v_mfma_f32_16x16x32_bf16 v[34:37], v[2:5], v[58:61], v[160:163]
	s_waitcnt lgkmcnt(2)
	v_mfma_f32_16x16x32_bf16 v[74:77], v[6:9], v[66:69], v[34:37]
	v_mfma_f32_16x16x32_bf16 v[34:37], v[180:183], v[58:61], v[106:109]
	v_mfma_f32_16x16x32_bf16 v[62:65], v[184:187], v[66:69], v[34:37]
	s_waitcnt lgkmcnt(1)
	v_mfma_f32_16x16x32_bf16 v[34:37], v[2:5], v[188:191], v[196:199]
	s_waitcnt lgkmcnt(0)
	v_mfma_f32_16x16x32_bf16 v[42:45], v[6:9], v[200:203], v[34:37]
	v_mfma_f32_16x16x32_bf16 v[34:37], v[180:183], v[188:191], v[98:101]
	v_mfma_f32_16x16x32_bf16 v[34:37], v[184:187], v[200:203], v[34:37]
	s_setprio 0
	s_barrier
	ds_read_b128 v[130:133], v151 offset:49152
	ds_read_b128 v[160:163], v151 offset:50176
	ds_read_b128 v[196:199], v151 offset:51200
	ds_read_b128 v[148:151], v151 offset:52224
	s_waitcnt vmcnt(0)
	s_barrier
	s_waitcnt lgkmcnt(0)
	s_setprio 1
	s_waitcnt lgkmcnt(3)
	v_mfma_f32_16x16x32_bf16 v[98:101], v[130:133], v[18:21], v[222:225]
	s_waitcnt lgkmcnt(1)
	v_mfma_f32_16x16x32_bf16 v[18:21], v[196:199], v[18:21], v[90:93]
	s_waitcnt lgkmcnt(0)
	v_mfma_f32_16x16x32_bf16 v[122:125], v[148:151], v[22:25], v[18:21]
	v_mfma_f32_16x16x32_bf16 v[18:21], v[130:133], v[38:41], v[86:89]
	v_mfma_f32_16x16x32_bf16 v[114:117], v[160:163], v[46:49], v[18:21]
	v_mfma_f32_16x16x32_bf16 v[18:21], v[196:199], v[38:41], v[82:85]
	v_mfma_f32_16x16x32_bf16 v[106:109], v[148:151], v[46:49], v[18:21]
	v_mfma_f32_16x16x32_bf16 v[18:21], v[130:133], v[58:61], v[78:81]
	v_mfma_f32_16x16x32_bf16 v[126:129], v[160:163], v[22:25], v[98:101]
	v_mfma_f32_16x16x32_bf16 v[98:101], v[160:163], v[66:69], v[18:21]
	v_mfma_f32_16x16x32_bf16 v[18:21], v[196:199], v[58:61], v[164:167]
	v_mfma_f32_16x16x32_bf16 v[90:93], v[148:151], v[66:69], v[18:21]
	v_mfma_f32_16x16x32_bf16 v[18:21], v[130:133], v[188:191], v[70:73]
	v_mfma_f32_16x16x32_bf16 v[66:69], v[160:163], v[200:203], v[18:21]
	v_mfma_f32_16x16x32_bf16 v[18:21], v[196:199], v[188:191], v[168:171]
	v_mfma_f32_16x16x32_bf16 v[58:61], v[148:151], v[200:203], v[18:21]
	s_setprio 0
	s_barrier
	ds_read_b128 v[82:85], v0 offset:49152
	ds_read_b128 v[164:167], v0 offset:50176
	ds_read_b128 v[168:171], v0 offset:51200
	ds_read_b128 v[188:191], v0 offset:52224
	ds_read_b128 v[200:203], v0 offset:53248
	ds_read_b128 v[222:225], v0 offset:54272
	ds_read_b128 v[244:247], v0 offset:55296
	ds_read_b128 v[248:251], v0 offset:56320
	s_barrier
	s_waitcnt lgkmcnt(0)
	s_setprio 1
	s_waitcnt lgkmcnt(7)
	v_mfma_f32_16x16x32_bf16 v[18:21], v[2:5], v[82:85], v[192:195]
	s_waitcnt lgkmcnt(6)
	v_mfma_f32_16x16x32_bf16 v[78:81], v[6:9], v[164:167], v[18:21]
	v_mfma_f32_16x16x32_bf16 v[18:21], v[180:183], v[82:85], v[232:235]
	v_mfma_f32_16x16x32_bf16 v[70:73], v[184:187], v[164:167], v[18:21]
	s_waitcnt lgkmcnt(5)
	v_mfma_f32_16x16x32_bf16 v[18:21], v[2:5], v[168:171], v[54:57]
	s_waitcnt lgkmcnt(4)
	v_mfma_f32_16x16x32_bf16 v[46:49], v[6:9], v[188:191], v[18:21]
	v_mfma_f32_16x16x32_bf16 v[18:21], v[180:183], v[168:171], v[50:53]
	v_mfma_f32_16x16x32_bf16 v[38:41], v[184:187], v[188:191], v[18:21]
	s_waitcnt lgkmcnt(3)
	v_mfma_f32_16x16x32_bf16 v[18:21], v[2:5], v[200:203], v[236:239]
	s_waitcnt lgkmcnt(1)
	v_mfma_f32_16x16x32_bf16 v[2:5], v[2:5], v[244:247], v[134:137]
	v_mfma_f32_16x16x32_bf16 v[22:25], v[6:9], v[222:225], v[18:21]
	v_mfma_f32_16x16x32_bf16 v[18:21], v[180:183], v[200:203], v[240:243]
	s_waitcnt lgkmcnt(0)
	v_mfma_f32_16x16x32_bf16 v[6:9], v[6:9], v[248:251], v[2:5]
	v_mfma_f32_16x16x32_bf16 v[2:5], v[180:183], v[244:247], v[138:141]
	v_mfma_f32_16x16x32_bf16 v[18:21], v[184:187], v[222:225], v[18:21]
	v_mfma_f32_16x16x32_bf16 v[2:5], v[184:187], v[248:251], v[2:5]
	s_setprio 0
	s_setprio 1
	v_mfma_f32_16x16x32_bf16 v[26:29], v[196:199], v[82:85], v[26:29]
	v_mfma_f32_16x16x32_bf16 v[30:33], v[130:133], v[82:85], v[30:33]
	v_mfma_f32_16x16x32_bf16 v[82:85], v[148:151], v[164:167], v[26:29]
	v_mfma_f32_16x16x32_bf16 v[26:29], v[130:133], v[168:171], v[152:155]
	v_mfma_f32_16x16x32_bf16 v[54:57], v[160:163], v[188:191], v[26:29]
	v_mfma_f32_16x16x32_bf16 v[26:29], v[196:199], v[168:171], v[156:159]
	v_mfma_f32_16x16x32_bf16 v[10:13], v[196:199], v[200:203], v[10:13]
	v_mfma_f32_16x16x32_bf16 v[50:53], v[148:151], v[188:191], v[26:29]
	v_mfma_f32_16x16x32_bf16 v[14:17], v[130:133], v[200:203], v[14:17]
	v_mfma_f32_16x16x32_bf16 v[26:29], v[148:151], v[222:225], v[10:13]
	v_mfma_f32_16x16x32_bf16 v[10:13], v[130:133], v[244:247], v[172:175]
	v_mfma_f32_16x16x32_bf16 v[86:89], v[160:163], v[164:167], v[30:33]
	v_mfma_f32_16x16x32_bf16 v[30:33], v[160:163], v[222:225], v[14:17]
	v_mfma_f32_16x16x32_bf16 v[14:17], v[160:163], v[248:251], v[10:13]
	v_mfma_f32_16x16x32_bf16 v[10:13], v[196:199], v[244:247], v[176:179]
	v_mfma_f32_16x16x32_bf16 v[10:13], v[148:151], v[248:251], v[10:13]
	s_setprio 0
	s_movk_i32 s0, 0x100
	v_cmp_gt_u32_e32 vcc, s0, v142
	s_barrier
	s_and_saveexec_b64 s[0:1], vcc
	s_cbranch_execz .LBB0_81
	s_barrier
	s_branch .LBB0_81

.LBB0_180:
	ds_read_b128 v[164:167], v151
	ds_read_b128 v[168:171], v151 offset:1024
	ds_read_b128 v[172:175], v151 offset:2048
	ds_read_b128 v[176:179], v151 offset:3072
	v_add_u32_e32 v162, 0xc000, v147
	v_lshl_add_u64 v[204:205], v[138:139], 0, s[12:13]
	v_readfirstlane_b32 s1, v162
	v_lshl_add_u64 v[210:211], v[204:205], 0, s[60:61]
	s_mov_b32 m0, s1
	v_add_u32_e32 v163, 0xe000, v147
	ds_read_b128 v[180:183], v0
	ds_read_b128 v[184:187], v0 offset:1024
	ds_read_b128 v[188:191], v0 offset:2048
	ds_read_b128 v[192:195], v0 offset:3072
	ds_read_b128 v[196:199], v0 offset:4096
	ds_read_b128 v[200:203], v0 offset:5120
	ds_read_b128 v[222:225], v0 offset:6144
	ds_read_b128 v[232:235], v0 offset:7168
	global_load_lds_dwordx4 v[210:211], off
	v_lshl_add_u64 v[210:211], v[140:141], 0, s[12:13]
	v_readfirstlane_b32 s1, v163
	v_lshl_add_u64 v[216:217], v[210:211], 0, s[60:61]
	s_mov_b32 m0, s1
	s_nop 0
	global_load_lds_dwordx4 v[216:217], off
	s_waitcnt lgkmcnt(8)
	s_waitcnt vmcnt(10)
	s_barrier
	s_waitcnt lgkmcnt(0)
	s_setprio 1
	s_waitcnt lgkmcnt(0)
	v_mfma_f32_16x16x32_bf16 v[126:129], v[164:167], v[180:183], v[126:129]
	v_mfma_f32_16x16x32_bf16 v[122:125], v[172:175], v[180:183], v[122:125]
	v_mfma_f32_16x16x32_bf16 v[118:121], v[164:167], v[188:191], v[118:121]
	v_mfma_f32_16x16x32_bf16 v[114:117], v[172:175], v[188:191], v[114:117]
	v_mfma_f32_16x16x32_bf16 v[110:113], v[164:167], v[196:199], v[110:113]
	v_mfma_f32_16x16x32_bf16 v[106:109], v[172:175], v[196:199], v[106:109]
	v_mfma_f32_16x16x32_bf16 v[102:105], v[164:167], v[222:225], v[102:105]
	v_mfma_f32_16x16x32_bf16 v[98:101], v[172:175], v[222:225], v[98:101]
	v_mfma_f32_16x16x32_bf16 v[126:129], v[168:171], v[184:187], v[126:129]
	v_mfma_f32_16x16x32_bf16 v[122:125], v[176:179], v[184:187], v[122:125]
	v_mfma_f32_16x16x32_bf16 v[118:121], v[168:171], v[192:195], v[118:121]
	v_mfma_f32_16x16x32_bf16 v[114:117], v[176:179], v[192:195], v[114:117]
	v_mfma_f32_16x16x32_bf16 v[110:113], v[168:171], v[200:203], v[110:113]
	v_mfma_f32_16x16x32_bf16 v[106:109], v[176:179], v[200:203], v[106:109]
	v_mfma_f32_16x16x32_bf16 v[102:105], v[168:171], v[232:235], v[102:105]
	v_mfma_f32_16x16x32_bf16 v[98:101], v[176:179], v[232:235], v[98:101]
	s_setprio 0
	s_barrier
	v_lshl_add_u64 v[216:217], v[134:135], 0, s[12:13]
	v_readfirstlane_b32 s1, v149
	v_lshl_add_u64 v[218:219], v[216:217], 0, s[74:75]
	s_mov_b32 m0, s1
	ds_read_b128 v[236:239], v151 offset:16384
	ds_read_b128 v[240:243], v151 offset:17408
	ds_read_b128 v[244:247], v151 offset:18432
	ds_read_b128 v[248:251], v151 offset:19456
	global_load_lds_dwordx4 v[218:219], off
	v_lshl_add_u64 v[218:219], v[136:137], 0, s[12:13]
	v_readfirstlane_b32 s1, v150
	v_lshl_add_u64 v[228:229], v[218:219], 0, s[74:75]
	s_mov_b32 m0, s1
	s_nop 0
	global_load_lds_dwordx4 v[228:229], off
	s_waitcnt vmcnt(10)
	s_barrier
	s_waitcnt lgkmcnt(0)
	s_setprio 1
	s_waitcnt lgkmcnt(0)
	v_mfma_f32_16x16x32_bf16 v[94:97], v[236:239], v[180:183], v[94:97]
	v_mfma_f32_16x16x32_bf16 v[90:93], v[244:247], v[180:183], v[90:93]
	v_mfma_f32_16x16x32_bf16 v[86:89], v[236:239], v[188:191], v[86:89]
	v_mfma_f32_16x16x32_bf16 v[82:85], v[244:247], v[188:191], v[82:85]
	v_mfma_f32_16x16x32_bf16 v[78:81], v[236:239], v[196:199], v[78:81]
	v_mfma_f32_16x16x32_bf16 v[74:77], v[244:247], v[196:199], v[74:77]
	v_mfma_f32_16x16x32_bf16 v[70:73], v[236:239], v[222:225], v[70:73]
	v_mfma_f32_16x16x32_bf16 v[66:69], v[244:247], v[222:225], v[66:69]
	v_mfma_f32_16x16x32_bf16 v[94:97], v[240:243], v[184:187], v[94:97]
	v_mfma_f32_16x16x32_bf16 v[90:93], v[248:251], v[184:187], v[90:93]
	v_mfma_f32_16x16x32_bf16 v[86:89], v[240:243], v[192:195], v[86:89]
	v_mfma_f32_16x16x32_bf16 v[82:85], v[248:251], v[192:195], v[82:85]
	v_mfma_f32_16x16x32_bf16 v[78:81], v[240:243], v[200:203], v[78:81]
	v_mfma_f32_16x16x32_bf16 v[74:77], v[248:251], v[200:203], v[74:77]
	v_mfma_f32_16x16x32_bf16 v[70:73], v[240:243], v[232:235], v[70:73]
	v_mfma_f32_16x16x32_bf16 v[66:69], v[248:251], v[232:235], v[66:69]
	s_setprio 0
	v_readfirstlane_b32 s1, v147
	v_lshl_add_u64 v[228:229], v[204:205], 0, s[74:75]
	s_mov_b32 m0, s1
	v_readfirstlane_b32 s1, v148
	s_barrier
	ds_read_b128 v[180:183], v0 offset:16384
	ds_read_b128 v[184:187], v0 offset:17408
	ds_read_b128 v[188:191], v0 offset:18432
	ds_read_b128 v[192:195], v0 offset:19456
	ds_read_b128 v[196:199], v0 offset:20480
	ds_read_b128 v[200:203], v0 offset:21504
	ds_read_b128 v[222:225], v0 offset:22528
	ds_read_b128 v[232:235], v0 offset:23552
	global_load_lds_dwordx4 v[228:229], off
	v_lshl_add_u64 v[228:229], v[210:211], 0, s[74:75]
	s_mov_b32 m0, s1
	s_nop 0
	global_load_lds_dwordx4 v[228:229], off
	s_barrier
	s_waitcnt lgkmcnt(0)
	s_setprio 1
	s_waitcnt lgkmcnt(0)
	v_mfma_f32_16x16x32_bf16 v[62:65], v[164:167], v[180:183], v[62:65]
	v_mfma_f32_16x16x32_bf16 v[58:61], v[172:175], v[180:183], v[58:61]
	v_mfma_f32_16x16x32_bf16 v[54:57], v[164:167], v[188:191], v[54:57]
	v_mfma_f32_16x16x32_bf16 v[50:53], v[172:175], v[188:191], v[50:53]
	v_mfma_f32_16x16x32_bf16 v[46:49], v[164:167], v[196:199], v[46:49]
	v_mfma_f32_16x16x32_bf16 v[42:45], v[172:175], v[196:199], v[42:45]
	v_mfma_f32_16x16x32_bf16 v[38:41], v[164:167], v[222:225], v[38:41]
	v_mfma_f32_16x16x32_bf16 v[34:37], v[172:175], v[222:225], v[34:37]
	v_mfma_f32_16x16x32_bf16 v[62:65], v[168:171], v[184:187], v[62:65]
	v_mfma_f32_16x16x32_bf16 v[58:61], v[176:179], v[184:187], v[58:61]
	v_mfma_f32_16x16x32_bf16 v[54:57], v[168:171], v[192:195], v[54:57]
	v_mfma_f32_16x16x32_bf16 v[50:53], v[176:179], v[192:195], v[50:53]
	v_mfma_f32_16x16x32_bf16 v[46:49], v[168:171], v[200:203], v[46:49]
	v_mfma_f32_16x16x32_bf16 v[42:45], v[176:179], v[200:203], v[42:45]
	v_mfma_f32_16x16x32_bf16 v[38:41], v[168:171], v[232:235], v[38:41]
	v_mfma_f32_16x16x32_bf16 v[34:37], v[176:179], v[232:235], v[34:37]
	s_setprio 0
	s_barrier
	v_readfirstlane_b32 s1, v152
	v_lshl_add_u64 v[164:165], v[216:217], 0, s[18:19]
	s_mov_b32 m0, s1
	v_readfirstlane_b32 s1, v153
	global_load_lds_dwordx4 v[164:165], off
	v_lshl_add_u64 v[164:165], v[218:219], 0, s[18:19]
	s_mov_b32 m0, s1
	s_nop 0
	global_load_lds_dwordx4 v[164:165], off
	s_waitcnt vmcnt(10)
	s_barrier
	s_setprio 1
	v_mfma_f32_16x16x32_bf16 v[30:33], v[236:239], v[180:183], v[30:33]
	v_mfma_f32_16x16x32_bf16 v[26:29], v[244:247], v[180:183], v[26:29]
	v_mfma_f32_16x16x32_bf16 v[22:25], v[236:239], v[188:191], v[22:25]
	v_mfma_f32_16x16x32_bf16 v[18:21], v[244:247], v[188:191], v[18:21]
	v_mfma_f32_16x16x32_bf16 v[14:17], v[236:239], v[196:199], v[14:17]
	v_mfma_f32_16x16x32_bf16 v[10:13], v[244:247], v[196:199], v[10:13]
	v_mfma_f32_16x16x32_bf16 v[6:9], v[236:239], v[222:225], v[6:9]
	v_mfma_f32_16x16x32_bf16 v[2:5], v[244:247], v[222:225], v[2:5]
	v_mfma_f32_16x16x32_bf16 v[30:33], v[240:243], v[184:187], v[30:33]
	v_mfma_f32_16x16x32_bf16 v[26:29], v[248:251], v[184:187], v[26:29]
	v_mfma_f32_16x16x32_bf16 v[22:25], v[240:243], v[192:195], v[22:25]
	v_mfma_f32_16x16x32_bf16 v[18:21], v[248:251], v[192:195], v[18:21]
	v_mfma_f32_16x16x32_bf16 v[14:17], v[240:243], v[200:203], v[14:17]
	v_mfma_f32_16x16x32_bf16 v[10:13], v[248:251], v[200:203], v[10:13]
	v_mfma_f32_16x16x32_bf16 v[6:9], v[240:243], v[232:235], v[6:9]
	v_mfma_f32_16x16x32_bf16 v[2:5], v[248:251], v[232:235], v[2:5]
	s_setprio 0
	s_barrier
	ds_read_b128 v[164:167], v151 offset:32768
	ds_read_b128 v[168:171], v151 offset:33792
	ds_read_b128 v[172:175], v151 offset:34816
	ds_read_b128 v[176:179], v151 offset:35840
	v_readfirstlane_b32 s1, v154
	v_lshl_add_u64 v[228:229], v[204:205], 0, s[18:19]
	s_mov_b32 m0, s1
	v_readfirstlane_b32 s1, v155
	ds_read_b128 v[180:183], v0 offset:32768
	ds_read_b128 v[184:187], v0 offset:33792
	ds_read_b128 v[188:191], v0 offset:34816
	ds_read_b128 v[192:195], v0 offset:35840
	ds_read_b128 v[196:199], v0 offset:36864
	ds_read_b128 v[200:203], v0 offset:37888
	ds_read_b128 v[222:225], v0 offset:38912
	ds_read_b128 v[232:235], v0 offset:39936
	global_load_lds_dwordx4 v[228:229], off
	v_lshl_add_u64 v[228:229], v[210:211], 0, s[18:19]
	s_mov_b32 m0, s1
	s_nop 0
	global_load_lds_dwordx4 v[228:229], off
	s_waitcnt lgkmcnt(8)
	s_waitcnt vmcnt(10)
	s_barrier
	s_waitcnt lgkmcnt(0)
	s_setprio 1
	s_waitcnt lgkmcnt(0)
	v_mfma_f32_16x16x32_bf16 v[126:129], v[164:167], v[180:183], v[126:129]
	v_mfma_f32_16x16x32_bf16 v[122:125], v[172:175], v[180:183], v[122:125]
	v_mfma_f32_16x16x32_bf16 v[118:121], v[164:167], v[188:191], v[118:121]
	v_mfma_f32_16x16x32_bf16 v[114:117], v[172:175], v[188:191], v[114:117]
	v_mfma_f32_16x16x32_bf16 v[110:113], v[164:167], v[196:199], v[110:113]
	v_mfma_f32_16x16x32_bf16 v[106:109], v[172:175], v[196:199], v[106:109]
	v_mfma_f32_16x16x32_bf16 v[102:105], v[164:167], v[222:225], v[102:105]
	v_mfma_f32_16x16x32_bf16 v[98:101], v[172:175], v[222:225], v[98:101]
	v_mfma_f32_16x16x32_bf16 v[126:129], v[168:171], v[184:187], v[126:129]
	v_mfma_f32_16x16x32_bf16 v[122:125], v[176:179], v[184:187], v[122:125]
	v_mfma_f32_16x16x32_bf16 v[118:121], v[168:171], v[192:195], v[118:121]
	v_mfma_f32_16x16x32_bf16 v[114:117], v[176:179], v[192:195], v[114:117]
	v_mfma_f32_16x16x32_bf16 v[110:113], v[168:171], v[200:203], v[110:113]
	v_mfma_f32_16x16x32_bf16 v[106:109], v[176:179], v[200:203], v[106:109]
	v_mfma_f32_16x16x32_bf16 v[102:105], v[168:171], v[232:235], v[102:105]
	v_mfma_f32_16x16x32_bf16 v[98:101], v[176:179], v[232:235], v[98:101]
	s_setprio 0
	s_barrier
	v_readfirstlane_b32 s1, v156
	v_lshl_add_u64 v[228:229], v[216:217], 0, s[28:29]
	s_mov_b32 m0, s1
	v_readfirstlane_b32 s1, v157
	ds_read_b128 v[236:239], v151 offset:49152
	ds_read_b128 v[240:243], v151 offset:50176
	ds_read_b128 v[244:247], v151 offset:51200
	ds_read_b128 v[248:251], v151 offset:52224
	global_load_lds_dwordx4 v[228:229], off
	v_lshl_add_u64 v[228:229], v[218:219], 0, s[28:29]
	s_mov_b32 m0, s1
	s_nop 0
	global_load_lds_dwordx4 v[228:229], off
	s_waitcnt vmcnt(10)
	s_barrier
	s_waitcnt lgkmcnt(0)
	s_setprio 1
	s_waitcnt lgkmcnt(0)
	v_mfma_f32_16x16x32_bf16 v[94:97], v[236:239], v[180:183], v[94:97]
	v_mfma_f32_16x16x32_bf16 v[90:93], v[244:247], v[180:183], v[90:93]
	v_mfma_f32_16x16x32_bf16 v[86:89], v[236:239], v[188:191], v[86:89]
	v_mfma_f32_16x16x32_bf16 v[82:85], v[244:247], v[188:191], v[82:85]
	v_mfma_f32_16x16x32_bf16 v[78:81], v[236:239], v[196:199], v[78:81]
	v_mfma_f32_16x16x32_bf16 v[74:77], v[244:247], v[196:199], v[74:77]
	v_mfma_f32_16x16x32_bf16 v[70:73], v[236:239], v[222:225], v[70:73]
	v_mfma_f32_16x16x32_bf16 v[66:69], v[244:247], v[222:225], v[66:69]
	v_mfma_f32_16x16x32_bf16 v[94:97], v[240:243], v[184:187], v[94:97]
	v_mfma_f32_16x16x32_bf16 v[90:93], v[248:251], v[184:187], v[90:93]
	v_mfma_f32_16x16x32_bf16 v[86:89], v[240:243], v[192:195], v[86:89]
	v_mfma_f32_16x16x32_bf16 v[82:85], v[248:251], v[192:195], v[82:85]
	v_mfma_f32_16x16x32_bf16 v[78:81], v[240:243], v[200:203], v[78:81]
	v_mfma_f32_16x16x32_bf16 v[74:77], v[248:251], v[200:203], v[74:77]
	v_mfma_f32_16x16x32_bf16 v[70:73], v[240:243], v[232:235], v[70:73]
	v_mfma_f32_16x16x32_bf16 v[66:69], v[248:251], v[232:235], v[66:69]
	s_setprio 0
	v_readfirstlane_b32 s1, v158
	v_lshl_add_u64 v[204:205], v[204:205], 0, s[28:29]
	s_mov_b32 m0, s1
	v_readfirstlane_b32 s1, v159
	s_barrier
	ds_read_b128 v[180:183], v0 offset:49152
	ds_read_b128 v[184:187], v0 offset:50176
	ds_read_b128 v[188:191], v0 offset:51200
	ds_read_b128 v[192:195], v0 offset:52224
	ds_read_b128 v[196:199], v0 offset:53248
	ds_read_b128 v[200:203], v0 offset:54272
	ds_read_b128 v[222:225], v0 offset:55296
	ds_read_b128 v[232:235], v0 offset:56320
	global_load_lds_dwordx4 v[204:205], off
	v_lshl_add_u64 v[204:205], v[210:211], 0, s[28:29]
	s_mov_b32 m0, s1
	s_nop 0
	global_load_lds_dwordx4 v[204:205], off
	s_barrier
	s_waitcnt lgkmcnt(0)
	s_setprio 1
	s_waitcnt lgkmcnt(0)
	v_mfma_f32_16x16x32_bf16 v[62:65], v[164:167], v[180:183], v[62:65]
	v_mfma_f32_16x16x32_bf16 v[58:61], v[172:175], v[180:183], v[58:61]
	v_mfma_f32_16x16x32_bf16 v[54:57], v[164:167], v[188:191], v[54:57]
	v_mfma_f32_16x16x32_bf16 v[50:53], v[172:175], v[188:191], v[50:53]
	v_mfma_f32_16x16x32_bf16 v[46:49], v[164:167], v[196:199], v[46:49]
	v_mfma_f32_16x16x32_bf16 v[42:45], v[172:175], v[196:199], v[42:45]
	v_mfma_f32_16x16x32_bf16 v[38:41], v[164:167], v[222:225], v[38:41]
	v_mfma_f32_16x16x32_bf16 v[34:37], v[172:175], v[222:225], v[34:37]
	v_mfma_f32_16x16x32_bf16 v[62:65], v[168:171], v[184:187], v[62:65]
	v_mfma_f32_16x16x32_bf16 v[58:61], v[176:179], v[184:187], v[58:61]
	v_mfma_f32_16x16x32_bf16 v[54:57], v[168:171], v[192:195], v[54:57]
	v_mfma_f32_16x16x32_bf16 v[50:53], v[176:179], v[192:195], v[50:53]
	v_mfma_f32_16x16x32_bf16 v[46:49], v[168:171], v[200:203], v[46:49]
	v_mfma_f32_16x16x32_bf16 v[42:45], v[176:179], v[200:203], v[42:45]
	v_mfma_f32_16x16x32_bf16 v[38:41], v[168:171], v[232:235], v[38:41]
	v_mfma_f32_16x16x32_bf16 v[34:37], v[176:179], v[232:235], v[34:37]
	s_setprio 0
	s_barrier
	v_readfirstlane_b32 s1, v160
	v_lshl_add_u64 v[164:165], v[216:217], 0, s[30:31]
	s_mov_b32 m0, s1
	v_readfirstlane_b32 s1, v161
	global_load_lds_dwordx4 v[164:165], off
	v_lshl_add_u64 v[164:165], v[218:219], 0, s[30:31]
	s_mov_b32 m0, s1
	s_nop 0
	global_load_lds_dwordx4 v[164:165], off
	s_waitcnt vmcnt(10)
	s_barrier
	s_setprio 1
	v_mfma_f32_16x16x32_bf16 v[30:33], v[236:239], v[180:183], v[30:33]
	v_mfma_f32_16x16x32_bf16 v[26:29], v[244:247], v[180:183], v[26:29]
	v_mfma_f32_16x16x32_bf16 v[22:25], v[236:239], v[188:191], v[22:25]
	v_mfma_f32_16x16x32_bf16 v[18:21], v[244:247], v[188:191], v[18:21]
	v_mfma_f32_16x16x32_bf16 v[14:17], v[236:239], v[196:199], v[14:17]
	v_mfma_f32_16x16x32_bf16 v[10:13], v[244:247], v[196:199], v[10:13]
	v_mfma_f32_16x16x32_bf16 v[6:9], v[236:239], v[222:225], v[6:9]
	v_mfma_f32_16x16x32_bf16 v[2:5], v[244:247], v[222:225], v[2:5]
	v_mfma_f32_16x16x32_bf16 v[30:33], v[240:243], v[184:187], v[30:33]
	v_mfma_f32_16x16x32_bf16 v[26:29], v[248:251], v[184:187], v[26:29]
	v_mfma_f32_16x16x32_bf16 v[22:25], v[240:243], v[192:195], v[22:25]
	v_mfma_f32_16x16x32_bf16 v[18:21], v[248:251], v[192:195], v[18:21]
	v_mfma_f32_16x16x32_bf16 v[14:17], v[240:243], v[200:203], v[14:17]
	v_mfma_f32_16x16x32_bf16 v[10:13], v[248:251], v[200:203], v[10:13]
	v_mfma_f32_16x16x32_bf16 v[6:9], v[240:243], v[232:235], v[6:9]
	v_mfma_f32_16x16x32_bf16 v[2:5], v[248:251], v[232:235], v[2:5]
	s_setprio 0
	s_add_i32 s0, s0, 2
	s_add_u32 s12, s12, 0x100
	s_addc_u32 s13, s13, 0
	s_cmp_lt_u32 s0, 28
	s_barrier
	s_cbranch_scc1 .LBB0_180
	s_mov_b64 s[12:13], 0xf80
	v_readfirstlane_b32 s0, v162
	v_lshl_add_u64 v[132:133], v[132:133], 0, s[12:13]
	s_mov_b32 m0, s0
	v_readfirstlane_b32 s0, v163
	ds_read_b128 v[134:137], v151
	ds_read_b128 v[138:141], v151 offset:1024
	ds_read_b128 v[152:155], v151 offset:2048
	ds_read_b128 v[156:159], v151 offset:3072
	ds_read_b128 v[164:167], v0
	ds_read_b128 v[168:171], v0 offset:1024
	ds_read_b128 v[172:175], v0 offset:2048
	ds_read_b128 v[176:179], v0 offset:3072
	ds_read_b128 v[180:183], v0 offset:4096
	ds_read_b128 v[184:187], v0 offset:5120
	ds_read_b128 v[188:191], v0 offset:6144
	ds_read_b128 v[192:195], v0 offset:7168
	global_load_lds_dwordx4 v[132:133], off
	v_lshl_add_u64 v[130:131], v[130:131], 0, s[12:13]
	s_mov_b32 m0, s0
	s_nop 0
	global_load_lds_dwordx4 v[130:131], off
	s_barrier
	s_waitcnt lgkmcnt(0)
	s_setprio 1
	s_waitcnt lgkmcnt(0)
	v_mfma_f32_16x16x32_bf16 v[126:129], v[134:137], v[164:167], v[126:129]
	v_mfma_f32_16x16x32_bf16 v[122:125], v[152:155], v[164:167], v[122:125]
	v_mfma_f32_16x16x32_bf16 v[114:117], v[152:155], v[172:175], v[114:117]
	v_mfma_f32_16x16x32_bf16 v[106:109], v[152:155], v[180:183], v[106:109]
	v_mfma_f32_16x16x32_bf16 v[98:101], v[152:155], v[188:191], v[98:101]
	v_mfma_f32_16x16x32_bf16 v[126:129], v[138:141], v[168:171], v[126:129]
	v_mfma_f32_16x16x32_bf16 v[122:125], v[156:159], v[168:171], v[122:125]
	v_mfma_f32_16x16x32_bf16 v[118:121], v[134:137], v[172:175], v[118:121]
	v_mfma_f32_16x16x32_bf16 v[114:117], v[156:159], v[176:179], v[114:117]
	v_mfma_f32_16x16x32_bf16 v[110:113], v[134:137], v[180:183], v[110:113]
	v_mfma_f32_16x16x32_bf16 v[106:109], v[156:159], v[184:187], v[106:109]
	v_mfma_f32_16x16x32_bf16 v[102:105], v[134:137], v[188:191], v[102:105]
	v_mfma_f32_16x16x32_bf16 v[98:101], v[156:159], v[192:195], v[98:101]
	v_mfma_f32_16x16x32_bf16 v[130:133], v[138:141], v[176:179], v[118:121]
	v_mfma_f32_16x16x32_bf16 v[160:163], v[138:141], v[184:187], v[110:113]
	v_mfma_f32_16x16x32_bf16 v[196:199], v[138:141], v[192:195], v[102:105]
	s_setprio 0
	s_barrier
	s_nop 0
	ds_read_b128 v[102:105], v151 offset:16384
	ds_read_b128 v[110:113], v151 offset:17408
	ds_read_b128 v[118:121], v151 offset:18432
	ds_read_b128 v[200:203], v151 offset:19456
	s_barrier
	s_waitcnt lgkmcnt(0)
	s_setprio 1
	s_waitcnt lgkmcnt(1)
	v_mfma_f32_16x16x32_bf16 v[90:93], v[118:121], v[164:167], v[90:93]
	v_mfma_f32_16x16x32_bf16 v[82:85], v[118:121], v[172:175], v[82:85]
	v_mfma_f32_16x16x32_bf16 v[74:77], v[118:121], v[180:183], v[74:77]
	v_mfma_f32_16x16x32_bf16 v[66:69], v[118:121], v[188:191], v[66:69]
	v_mfma_f32_16x16x32_bf16 v[94:97], v[102:105], v[164:167], v[94:97]
	s_waitcnt lgkmcnt(0)
	v_mfma_f32_16x16x32_bf16 v[90:93], v[200:203], v[168:171], v[90:93]
	v_mfma_f32_16x16x32_bf16 v[86:89], v[102:105], v[172:175], v[86:89]
	v_mfma_f32_16x16x32_bf16 v[82:85], v[200:203], v[176:179], v[82:85]
	v_mfma_f32_16x16x32_bf16 v[78:81], v[102:105], v[180:183], v[78:81]
	v_mfma_f32_16x16x32_bf16 v[74:77], v[200:203], v[184:187], v[74:77]
	v_mfma_f32_16x16x32_bf16 v[70:73], v[102:105], v[188:191], v[70:73]
	v_mfma_f32_16x16x32_bf16 v[66:69], v[200:203], v[192:195], v[66:69]
	v_mfma_f32_16x16x32_bf16 v[222:225], v[110:113], v[168:171], v[94:97]
	v_mfma_f32_16x16x32_bf16 v[164:167], v[110:113], v[176:179], v[86:89]
	v_mfma_f32_16x16x32_bf16 v[168:171], v[110:113], v[184:187], v[78:81]
	v_mfma_f32_16x16x32_bf16 v[172:175], v[110:113], v[192:195], v[70:73]
	s_setprio 0
	s_barrier
	s_nop 0
	ds_read_b128 v[70:73], v0 offset:16384
	ds_read_b128 v[78:81], v0 offset:17408
	ds_read_b128 v[86:89], v0 offset:18432
	ds_read_b128 v[94:97], v0 offset:19456
	ds_read_b128 v[176:179], v0 offset:20480
	ds_read_b128 v[180:183], v0 offset:21504
	ds_read_b128 v[184:187], v0 offset:22528
	ds_read_b128 v[188:191], v0 offset:23552
	s_waitcnt vmcnt(4)
	s_barrier
	s_waitcnt lgkmcnt(0)
	s_setprio 1
	s_waitcnt lgkmcnt(7)
	v_mfma_f32_16x16x32_bf16 v[62:65], v[134:137], v[70:73], v[62:65]
	v_mfma_f32_16x16x32_bf16 v[58:61], v[152:155], v[70:73], v[58:61]
	s_waitcnt lgkmcnt(5)
	v_mfma_f32_16x16x32_bf16 v[50:53], v[152:155], v[86:89], v[50:53]
	s_waitcnt lgkmcnt(3)
	v_mfma_f32_16x16x32_bf16 v[42:45], v[152:155], v[176:179], v[42:45]
	s_waitcnt lgkmcnt(1)
	v_mfma_f32_16x16x32_bf16 v[34:37], v[152:155], v[184:187], v[34:37]
	v_mfma_f32_16x16x32_bf16 v[62:65], v[138:141], v[78:81], v[62:65]
	v_mfma_f32_16x16x32_bf16 v[58:61], v[156:159], v[78:81], v[58:61]
	v_mfma_f32_16x16x32_bf16 v[54:57], v[134:137], v[86:89], v[54:57]
	v_mfma_f32_16x16x32_bf16 v[50:53], v[156:159], v[94:97], v[50:53]
	v_mfma_f32_16x16x32_bf16 v[46:49], v[134:137], v[176:179], v[46:49]
	v_mfma_f32_16x16x32_bf16 v[42:45], v[156:159], v[180:183], v[42:45]
	v_mfma_f32_16x16x32_bf16 v[38:41], v[134:137], v[184:187], v[38:41]
	s_waitcnt lgkmcnt(0)
	v_mfma_f32_16x16x32_bf16 v[34:37], v[156:159], v[188:191], v[34:37]
	v_mfma_f32_16x16x32_bf16 v[192:195], v[138:141], v[94:97], v[54:57]
	v_mfma_f32_16x16x32_bf16 v[232:235], v[138:141], v[180:183], v[46:49]
	v_mfma_f32_16x16x32_bf16 v[134:137], v[138:141], v[188:191], v[38:41]
	s_setprio 0
	s_setprio 1
	v_mfma_f32_16x16x32_bf16 v[26:29], v[118:121], v[70:73], v[26:29]
	v_mfma_f32_16x16x32_bf16 v[18:21], v[118:121], v[86:89], v[18:21]
	v_mfma_f32_16x16x32_bf16 v[10:13], v[118:121], v[176:179], v[10:13]
	v_mfma_f32_16x16x32_bf16 v[2:5], v[118:121], v[184:187], v[2:5]
	v_mfma_f32_16x16x32_bf16 v[30:33], v[102:105], v[70:73], v[30:33]
	v_mfma_f32_16x16x32_bf16 v[26:29], v[200:203], v[78:81], v[26:29]
	v_mfma_f32_16x16x32_bf16 v[22:25], v[102:105], v[86:89], v[22:25]
	v_mfma_f32_16x16x32_bf16 v[18:21], v[200:203], v[94:97], v[18:21]
	v_mfma_f32_16x16x32_bf16 v[14:17], v[102:105], v[176:179], v[14:17]
	v_mfma_f32_16x16x32_bf16 v[10:13], v[200:203], v[180:183], v[10:13]
	v_mfma_f32_16x16x32_bf16 v[6:9], v[102:105], v[184:187], v[6:9]
	v_mfma_f32_16x16x32_bf16 v[2:5], v[200:203], v[188:191], v[2:5]
	v_mfma_f32_16x16x32_bf16 v[138:141], v[110:113], v[78:81], v[30:33]
	v_mfma_f32_16x16x32_bf16 v[152:155], v[110:113], v[94:97], v[22:25]
	v_mfma_f32_16x16x32_bf16 v[156:159], v[110:113], v[180:183], v[14:17]
	v_mfma_f32_16x16x32_bf16 v[176:179], v[110:113], v[188:191], v[6:9]
	s_setprio 0
	s_barrier
	s_nop 0
	ds_read_b128 v[6:9], v151 offset:32768
	ds_read_b128 v[14:17], v151 offset:33792
	ds_read_b128 v[180:183], v151 offset:34816
	ds_read_b128 v[184:187], v151 offset:35840
	ds_read_b128 v[22:25], v0 offset:32768
	ds_read_b128 v[30:33], v0 offset:33792
	ds_read_b128 v[38:41], v0 offset:34816
	ds_read_b128 v[46:49], v0 offset:35840
	ds_read_b128 v[54:57], v0 offset:36864
	ds_read_b128 v[188:191], v0 offset:37888
	ds_read_b128 v[200:203], v0 offset:38912
	ds_read_b128 v[236:239], v0 offset:39936
	s_waitcnt vmcnt(2)
	s_barrier
	s_waitcnt lgkmcnt(0)
	s_setprio 1
	s_waitcnt lgkmcnt(7)
	v_mfma_f32_16x16x32_bf16 v[70:73], v[6:9], v[22:25], v[126:129]
	s_waitcnt lgkmcnt(6)
	v_mfma_f32_16x16x32_bf16 v[126:129], v[14:17], v[30:33], v[70:73]
	v_mfma_f32_16x16x32_bf16 v[70:73], v[180:183], v[22:25], v[122:125]
	v_mfma_f32_16x16x32_bf16 v[118:121], v[184:187], v[30:33], v[70:73]
	s_waitcnt lgkmcnt(5)
	v_mfma_f32_16x16x32_bf16 v[70:73], v[6:9], v[38:41], v[130:133]
	s_waitcnt lgkmcnt(4)
	v_mfma_f32_16x16x32_bf16 v[110:113], v[14:17], v[46:49], v[70:73]
	v_mfma_f32_16x16x32_bf16 v[70:73], v[180:183], v[38:41], v[114:117]
	v_mfma_f32_16x16x32_bf16 v[102:105], v[184:187], v[46:49], v[70:73]
	s_waitcnt lgkmcnt(3)
	v_mfma_f32_16x16x32_bf16 v[70:73], v[6:9], v[54:57], v[160:163]
	s_waitcnt lgkmcnt(2)
	v_mfma_f32_16x16x32_bf16 v[94:97], v[14:17], v[188:191], v[70:73]
	v_mfma_f32_16x16x32_bf16 v[70:73], v[180:183], v[54:57], v[106:109]
	v_mfma_f32_16x16x32_bf16 v[86:89], v[184:187], v[188:191], v[70:73]
	s_waitcnt lgkmcnt(1)
	v_mfma_f32_16x16x32_bf16 v[70:73], v[6:9], v[200:203], v[196:199]
	s_waitcnt lgkmcnt(0)
	v_mfma_f32_16x16x32_bf16 v[78:81], v[14:17], v[236:239], v[70:73]
	v_mfma_f32_16x16x32_bf16 v[70:73], v[180:183], v[200:203], v[98:101]
	v_mfma_f32_16x16x32_bf16 v[70:73], v[184:187], v[236:239], v[70:73]
	s_setprio 0
	s_barrier
	ds_read_b128 v[130:133], v151 offset:49152
	ds_read_b128 v[160:163], v151 offset:50176
	ds_read_b128 v[196:199], v151 offset:51200
	ds_read_b128 v[148:151], v151 offset:52224
	s_waitcnt vmcnt(0)
	s_barrier
	s_waitcnt lgkmcnt(0)
	s_setprio 1
	s_waitcnt lgkmcnt(3)
	v_mfma_f32_16x16x32_bf16 v[98:101], v[130:133], v[22:25], v[222:225]
	s_waitcnt lgkmcnt(1)
	v_mfma_f32_16x16x32_bf16 v[22:25], v[196:199], v[22:25], v[90:93]
	s_waitcnt lgkmcnt(0)
	v_mfma_f32_16x16x32_bf16 v[114:117], v[148:151], v[30:33], v[22:25]
	v_mfma_f32_16x16x32_bf16 v[22:25], v[130:133], v[38:41], v[164:167]
	v_mfma_f32_16x16x32_bf16 v[106:109], v[160:163], v[46:49], v[22:25]
	v_mfma_f32_16x16x32_bf16 v[22:25], v[196:199], v[38:41], v[82:85]
	v_mfma_f32_16x16x32_bf16 v[122:125], v[160:163], v[30:33], v[98:101]
	v_mfma_f32_16x16x32_bf16 v[98:101], v[148:151], v[46:49], v[22:25]
	v_mfma_f32_16x16x32_bf16 v[22:25], v[130:133], v[54:57], v[168:171]
	v_mfma_f32_16x16x32_bf16 v[90:93], v[160:163], v[188:191], v[22:25]
	v_mfma_f32_16x16x32_bf16 v[22:25], v[196:199], v[54:57], v[74:77]
	v_mfma_f32_16x16x32_bf16 v[82:85], v[148:151], v[188:191], v[22:25]
	v_mfma_f32_16x16x32_bf16 v[22:25], v[130:133], v[200:203], v[172:175]
	v_mfma_f32_16x16x32_bf16 v[74:77], v[160:163], v[236:239], v[22:25]
	v_mfma_f32_16x16x32_bf16 v[22:25], v[196:199], v[200:203], v[66:69]
	v_mfma_f32_16x16x32_bf16 v[66:69], v[148:151], v[236:239], v[22:25]
	s_setprio 0
	s_barrier
	ds_read_b128 v[164:167], v0 offset:49152
	ds_read_b128 v[168:171], v0 offset:50176
	ds_read_b128 v[172:175], v0 offset:51200
	ds_read_b128 v[188:191], v0 offset:52224
	ds_read_b128 v[200:203], v0 offset:53248
	ds_read_b128 v[222:225], v0 offset:54272
	ds_read_b128 v[236:239], v0 offset:55296
	ds_read_b128 v[240:243], v0 offset:56320
	s_barrier
	s_waitcnt lgkmcnt(0)
	s_setprio 1
	s_waitcnt lgkmcnt(7)
	v_mfma_f32_16x16x32_bf16 v[22:25], v[6:9], v[164:167], v[62:65]
	s_waitcnt lgkmcnt(6)
	v_mfma_f32_16x16x32_bf16 v[62:65], v[14:17], v[168:171], v[22:25]
	v_mfma_f32_16x16x32_bf16 v[22:25], v[180:183], v[164:167], v[58:61]
	v_mfma_f32_16x16x32_bf16 v[54:57], v[184:187], v[168:171], v[22:25]
	s_waitcnt lgkmcnt(5)
	v_mfma_f32_16x16x32_bf16 v[22:25], v[6:9], v[172:175], v[192:195]
	s_waitcnt lgkmcnt(4)
	v_mfma_f32_16x16x32_bf16 v[46:49], v[14:17], v[188:191], v[22:25]
	v_mfma_f32_16x16x32_bf16 v[22:25], v[180:183], v[172:175], v[50:53]
	v_mfma_f32_16x16x32_bf16 v[38:41], v[184:187], v[188:191], v[22:25]
	s_waitcnt lgkmcnt(3)
	v_mfma_f32_16x16x32_bf16 v[22:25], v[6:9], v[200:203], v[232:235]
	s_waitcnt lgkmcnt(1)
	v_mfma_f32_16x16x32_bf16 v[6:9], v[6:9], v[236:239], v[134:137]
	v_mfma_f32_16x16x32_bf16 v[30:33], v[14:17], v[222:225], v[22:25]
	v_mfma_f32_16x16x32_bf16 v[22:25], v[180:183], v[200:203], v[42:45]
	s_waitcnt lgkmcnt(0)
	v_mfma_f32_16x16x32_bf16 v[14:17], v[14:17], v[240:243], v[6:9]
	v_mfma_f32_16x16x32_bf16 v[6:9], v[180:183], v[236:239], v[34:37]
	v_mfma_f32_16x16x32_bf16 v[22:25], v[184:187], v[222:225], v[22:25]
	v_mfma_f32_16x16x32_bf16 v[6:9], v[184:187], v[240:243], v[6:9]
	s_setprio 0
	s_setprio 1
	v_mfma_f32_16x16x32_bf16 v[34:37], v[130:133], v[164:167], v[138:141]
	v_mfma_f32_16x16x32_bf16 v[26:29], v[196:199], v[164:167], v[26:29]
	v_mfma_f32_16x16x32_bf16 v[18:21], v[196:199], v[172:175], v[18:21]
	v_mfma_f32_16x16x32_bf16 v[58:61], v[160:163], v[168:171], v[34:37]
	v_mfma_f32_16x16x32_bf16 v[50:53], v[148:151], v[168:171], v[26:29]
	v_mfma_f32_16x16x32_bf16 v[26:29], v[130:133], v[172:175], v[152:155]
	v_mfma_f32_16x16x32_bf16 v[34:37], v[148:151], v[188:191], v[18:21]
	v_mfma_f32_16x16x32_bf16 v[18:21], v[130:133], v[200:203], v[156:159]
	v_mfma_f32_16x16x32_bf16 v[10:13], v[196:199], v[200:203], v[10:13]
	v_mfma_f32_16x16x32_bf16 v[42:45], v[160:163], v[188:191], v[26:29]
	v_mfma_f32_16x16x32_bf16 v[26:29], v[160:163], v[222:225], v[18:21]
	v_mfma_f32_16x16x32_bf16 v[18:21], v[148:151], v[222:225], v[10:13]
	v_mfma_f32_16x16x32_bf16 v[10:13], v[130:133], v[236:239], v[176:179]
	v_mfma_f32_16x16x32_bf16 v[2:5], v[196:199], v[236:239], v[2:5]
	v_mfma_f32_16x16x32_bf16 v[10:13], v[160:163], v[240:243], v[10:13]
	v_mfma_f32_16x16x32_bf16 v[2:5], v[148:151], v[240:243], v[2:5]
	s_setprio 0
	s_movk_i32 s0, 0x100
	v_cmp_gt_u32_e32 vcc, s0, v142
	s_barrier
	s_and_saveexec_b64 s[0:1], vcc
	s_cbranch_execz .LBB0_183
	s_barrier

.LBB0_678:
	ds_read_b128 v[164:167], v151
	ds_read_b128 v[168:171], v151 offset:1024
	ds_read_b128 v[172:175], v151 offset:2048
	ds_read_b128 v[176:179], v151 offset:3072
	v_add_u32_e32 v162, 0xc000, v147
	v_lshl_add_u64 v[204:205], v[138:139], 0, s[8:9]
	v_readfirstlane_b32 s1, v162
	v_add_u32_e32 v163, 0xe000, v147
	v_lshl_add_u64 v[222:223], v[204:205], 0, s[60:61]
	s_mov_b32 m0, s1
	v_lshl_add_u64 v[216:217], v[140:141], 0, s[8:9]
	v_readfirstlane_b32 s1, v163
	ds_read_b128 v[180:183], v0
	ds_read_b128 v[184:187], v0 offset:1024
	ds_read_b128 v[188:191], v0 offset:2048
	ds_read_b128 v[192:195], v0 offset:3072
	ds_read_b128 v[196:199], v0 offset:4096
	ds_read_b128 v[200:203], v0 offset:5120
	ds_read_b128 v[232:235], v0 offset:6144
	ds_read_b128 v[236:239], v0 offset:7168
	global_load_lds_dwordx4 v[222:223], off
	v_lshl_add_u64 v[222:223], v[216:217], 0, s[60:61]
	s_mov_b32 m0, s1
	s_nop 0
	global_load_lds_dwordx4 v[222:223], off
	s_waitcnt lgkmcnt(8)
	s_waitcnt vmcnt(10)
	s_barrier
	s_waitcnt lgkmcnt(0)
	s_setprio 1
	s_waitcnt lgkmcnt(0)
	v_mfma_f32_16x16x32_bf16 v[126:129], v[164:167], v[180:183], v[126:129]
	v_mfma_f32_16x16x32_bf16 v[122:125], v[172:175], v[180:183], v[122:125]
	v_mfma_f32_16x16x32_bf16 v[118:121], v[164:167], v[188:191], v[118:121]
	v_mfma_f32_16x16x32_bf16 v[114:117], v[172:175], v[188:191], v[114:117]
	v_mfma_f32_16x16x32_bf16 v[110:113], v[164:167], v[196:199], v[110:113]
	v_mfma_f32_16x16x32_bf16 v[106:109], v[172:175], v[196:199], v[106:109]
	v_mfma_f32_16x16x32_bf16 v[102:105], v[164:167], v[232:235], v[102:105]
	v_mfma_f32_16x16x32_bf16 v[98:101], v[172:175], v[232:235], v[98:101]
	v_mfma_f32_16x16x32_bf16 v[126:129], v[168:171], v[184:187], v[126:129]
	v_mfma_f32_16x16x32_bf16 v[122:125], v[176:179], v[184:187], v[122:125]
	v_mfma_f32_16x16x32_bf16 v[118:121], v[168:171], v[192:195], v[118:121]
	v_mfma_f32_16x16x32_bf16 v[114:117], v[176:179], v[192:195], v[114:117]
	v_mfma_f32_16x16x32_bf16 v[110:113], v[168:171], v[200:203], v[110:113]
	v_mfma_f32_16x16x32_bf16 v[106:109], v[176:179], v[200:203], v[106:109]
	v_mfma_f32_16x16x32_bf16 v[102:105], v[168:171], v[236:239], v[102:105]
	v_mfma_f32_16x16x32_bf16 v[98:101], v[176:179], v[236:239], v[98:101]
	s_setprio 0
	s_barrier
	v_lshl_add_u64 v[210:211], v[134:135], 0, s[8:9]
	v_readfirstlane_b32 s1, v149
	v_lshl_add_u64 v[228:229], v[210:211], 0, s[74:75]
	s_mov_b32 m0, s1
	ds_read_b128 v[240:243], v151 offset:16384
	ds_read_b128 v[244:247], v151 offset:17408
	ds_read_b128 v[248:251], v151 offset:18432
	ds_read_b128 v[222:225], v151 offset:19456
	global_load_lds_dwordx4 v[228:229], off
	v_lshl_add_u64 v[228:229], v[136:137], 0, s[8:9]
	v_readfirstlane_b32 s1, v150
	v_lshl_add_u64 v[218:219], v[228:229], 0, s[74:75]
	s_mov_b32 m0, s1
	s_nop 0
	global_load_lds_dwordx4 v[218:219], off
	s_waitcnt vmcnt(10)
	s_barrier
	s_waitcnt lgkmcnt(0)
	s_setprio 1
	s_waitcnt lgkmcnt(0)
	v_mfma_f32_16x16x32_bf16 v[94:97], v[240:243], v[180:183], v[94:97]
	v_mfma_f32_16x16x32_bf16 v[90:93], v[248:251], v[180:183], v[90:93]
	v_mfma_f32_16x16x32_bf16 v[86:89], v[240:243], v[188:191], v[86:89]
	v_mfma_f32_16x16x32_bf16 v[82:85], v[248:251], v[188:191], v[82:85]
	v_mfma_f32_16x16x32_bf16 v[78:81], v[240:243], v[196:199], v[78:81]
	v_mfma_f32_16x16x32_bf16 v[74:77], v[248:251], v[196:199], v[74:77]
	v_mfma_f32_16x16x32_bf16 v[70:73], v[240:243], v[232:235], v[70:73]
	v_mfma_f32_16x16x32_bf16 v[66:69], v[248:251], v[232:235], v[66:69]
	v_mfma_f32_16x16x32_bf16 v[94:97], v[244:247], v[184:187], v[94:97]
	v_mfma_f32_16x16x32_bf16 v[90:93], v[222:225], v[184:187], v[90:93]
	v_mfma_f32_16x16x32_bf16 v[86:89], v[244:247], v[192:195], v[86:89]
	v_mfma_f32_16x16x32_bf16 v[82:85], v[222:225], v[192:195], v[82:85]
	v_mfma_f32_16x16x32_bf16 v[78:81], v[244:247], v[200:203], v[78:81]
	v_mfma_f32_16x16x32_bf16 v[74:77], v[222:225], v[200:203], v[74:77]
	v_mfma_f32_16x16x32_bf16 v[70:73], v[244:247], v[236:239], v[70:73]
	v_mfma_f32_16x16x32_bf16 v[66:69], v[222:225], v[236:239], v[66:69]
	s_setprio 0
	v_readfirstlane_b32 s1, v147
	v_lshl_add_u64 v[218:219], v[204:205], 0, s[74:75]
	s_mov_b32 m0, s1
	v_readfirstlane_b32 s1, v148
	s_barrier
	ds_read_b128 v[180:183], v0 offset:16384
	ds_read_b128 v[184:187], v0 offset:17408
	ds_read_b128 v[188:191], v0 offset:18432
	ds_read_b128 v[192:195], v0 offset:19456
	ds_read_b128 v[196:199], v0 offset:20480
	ds_read_b128 v[200:203], v0 offset:21504
	ds_read_b128 v[232:235], v0 offset:22528
	ds_read_b128 v[236:239], v0 offset:23552
	global_load_lds_dwordx4 v[218:219], off
	v_lshl_add_u64 v[218:219], v[216:217], 0, s[74:75]
	s_mov_b32 m0, s1
	s_nop 0
	global_load_lds_dwordx4 v[218:219], off
	s_barrier
	s_waitcnt lgkmcnt(0)
	s_setprio 1
	s_waitcnt lgkmcnt(0)
	v_mfma_f32_16x16x32_bf16 v[62:65], v[164:167], v[180:183], v[62:65]
	v_mfma_f32_16x16x32_bf16 v[58:61], v[172:175], v[180:183], v[58:61]
	v_mfma_f32_16x16x32_bf16 v[54:57], v[164:167], v[188:191], v[54:57]
	v_mfma_f32_16x16x32_bf16 v[50:53], v[172:175], v[188:191], v[50:53]
	v_mfma_f32_16x16x32_bf16 v[46:49], v[164:167], v[196:199], v[46:49]
	v_mfma_f32_16x16x32_bf16 v[42:45], v[172:175], v[196:199], v[42:45]
	v_mfma_f32_16x16x32_bf16 v[38:41], v[164:167], v[232:235], v[38:41]
	v_mfma_f32_16x16x32_bf16 v[34:37], v[172:175], v[232:235], v[34:37]
	v_mfma_f32_16x16x32_bf16 v[62:65], v[168:171], v[184:187], v[62:65]
	v_mfma_f32_16x16x32_bf16 v[58:61], v[176:179], v[184:187], v[58:61]
	v_mfma_f32_16x16x32_bf16 v[54:57], v[168:171], v[192:195], v[54:57]
	v_mfma_f32_16x16x32_bf16 v[50:53], v[176:179], v[192:195], v[50:53]
	v_mfma_f32_16x16x32_bf16 v[46:49], v[168:171], v[200:203], v[46:49]
	v_mfma_f32_16x16x32_bf16 v[42:45], v[176:179], v[200:203], v[42:45]
	v_mfma_f32_16x16x32_bf16 v[38:41], v[168:171], v[236:239], v[38:41]
	v_mfma_f32_16x16x32_bf16 v[34:37], v[176:179], v[236:239], v[34:37]
	s_setprio 0
	s_barrier
	v_readfirstlane_b32 s1, v152
	v_lshl_add_u64 v[164:165], v[210:211], 0, s[18:19]
	s_mov_b32 m0, s1
	v_readfirstlane_b32 s1, v153
	global_load_lds_dwordx4 v[164:165], off
	v_lshl_add_u64 v[164:165], v[228:229], 0, s[18:19]
	s_mov_b32 m0, s1
	s_nop 0
	global_load_lds_dwordx4 v[164:165], off
	s_waitcnt vmcnt(10)
	s_barrier
	s_setprio 1
	v_mfma_f32_16x16x32_bf16 v[30:33], v[240:243], v[180:183], v[30:33]
	v_mfma_f32_16x16x32_bf16 v[26:29], v[248:251], v[180:183], v[26:29]
	v_mfma_f32_16x16x32_bf16 v[22:25], v[240:243], v[188:191], v[22:25]
	v_mfma_f32_16x16x32_bf16 v[18:21], v[248:251], v[188:191], v[18:21]
	v_mfma_f32_16x16x32_bf16 v[14:17], v[240:243], v[196:199], v[14:17]
	v_mfma_f32_16x16x32_bf16 v[10:13], v[248:251], v[196:199], v[10:13]
	v_mfma_f32_16x16x32_bf16 v[6:9], v[240:243], v[232:235], v[6:9]
	v_mfma_f32_16x16x32_bf16 v[2:5], v[248:251], v[232:235], v[2:5]
	v_mfma_f32_16x16x32_bf16 v[30:33], v[244:247], v[184:187], v[30:33]
	v_mfma_f32_16x16x32_bf16 v[26:29], v[222:225], v[184:187], v[26:29]
	v_mfma_f32_16x16x32_bf16 v[22:25], v[244:247], v[192:195], v[22:25]
	v_mfma_f32_16x16x32_bf16 v[18:21], v[222:225], v[192:195], v[18:21]
	v_mfma_f32_16x16x32_bf16 v[14:17], v[244:247], v[200:203], v[14:17]
	v_mfma_f32_16x16x32_bf16 v[10:13], v[222:225], v[200:203], v[10:13]
	v_mfma_f32_16x16x32_bf16 v[6:9], v[244:247], v[236:239], v[6:9]
	v_mfma_f32_16x16x32_bf16 v[2:5], v[222:225], v[236:239], v[2:5]
	s_setprio 0
	s_barrier
	ds_read_b128 v[164:167], v151 offset:32768
	ds_read_b128 v[168:171], v151 offset:33792
	ds_read_b128 v[172:175], v151 offset:34816
	ds_read_b128 v[176:179], v151 offset:35840
	v_readfirstlane_b32 s1, v154
	v_lshl_add_u64 v[218:219], v[204:205], 0, s[18:19]
	s_mov_b32 m0, s1
	v_readfirstlane_b32 s1, v155
	ds_read_b128 v[180:183], v0 offset:32768
	ds_read_b128 v[184:187], v0 offset:33792
	ds_read_b128 v[188:191], v0 offset:34816
	ds_read_b128 v[192:195], v0 offset:35840
	ds_read_b128 v[196:199], v0 offset:36864
	ds_read_b128 v[200:203], v0 offset:37888
	ds_read_b128 v[222:225], v0 offset:38912
	ds_read_b128 v[232:235], v0 offset:39936
	global_load_lds_dwordx4 v[218:219], off
	v_lshl_add_u64 v[218:219], v[216:217], 0, s[18:19]
	s_mov_b32 m0, s1
	s_nop 0
	global_load_lds_dwordx4 v[218:219], off
	s_waitcnt lgkmcnt(8)
	s_waitcnt vmcnt(10)
	s_barrier
	s_waitcnt lgkmcnt(0)
	s_setprio 1
	s_waitcnt lgkmcnt(0)
	v_mfma_f32_16x16x32_bf16 v[126:129], v[164:167], v[180:183], v[126:129]
	v_mfma_f32_16x16x32_bf16 v[122:125], v[172:175], v[180:183], v[122:125]
	v_mfma_f32_16x16x32_bf16 v[118:121], v[164:167], v[188:191], v[118:121]
	v_mfma_f32_16x16x32_bf16 v[114:117], v[172:175], v[188:191], v[114:117]
	v_mfma_f32_16x16x32_bf16 v[110:113], v[164:167], v[196:199], v[110:113]
	v_mfma_f32_16x16x32_bf16 v[106:109], v[172:175], v[196:199], v[106:109]
	v_mfma_f32_16x16x32_bf16 v[102:105], v[164:167], v[222:225], v[102:105]
	v_mfma_f32_16x16x32_bf16 v[98:101], v[172:175], v[222:225], v[98:101]
	v_mfma_f32_16x16x32_bf16 v[126:129], v[168:171], v[184:187], v[126:129]
	v_mfma_f32_16x16x32_bf16 v[122:125], v[176:179], v[184:187], v[122:125]
	v_mfma_f32_16x16x32_bf16 v[118:121], v[168:171], v[192:195], v[118:121]
	v_mfma_f32_16x16x32_bf16 v[114:117], v[176:179], v[192:195], v[114:117]
	v_mfma_f32_16x16x32_bf16 v[110:113], v[168:171], v[200:203], v[110:113]
	v_mfma_f32_16x16x32_bf16 v[106:109], v[176:179], v[200:203], v[106:109]
	v_mfma_f32_16x16x32_bf16 v[102:105], v[168:171], v[232:235], v[102:105]
	v_mfma_f32_16x16x32_bf16 v[98:101], v[176:179], v[232:235], v[98:101]
	s_setprio 0
	s_barrier
	v_readfirstlane_b32 s1, v156
	v_lshl_add_u64 v[218:219], v[210:211], 0, s[28:29]
	s_mov_b32 m0, s1
	v_readfirstlane_b32 s1, v157
	ds_read_b128 v[236:239], v151 offset:49152
	ds_read_b128 v[240:243], v151 offset:50176
	ds_read_b128 v[244:247], v151 offset:51200
	ds_read_b128 v[248:251], v151 offset:52224
	global_load_lds_dwordx4 v[218:219], off
	v_lshl_add_u64 v[218:219], v[228:229], 0, s[28:29]
	s_mov_b32 m0, s1
	s_nop 0
	global_load_lds_dwordx4 v[218:219], off
	s_waitcnt vmcnt(10)
	s_barrier
	s_waitcnt lgkmcnt(0)
	s_setprio 1
	s_waitcnt lgkmcnt(0)
	v_mfma_f32_16x16x32_bf16 v[94:97], v[236:239], v[180:183], v[94:97]
	v_mfma_f32_16x16x32_bf16 v[90:93], v[244:247], v[180:183], v[90:93]
	v_mfma_f32_16x16x32_bf16 v[86:89], v[236:239], v[188:191], v[86:89]
	v_mfma_f32_16x16x32_bf16 v[82:85], v[244:247], v[188:191], v[82:85]
	v_mfma_f32_16x16x32_bf16 v[78:81], v[236:239], v[196:199], v[78:81]
	v_mfma_f32_16x16x32_bf16 v[74:77], v[244:247], v[196:199], v[74:77]
	v_mfma_f32_16x16x32_bf16 v[70:73], v[236:239], v[222:225], v[70:73]
	v_mfma_f32_16x16x32_bf16 v[66:69], v[244:247], v[222:225], v[66:69]
	v_mfma_f32_16x16x32_bf16 v[94:97], v[240:243], v[184:187], v[94:97]
	v_mfma_f32_16x16x32_bf16 v[90:93], v[248:251], v[184:187], v[90:93]
	v_mfma_f32_16x16x32_bf16 v[86:89], v[240:243], v[192:195], v[86:89]
	v_mfma_f32_16x16x32_bf16 v[82:85], v[248:251], v[192:195], v[82:85]
	v_mfma_f32_16x16x32_bf16 v[78:81], v[240:243], v[200:203], v[78:81]
	v_mfma_f32_16x16x32_bf16 v[74:77], v[248:251], v[200:203], v[74:77]
	v_mfma_f32_16x16x32_bf16 v[70:73], v[240:243], v[232:235], v[70:73]
	v_mfma_f32_16x16x32_bf16 v[66:69], v[248:251], v[232:235], v[66:69]
	s_setprio 0
	v_readfirstlane_b32 s1, v158
	v_lshl_add_u64 v[204:205], v[204:205], 0, s[28:29]
	s_mov_b32 m0, s1
	v_readfirstlane_b32 s1, v159
	s_barrier
	ds_read_b128 v[180:183], v0 offset:49152
	ds_read_b128 v[184:187], v0 offset:50176
	ds_read_b128 v[188:191], v0 offset:51200
	ds_read_b128 v[192:195], v0 offset:52224
	ds_read_b128 v[196:199], v0 offset:53248
	ds_read_b128 v[200:203], v0 offset:54272
	ds_read_b128 v[222:225], v0 offset:55296
	ds_read_b128 v[232:235], v0 offset:56320
	global_load_lds_dwordx4 v[204:205], off
	v_lshl_add_u64 v[204:205], v[216:217], 0, s[28:29]
	s_mov_b32 m0, s1
	s_nop 0
	global_load_lds_dwordx4 v[204:205], off
	s_barrier
	s_waitcnt lgkmcnt(0)
	s_setprio 1
	s_waitcnt lgkmcnt(0)
	v_mfma_f32_16x16x32_bf16 v[62:65], v[164:167], v[180:183], v[62:65]
	v_mfma_f32_16x16x32_bf16 v[58:61], v[172:175], v[180:183], v[58:61]
	v_mfma_f32_16x16x32_bf16 v[54:57], v[164:167], v[188:191], v[54:57]
	v_mfma_f32_16x16x32_bf16 v[50:53], v[172:175], v[188:191], v[50:53]
	v_mfma_f32_16x16x32_bf16 v[46:49], v[164:167], v[196:199], v[46:49]
	v_mfma_f32_16x16x32_bf16 v[42:45], v[172:175], v[196:199], v[42:45]
	v_mfma_f32_16x16x32_bf16 v[38:41], v[164:167], v[222:225], v[38:41]
	v_mfma_f32_16x16x32_bf16 v[34:37], v[172:175], v[222:225], v[34:37]
	v_mfma_f32_16x16x32_bf16 v[62:65], v[168:171], v[184:187], v[62:65]
	v_mfma_f32_16x16x32_bf16 v[58:61], v[176:179], v[184:187], v[58:61]
	v_mfma_f32_16x16x32_bf16 v[54:57], v[168:171], v[192:195], v[54:57]
	v_mfma_f32_16x16x32_bf16 v[50:53], v[176:179], v[192:195], v[50:53]
	v_mfma_f32_16x16x32_bf16 v[46:49], v[168:171], v[200:203], v[46:49]
	v_mfma_f32_16x16x32_bf16 v[42:45], v[176:179], v[200:203], v[42:45]
	v_mfma_f32_16x16x32_bf16 v[38:41], v[168:171], v[232:235], v[38:41]
	v_mfma_f32_16x16x32_bf16 v[34:37], v[176:179], v[232:235], v[34:37]
	s_setprio 0
	s_barrier
	v_readfirstlane_b32 s1, v160
	v_lshl_add_u64 v[164:165], v[210:211], 0, s[30:31]
	s_mov_b32 m0, s1
	v_readfirstlane_b32 s1, v161
	global_load_lds_dwordx4 v[164:165], off
	v_lshl_add_u64 v[164:165], v[228:229], 0, s[30:31]
	s_mov_b32 m0, s1
	s_nop 0
	global_load_lds_dwordx4 v[164:165], off
	s_waitcnt vmcnt(10)
	s_barrier
	s_setprio 1
	v_mfma_f32_16x16x32_bf16 v[30:33], v[236:239], v[180:183], v[30:33]
	v_mfma_f32_16x16x32_bf16 v[26:29], v[244:247], v[180:183], v[26:29]
	v_mfma_f32_16x16x32_bf16 v[22:25], v[236:239], v[188:191], v[22:25]
	v_mfma_f32_16x16x32_bf16 v[18:21], v[244:247], v[188:191], v[18:21]
	v_mfma_f32_16x16x32_bf16 v[14:17], v[236:239], v[196:199], v[14:17]
	v_mfma_f32_16x16x32_bf16 v[10:13], v[244:247], v[196:199], v[10:13]
	v_mfma_f32_16x16x32_bf16 v[6:9], v[236:239], v[222:225], v[6:9]
	v_mfma_f32_16x16x32_bf16 v[2:5], v[244:247], v[222:225], v[2:5]
	v_mfma_f32_16x16x32_bf16 v[30:33], v[240:243], v[184:187], v[30:33]
	v_mfma_f32_16x16x32_bf16 v[26:29], v[248:251], v[184:187], v[26:29]
	v_mfma_f32_16x16x32_bf16 v[22:25], v[240:243], v[192:195], v[22:25]
	v_mfma_f32_16x16x32_bf16 v[18:21], v[248:251], v[192:195], v[18:21]
	v_mfma_f32_16x16x32_bf16 v[14:17], v[240:243], v[200:203], v[14:17]
	v_mfma_f32_16x16x32_bf16 v[10:13], v[248:251], v[200:203], v[10:13]
	v_mfma_f32_16x16x32_bf16 v[6:9], v[240:243], v[232:235], v[6:9]
	v_mfma_f32_16x16x32_bf16 v[2:5], v[248:251], v[232:235], v[2:5]
	s_setprio 0
	s_add_i32 s0, s0, 2
	s_add_u32 s8, s8, 0x100
	s_addc_u32 s9, s9, 0
	s_cmp_lt_u32 s0, 28
	s_barrier
	s_cbranch_scc1 .LBB0_678
	s_mov_b64 s[8:9], 0xf80
	v_readfirstlane_b32 s0, v162
	v_lshl_add_u64 v[132:133], v[132:133], 0, s[8:9]
	s_mov_b32 m0, s0
	v_readfirstlane_b32 s0, v163
	ds_read_b128 v[134:137], v151
	ds_read_b128 v[138:141], v151 offset:1024
	ds_read_b128 v[152:155], v151 offset:2048
	ds_read_b128 v[156:159], v151 offset:3072
	ds_read_b128 v[164:167], v0
	ds_read_b128 v[168:171], v0 offset:1024
	ds_read_b128 v[172:175], v0 offset:2048
	ds_read_b128 v[176:179], v0 offset:3072
	ds_read_b128 v[180:183], v0 offset:4096
	ds_read_b128 v[184:187], v0 offset:5120
	ds_read_b128 v[188:191], v0 offset:6144
	ds_read_b128 v[192:195], v0 offset:7168
	global_load_lds_dwordx4 v[132:133], off
	v_lshl_add_u64 v[130:131], v[130:131], 0, s[8:9]
	s_mov_b32 m0, s0
	s_nop 0
	global_load_lds_dwordx4 v[130:131], off
	s_barrier
	s_waitcnt lgkmcnt(0)
	s_setprio 1
	s_waitcnt lgkmcnt(0)
	v_mfma_f32_16x16x32_bf16 v[126:129], v[134:137], v[164:167], v[126:129]
	v_mfma_f32_16x16x32_bf16 v[122:125], v[152:155], v[164:167], v[122:125]
	v_mfma_f32_16x16x32_bf16 v[114:117], v[152:155], v[172:175], v[114:117]
	v_mfma_f32_16x16x32_bf16 v[106:109], v[152:155], v[180:183], v[106:109]
	v_mfma_f32_16x16x32_bf16 v[98:101], v[152:155], v[188:191], v[98:101]
	v_mfma_f32_16x16x32_bf16 v[126:129], v[138:141], v[168:171], v[126:129]
	v_mfma_f32_16x16x32_bf16 v[122:125], v[156:159], v[168:171], v[122:125]
	v_mfma_f32_16x16x32_bf16 v[118:121], v[134:137], v[172:175], v[118:121]
	v_mfma_f32_16x16x32_bf16 v[114:117], v[156:159], v[176:179], v[114:117]
	v_mfma_f32_16x16x32_bf16 v[110:113], v[134:137], v[180:183], v[110:113]
	v_mfma_f32_16x16x32_bf16 v[106:109], v[156:159], v[184:187], v[106:109]
	v_mfma_f32_16x16x32_bf16 v[102:105], v[134:137], v[188:191], v[102:105]
	v_mfma_f32_16x16x32_bf16 v[98:101], v[156:159], v[192:195], v[98:101]
	v_mfma_f32_16x16x32_bf16 v[130:133], v[138:141], v[176:179], v[118:121]
	v_mfma_f32_16x16x32_bf16 v[160:163], v[138:141], v[184:187], v[110:113]
	v_mfma_f32_16x16x32_bf16 v[196:199], v[138:141], v[192:195], v[102:105]
	s_setprio 0
	s_barrier
	s_nop 0
	ds_read_b128 v[102:105], v151 offset:16384
	ds_read_b128 v[110:113], v151 offset:17408
	ds_read_b128 v[118:121], v151 offset:18432
	ds_read_b128 v[200:203], v151 offset:19456
	s_barrier
	s_waitcnt lgkmcnt(0)
	s_setprio 1
	s_waitcnt lgkmcnt(1)
	v_mfma_f32_16x16x32_bf16 v[90:93], v[118:121], v[164:167], v[90:93]
	v_mfma_f32_16x16x32_bf16 v[86:89], v[102:105], v[172:175], v[86:89]
	v_mfma_f32_16x16x32_bf16 v[82:85], v[118:121], v[172:175], v[82:85]
	v_mfma_f32_16x16x32_bf16 v[78:81], v[102:105], v[180:183], v[78:81]
	v_mfma_f32_16x16x32_bf16 v[70:73], v[102:105], v[188:191], v[70:73]
	v_mfma_f32_16x16x32_bf16 v[94:97], v[102:105], v[164:167], v[94:97]
	s_waitcnt lgkmcnt(0)
	v_mfma_f32_16x16x32_bf16 v[90:93], v[200:203], v[168:171], v[90:93]
	v_mfma_f32_16x16x32_bf16 v[86:89], v[110:113], v[176:179], v[86:89]
	v_mfma_f32_16x16x32_bf16 v[82:85], v[200:203], v[176:179], v[82:85]
	v_mfma_f32_16x16x32_bf16 v[78:81], v[110:113], v[184:187], v[78:81]
	v_mfma_f32_16x16x32_bf16 v[74:77], v[118:121], v[180:183], v[74:77]
	v_mfma_f32_16x16x32_bf16 v[70:73], v[110:113], v[192:195], v[70:73]
	v_mfma_f32_16x16x32_bf16 v[66:69], v[118:121], v[188:191], v[66:69]
	v_mfma_f32_16x16x32_bf16 v[222:225], v[110:113], v[168:171], v[94:97]
	v_mfma_f32_16x16x32_bf16 v[164:167], v[200:203], v[184:187], v[74:77]
	v_mfma_f32_16x16x32_bf16 v[168:171], v[200:203], v[192:195], v[66:69]
	s_setprio 0
	s_barrier
	s_nop 2
	ds_read_b128 v[66:69], v0 offset:16384
	ds_read_b128 v[74:77], v0 offset:17408
	ds_read_b128 v[94:97], v0 offset:18432
	ds_read_b128 v[172:175], v0 offset:19456
	ds_read_b128 v[176:179], v0 offset:20480
	ds_read_b128 v[180:183], v0 offset:21504
	ds_read_b128 v[184:187], v0 offset:22528
	ds_read_b128 v[188:191], v0 offset:23552
	s_waitcnt vmcnt(4)
	s_barrier
	s_waitcnt lgkmcnt(0)
	s_setprio 1
	s_waitcnt lgkmcnt(5)
	v_mfma_f32_16x16x32_bf16 v[54:57], v[134:137], v[94:97], v[54:57]
	v_mfma_f32_16x16x32_bf16 v[50:53], v[152:155], v[94:97], v[50:53]
	v_mfma_f32_16x16x32_bf16 v[62:65], v[134:137], v[66:69], v[62:65]
	v_mfma_f32_16x16x32_bf16 v[58:61], v[152:155], v[66:69], v[58:61]
	s_waitcnt lgkmcnt(4)
	v_mfma_f32_16x16x32_bf16 v[54:57], v[138:141], v[172:175], v[54:57]
	v_mfma_f32_16x16x32_bf16 v[50:53], v[156:159], v[172:175], v[50:53]
	s_waitcnt lgkmcnt(3)
	v_mfma_f32_16x16x32_bf16 v[46:49], v[134:137], v[176:179], v[46:49]
	v_mfma_f32_16x16x32_bf16 v[42:45], v[152:155], v[176:179], v[42:45]
	s_waitcnt lgkmcnt(1)
	v_mfma_f32_16x16x32_bf16 v[38:41], v[134:137], v[184:187], v[38:41]
	v_mfma_f32_16x16x32_bf16 v[34:37], v[152:155], v[184:187], v[34:37]
	v_mfma_f32_16x16x32_bf16 v[192:195], v[138:141], v[74:77], v[62:65]
	v_mfma_f32_16x16x32_bf16 v[232:235], v[156:159], v[74:77], v[58:61]
	v_mfma_f32_16x16x32_bf16 v[236:239], v[138:141], v[180:183], v[46:49]
	v_mfma_f32_16x16x32_bf16 v[240:243], v[156:159], v[180:183], v[42:45]
	s_waitcnt lgkmcnt(0)
	v_mfma_f32_16x16x32_bf16 v[134:137], v[138:141], v[188:191], v[38:41]
	v_mfma_f32_16x16x32_bf16 v[138:141], v[156:159], v[188:191], v[34:37]
	s_setprio 0
	s_setprio 1
	v_mfma_f32_16x16x32_bf16 v[30:33], v[102:105], v[66:69], v[30:33]
	v_mfma_f32_16x16x32_bf16 v[26:29], v[118:121], v[66:69], v[26:29]
	v_mfma_f32_16x16x32_bf16 v[14:17], v[102:105], v[176:179], v[14:17]
	v_mfma_f32_16x16x32_bf16 v[10:13], v[118:121], v[176:179], v[10:13]
	v_mfma_f32_16x16x32_bf16 v[30:33], v[110:113], v[74:77], v[30:33]
	v_mfma_f32_16x16x32_bf16 v[26:29], v[200:203], v[74:77], v[26:29]
	v_mfma_f32_16x16x32_bf16 v[22:25], v[102:105], v[94:97], v[22:25]
	v_mfma_f32_16x16x32_bf16 v[18:21], v[118:121], v[94:97], v[18:21]
	v_mfma_f32_16x16x32_bf16 v[14:17], v[110:113], v[180:183], v[14:17]
	v_mfma_f32_16x16x32_bf16 v[10:13], v[200:203], v[180:183], v[10:13]
	v_mfma_f32_16x16x32_bf16 v[6:9], v[102:105], v[184:187], v[6:9]
	v_mfma_f32_16x16x32_bf16 v[2:5], v[118:121], v[184:187], v[2:5]
	v_mfma_f32_16x16x32_bf16 v[152:155], v[110:113], v[172:175], v[22:25]
	v_mfma_f32_16x16x32_bf16 v[156:159], v[200:203], v[172:175], v[18:21]
	v_mfma_f32_16x16x32_bf16 v[172:175], v[110:113], v[188:191], v[6:9]
	v_mfma_f32_16x16x32_bf16 v[176:179], v[200:203], v[188:191], v[2:5]
	s_setprio 0
	s_barrier
	s_nop 1
	ds_read_b128 v[2:5], v151 offset:32768
	ds_read_b128 v[6:9], v151 offset:33792
	ds_read_b128 v[180:183], v151 offset:34816
	ds_read_b128 v[184:187], v151 offset:35840
	ds_read_b128 v[18:21], v0 offset:32768
	ds_read_b128 v[22:25], v0 offset:33792
	ds_read_b128 v[38:41], v0 offset:34816
	ds_read_b128 v[46:49], v0 offset:35840
	ds_read_b128 v[58:61], v0 offset:36864
	ds_read_b128 v[66:69], v0 offset:37888
	ds_read_b128 v[188:191], v0 offset:38912
	ds_read_b128 v[200:203], v0 offset:39936
	s_waitcnt vmcnt(2)
	s_barrier
	s_waitcnt lgkmcnt(0)
	s_setprio 1
	s_waitcnt lgkmcnt(7)
	v_mfma_f32_16x16x32_bf16 v[34:37], v[2:5], v[18:21], v[126:129]
	s_waitcnt lgkmcnt(6)
	v_mfma_f32_16x16x32_bf16 v[118:121], v[6:9], v[22:25], v[34:37]
	v_mfma_f32_16x16x32_bf16 v[34:37], v[180:183], v[18:21], v[122:125]
	v_mfma_f32_16x16x32_bf16 v[110:113], v[184:187], v[22:25], v[34:37]
	s_waitcnt lgkmcnt(5)
	v_mfma_f32_16x16x32_bf16 v[34:37], v[2:5], v[38:41], v[130:133]
	s_waitcnt lgkmcnt(4)
	v_mfma_f32_16x16x32_bf16 v[102:105], v[6:9], v[46:49], v[34:37]
	v_mfma_f32_16x16x32_bf16 v[34:37], v[180:183], v[38:41], v[114:117]
	v_mfma_f32_16x16x32_bf16 v[94:97], v[184:187], v[46:49], v[34:37]
	s_waitcnt lgkmcnt(3)
	v_mfma_f32_16x16x32_bf16 v[34:37], v[2:5], v[58:61], v[160:163]
	s_waitcnt lgkmcnt(2)
	v_mfma_f32_16x16x32_bf16 v[74:77], v[6:9], v[66:69], v[34:37]
	v_mfma_f32_16x16x32_bf16 v[34:37], v[180:183], v[58:61], v[106:109]
	v_mfma_f32_16x16x32_bf16 v[62:65], v[184:187], v[66:69], v[34:37]
	s_waitcnt lgkmcnt(1)
	v_mfma_f32_16x16x32_bf16 v[34:37], v[2:5], v[188:191], v[196:199]
	s_waitcnt lgkmcnt(0)
	v_mfma_f32_16x16x32_bf16 v[42:45], v[6:9], v[200:203], v[34:37]
	v_mfma_f32_16x16x32_bf16 v[34:37], v[180:183], v[188:191], v[98:101]
	v_mfma_f32_16x16x32_bf16 v[34:37], v[184:187], v[200:203], v[34:37]
	s_setprio 0
	s_barrier
	ds_read_b128 v[130:133], v151 offset:49152
	ds_read_b128 v[160:163], v151 offset:50176
	ds_read_b128 v[196:199], v151 offset:51200
	ds_read_b128 v[148:151], v151 offset:52224
	s_waitcnt vmcnt(0)
	s_barrier
	s_waitcnt lgkmcnt(0)
	s_setprio 1
	s_waitcnt lgkmcnt(3)
	v_mfma_f32_16x16x32_bf16 v[98:101], v[130:133], v[18:21], v[222:225]
	s_waitcnt lgkmcnt(1)
	v_mfma_f32_16x16x32_bf16 v[18:21], v[196:199], v[18:21], v[90:93]
	s_waitcnt lgkmcnt(0)
	v_mfma_f32_16x16x32_bf16 v[122:125], v[148:151], v[22:25], v[18:21]
	v_mfma_f32_16x16x32_bf16 v[18:21], v[130:133], v[38:41], v[86:89]
	v_mfma_f32_16x16x32_bf16 v[114:117], v[160:163], v[46:49], v[18:21]
	v_mfma_f32_16x16x32_bf16 v[18:21], v[196:199], v[38:41], v[82:85]
	v_mfma_f32_16x16x32_bf16 v[106:109], v[148:151], v[46:49], v[18:21]
	v_mfma_f32_16x16x32_bf16 v[18:21], v[130:133], v[58:61], v[78:81]
	v_mfma_f32_16x16x32_bf16 v[126:129], v[160:163], v[22:25], v[98:101]
	v_mfma_f32_16x16x32_bf16 v[98:101], v[160:163], v[66:69], v[18:21]
	v_mfma_f32_16x16x32_bf16 v[18:21], v[196:199], v[58:61], v[164:167]
	v_mfma_f32_16x16x32_bf16 v[90:93], v[148:151], v[66:69], v[18:21]
	v_mfma_f32_16x16x32_bf16 v[18:21], v[130:133], v[188:191], v[70:73]
	v_mfma_f32_16x16x32_bf16 v[66:69], v[160:163], v[200:203], v[18:21]
	v_mfma_f32_16x16x32_bf16 v[18:21], v[196:199], v[188:191], v[168:171]
	v_mfma_f32_16x16x32_bf16 v[58:61], v[148:151], v[200:203], v[18:21]
	s_setprio 0
	s_barrier
	ds_read_b128 v[82:85], v0 offset:49152
	ds_read_b128 v[164:167], v0 offset:50176
	ds_read_b128 v[168:171], v0 offset:51200
	ds_read_b128 v[188:191], v0 offset:52224
	ds_read_b128 v[200:203], v0 offset:53248
	ds_read_b128 v[222:225], v0 offset:54272
	ds_read_b128 v[244:247], v0 offset:55296
	ds_read_b128 v[248:251], v0 offset:56320
	s_barrier
	s_waitcnt lgkmcnt(0)
	s_setprio 1
	s_waitcnt lgkmcnt(7)
	v_mfma_f32_16x16x32_bf16 v[18:21], v[2:5], v[82:85], v[192:195]
	s_waitcnt lgkmcnt(6)
	v_mfma_f32_16x16x32_bf16 v[78:81], v[6:9], v[164:167], v[18:21]
	v_mfma_f32_16x16x32_bf16 v[18:21], v[180:183], v[82:85], v[232:235]
	v_mfma_f32_16x16x32_bf16 v[70:73], v[184:187], v[164:167], v[18:21]
	s_waitcnt lgkmcnt(5)
	v_mfma_f32_16x16x32_bf16 v[18:21], v[2:5], v[168:171], v[54:57]
	s_waitcnt lgkmcnt(4)
	v_mfma_f32_16x16x32_bf16 v[46:49], v[6:9], v[188:191], v[18:21]
	v_mfma_f32_16x16x32_bf16 v[18:21], v[180:183], v[168:171], v[50:53]
	v_mfma_f32_16x16x32_bf16 v[38:41], v[184:187], v[188:191], v[18:21]
	s_waitcnt lgkmcnt(3)
	v_mfma_f32_16x16x32_bf16 v[18:21], v[2:5], v[200:203], v[236:239]
	s_waitcnt lgkmcnt(1)
	v_mfma_f32_16x16x32_bf16 v[2:5], v[2:5], v[244:247], v[134:137]
	v_mfma_f32_16x16x32_bf16 v[22:25], v[6:9], v[222:225], v[18:21]
	v_mfma_f32_16x16x32_bf16 v[18:21], v[180:183], v[200:203], v[240:243]
	s_waitcnt lgkmcnt(0)
	v_mfma_f32_16x16x32_bf16 v[6:9], v[6:9], v[248:251], v[2:5]
	v_mfma_f32_16x16x32_bf16 v[2:5], v[180:183], v[244:247], v[138:141]
	v_mfma_f32_16x16x32_bf16 v[18:21], v[184:187], v[222:225], v[18:21]
	v_mfma_f32_16x16x32_bf16 v[2:5], v[184:187], v[248:251], v[2:5]
	s_setprio 0
	s_setprio 1
	v_mfma_f32_16x16x32_bf16 v[26:29], v[196:199], v[82:85], v[26:29]
	v_mfma_f32_16x16x32_bf16 v[30:33], v[130:133], v[82:85], v[30:33]
	v_mfma_f32_16x16x32_bf16 v[82:85], v[148:151], v[164:167], v[26:29]
	v_mfma_f32_16x16x32_bf16 v[26:29], v[130:133], v[168:171], v[152:155]
	v_mfma_f32_16x16x32_bf16 v[54:57], v[160:163], v[188:191], v[26:29]
	v_mfma_f32_16x16x32_bf16 v[26:29], v[196:199], v[168:171], v[156:159]
	v_mfma_f32_16x16x32_bf16 v[10:13], v[196:199], v[200:203], v[10:13]
	v_mfma_f32_16x16x32_bf16 v[50:53], v[148:151], v[188:191], v[26:29]
	v_mfma_f32_16x16x32_bf16 v[14:17], v[130:133], v[200:203], v[14:17]
	v_mfma_f32_16x16x32_bf16 v[26:29], v[148:151], v[222:225], v[10:13]
	v_mfma_f32_16x16x32_bf16 v[10:13], v[130:133], v[244:247], v[172:175]
	v_mfma_f32_16x16x32_bf16 v[86:89], v[160:163], v[164:167], v[30:33]
	v_mfma_f32_16x16x32_bf16 v[30:33], v[160:163], v[222:225], v[14:17]
	v_mfma_f32_16x16x32_bf16 v[14:17], v[160:163], v[248:251], v[10:13]
	v_mfma_f32_16x16x32_bf16 v[10:13], v[196:199], v[244:247], v[176:179]
	v_mfma_f32_16x16x32_bf16 v[10:13], v[148:151], v[248:251], v[10:13]
	s_setprio 0
	s_movk_i32 s0, 0x100
	v_cmp_gt_u32_e32 vcc, s0, v142
	s_barrier
	s_and_saveexec_b64 s[0:1], vcc
	s_cbranch_execz .LBB0_674
	s_barrier
	s_branch .LBB0_674

.LBB0_761:
	ds_read_b128 v[164:167], v148
	ds_read_b128 v[168:171], v148 offset:1024
	ds_read_b128 v[172:175], v148 offset:2048
	ds_read_b128 v[176:179], v148 offset:3072
	v_add_u32_e32 v161, 0xc000, v145
	v_lshl_add_u64 v[204:205], v[136:137], 0, s[10:11]
	v_readfirstlane_b32 s1, v161
	v_lshl_add_u64 v[162:163], v[204:205], 0, s[34:35]
	s_mov_b32 m0, s1
	ds_read_b128 v[180:183], v147
	ds_read_b128 v[184:187], v147 offset:1024
	ds_read_b128 v[188:191], v147 offset:2048
	ds_read_b128 v[192:195], v147 offset:3072
	ds_read_b128 v[196:199], v147 offset:4096
	ds_read_b128 v[200:203], v147 offset:5120
	ds_read_b128 v[222:225], v147 offset:6144
	ds_read_b128 v[232:235], v147 offset:7168
	global_load_lds_dwordx4 v[162:163], off
	v_add_u32_e32 v162, 0xe000, v145
	v_lshl_add_u64 v[210:211], v[138:139], 0, s[10:11]
	v_readfirstlane_b32 s1, v162
	v_lshl_add_u64 v[216:217], v[210:211], 0, s[34:35]
	s_mov_b32 m0, s1
	s_nop 0
	global_load_lds_dwordx4 v[216:217], off
	s_waitcnt lgkmcnt(8)
	s_waitcnt vmcnt(10)
	s_barrier
	s_waitcnt lgkmcnt(0)
	s_setprio 1
	s_waitcnt lgkmcnt(0)
	v_mfma_f32_16x16x32_bf16 v[126:129], v[164:167], v[180:183], v[126:129]
	v_mfma_f32_16x16x32_bf16 v[122:125], v[172:175], v[180:183], v[122:125]
	v_mfma_f32_16x16x32_bf16 v[118:121], v[164:167], v[188:191], v[118:121]
	v_mfma_f32_16x16x32_bf16 v[114:117], v[172:175], v[188:191], v[114:117]
	v_mfma_f32_16x16x32_bf16 v[110:113], v[164:167], v[196:199], v[110:113]
	v_mfma_f32_16x16x32_bf16 v[106:109], v[172:175], v[196:199], v[106:109]
	v_mfma_f32_16x16x32_bf16 v[102:105], v[164:167], v[222:225], v[102:105]
	v_mfma_f32_16x16x32_bf16 v[98:101], v[172:175], v[222:225], v[98:101]
	v_mfma_f32_16x16x32_bf16 v[126:129], v[168:171], v[184:187], v[126:129]
	v_mfma_f32_16x16x32_bf16 v[122:125], v[176:179], v[184:187], v[122:125]
	v_mfma_f32_16x16x32_bf16 v[118:121], v[168:171], v[192:195], v[118:121]
	v_mfma_f32_16x16x32_bf16 v[114:117], v[176:179], v[192:195], v[114:117]
	v_mfma_f32_16x16x32_bf16 v[110:113], v[168:171], v[200:203], v[110:113]
	v_mfma_f32_16x16x32_bf16 v[106:109], v[176:179], v[200:203], v[106:109]
	v_mfma_f32_16x16x32_bf16 v[102:105], v[168:171], v[232:235], v[102:105]
	v_mfma_f32_16x16x32_bf16 v[98:101], v[176:179], v[232:235], v[98:101]
	s_setprio 0
	s_barrier
	v_lshl_add_u64 v[216:217], v[132:133], 0, s[10:11]
	v_readfirstlane_b32 s1, v149
	v_lshl_add_u64 v[218:219], v[216:217], 0, s[74:75]
	s_mov_b32 m0, s1
	ds_read_b128 v[236:239], v148 offset:16384
	ds_read_b128 v[240:243], v148 offset:17408
	ds_read_b128 v[244:247], v148 offset:18432
	ds_read_b128 v[248:251], v148 offset:19456
	global_load_lds_dwordx4 v[218:219], off
	v_lshl_add_u64 v[218:219], v[134:135], 0, s[10:11]
	v_readfirstlane_b32 s1, v150
	v_lshl_add_u64 v[228:229], v[218:219], 0, s[74:75]
	s_mov_b32 m0, s1
	s_nop 0
	global_load_lds_dwordx4 v[228:229], off
	s_waitcnt vmcnt(10)
	s_barrier
	s_waitcnt lgkmcnt(0)
	s_setprio 1
	s_waitcnt lgkmcnt(0)
	v_mfma_f32_16x16x32_bf16 v[94:97], v[236:239], v[180:183], v[94:97]
	v_mfma_f32_16x16x32_bf16 v[90:93], v[244:247], v[180:183], v[90:93]
	v_mfma_f32_16x16x32_bf16 v[86:89], v[236:239], v[188:191], v[86:89]
	v_mfma_f32_16x16x32_bf16 v[82:85], v[244:247], v[188:191], v[82:85]
	v_mfma_f32_16x16x32_bf16 v[78:81], v[236:239], v[196:199], v[78:81]
	v_mfma_f32_16x16x32_bf16 v[74:77], v[244:247], v[196:199], v[74:77]
	v_mfma_f32_16x16x32_bf16 v[70:73], v[236:239], v[222:225], v[70:73]
	v_mfma_f32_16x16x32_bf16 v[66:69], v[244:247], v[222:225], v[66:69]
	v_mfma_f32_16x16x32_bf16 v[94:97], v[240:243], v[184:187], v[94:97]
	v_mfma_f32_16x16x32_bf16 v[90:93], v[248:251], v[184:187], v[90:93]
	v_mfma_f32_16x16x32_bf16 v[86:89], v[240:243], v[192:195], v[86:89]
	v_mfma_f32_16x16x32_bf16 v[82:85], v[248:251], v[192:195], v[82:85]
	v_mfma_f32_16x16x32_bf16 v[78:81], v[240:243], v[200:203], v[78:81]
	v_mfma_f32_16x16x32_bf16 v[74:77], v[248:251], v[200:203], v[74:77]
	v_mfma_f32_16x16x32_bf16 v[70:73], v[240:243], v[232:235], v[70:73]
	v_mfma_f32_16x16x32_bf16 v[66:69], v[248:251], v[232:235], v[66:69]
	s_setprio 0
	v_readfirstlane_b32 s1, v145
	v_lshl_add_u64 v[228:229], v[204:205], 0, s[74:75]
	s_mov_b32 m0, s1
	v_readfirstlane_b32 s1, v146
	s_barrier
	ds_read_b128 v[180:183], v147 offset:16384
	ds_read_b128 v[184:187], v147 offset:17408
	ds_read_b128 v[188:191], v147 offset:18432
	ds_read_b128 v[192:195], v147 offset:19456
	ds_read_b128 v[196:199], v147 offset:20480
	ds_read_b128 v[200:203], v147 offset:21504
	ds_read_b128 v[222:225], v147 offset:22528
	ds_read_b128 v[232:235], v147 offset:23552
	global_load_lds_dwordx4 v[228:229], off
	v_lshl_add_u64 v[228:229], v[210:211], 0, s[74:75]
	s_mov_b32 m0, s1
	s_nop 0
	global_load_lds_dwordx4 v[228:229], off
	s_barrier
	s_waitcnt lgkmcnt(0)
	s_setprio 1
	s_waitcnt lgkmcnt(0)
	v_mfma_f32_16x16x32_bf16 v[62:65], v[164:167], v[180:183], v[62:65]
	v_mfma_f32_16x16x32_bf16 v[58:61], v[172:175], v[180:183], v[58:61]
	v_mfma_f32_16x16x32_bf16 v[54:57], v[164:167], v[188:191], v[54:57]
	v_mfma_f32_16x16x32_bf16 v[50:53], v[172:175], v[188:191], v[50:53]
	v_mfma_f32_16x16x32_bf16 v[46:49], v[164:167], v[196:199], v[46:49]
	v_mfma_f32_16x16x32_bf16 v[42:45], v[172:175], v[196:199], v[42:45]
	v_mfma_f32_16x16x32_bf16 v[38:41], v[164:167], v[222:225], v[38:41]
	v_mfma_f32_16x16x32_bf16 v[34:37], v[172:175], v[222:225], v[34:37]
	v_mfma_f32_16x16x32_bf16 v[62:65], v[168:171], v[184:187], v[62:65]
	v_mfma_f32_16x16x32_bf16 v[58:61], v[176:179], v[184:187], v[58:61]
	v_mfma_f32_16x16x32_bf16 v[54:57], v[168:171], v[192:195], v[54:57]
	v_mfma_f32_16x16x32_bf16 v[50:53], v[176:179], v[192:195], v[50:53]
	v_mfma_f32_16x16x32_bf16 v[46:49], v[168:171], v[200:203], v[46:49]
	v_mfma_f32_16x16x32_bf16 v[42:45], v[176:179], v[200:203], v[42:45]
	v_mfma_f32_16x16x32_bf16 v[38:41], v[168:171], v[232:235], v[38:41]
	v_mfma_f32_16x16x32_bf16 v[34:37], v[176:179], v[232:235], v[34:37]
	s_setprio 0
	s_barrier
	v_readfirstlane_b32 s1, v151
	v_lshl_add_u64 v[164:165], v[216:217], 0, s[78:79]
	s_mov_b32 m0, s1
	v_readfirstlane_b32 s1, v152
	global_load_lds_dwordx4 v[164:165], off
	v_lshl_add_u64 v[164:165], v[218:219], 0, s[78:79]
	s_mov_b32 m0, s1
	s_nop 0
	global_load_lds_dwordx4 v[164:165], off
	s_waitcnt vmcnt(10)
	s_barrier
	s_setprio 1
	v_mfma_f32_16x16x32_bf16 v[30:33], v[236:239], v[180:183], v[30:33]
	v_mfma_f32_16x16x32_bf16 v[26:29], v[244:247], v[180:183], v[26:29]
	v_mfma_f32_16x16x32_bf16 v[22:25], v[236:239], v[188:191], v[22:25]
	v_mfma_f32_16x16x32_bf16 v[18:21], v[244:247], v[188:191], v[18:21]
	v_mfma_f32_16x16x32_bf16 v[14:17], v[236:239], v[196:199], v[14:17]
	v_mfma_f32_16x16x32_bf16 v[10:13], v[244:247], v[196:199], v[10:13]
	v_mfma_f32_16x16x32_bf16 v[6:9], v[236:239], v[222:225], v[6:9]
	v_mfma_f32_16x16x32_bf16 v[2:5], v[244:247], v[222:225], v[2:5]
	v_mfma_f32_16x16x32_bf16 v[30:33], v[240:243], v[184:187], v[30:33]
	v_mfma_f32_16x16x32_bf16 v[26:29], v[248:251], v[184:187], v[26:29]
	v_mfma_f32_16x16x32_bf16 v[22:25], v[240:243], v[192:195], v[22:25]
	v_mfma_f32_16x16x32_bf16 v[18:21], v[248:251], v[192:195], v[18:21]
	v_mfma_f32_16x16x32_bf16 v[14:17], v[240:243], v[200:203], v[14:17]
	v_mfma_f32_16x16x32_bf16 v[10:13], v[248:251], v[200:203], v[10:13]
	v_mfma_f32_16x16x32_bf16 v[6:9], v[240:243], v[232:235], v[6:9]
	v_mfma_f32_16x16x32_bf16 v[2:5], v[248:251], v[232:235], v[2:5]
	s_setprio 0
	s_barrier
	ds_read_b128 v[164:167], v148 offset:32768
	ds_read_b128 v[168:171], v148 offset:33792
	ds_read_b128 v[172:175], v148 offset:34816
	ds_read_b128 v[176:179], v148 offset:35840
	v_readfirstlane_b32 s1, v153
	v_lshl_add_u64 v[228:229], v[204:205], 0, s[78:79]
	s_mov_b32 m0, s1
	v_readfirstlane_b32 s1, v154
	ds_read_b128 v[180:183], v147 offset:32768
	ds_read_b128 v[184:187], v147 offset:33792
	ds_read_b128 v[188:191], v147 offset:34816
	ds_read_b128 v[192:195], v147 offset:35840
	ds_read_b128 v[196:199], v147 offset:36864
	ds_read_b128 v[200:203], v147 offset:37888
	ds_read_b128 v[222:225], v147 offset:38912
	ds_read_b128 v[232:235], v147 offset:39936
	global_load_lds_dwordx4 v[228:229], off
	v_lshl_add_u64 v[228:229], v[210:211], 0, s[78:79]
	s_mov_b32 m0, s1
	s_nop 0
	global_load_lds_dwordx4 v[228:229], off
	s_waitcnt lgkmcnt(8)
	s_waitcnt vmcnt(10)
	s_barrier
	s_waitcnt lgkmcnt(0)
	s_setprio 1
	s_waitcnt lgkmcnt(0)
	v_mfma_f32_16x16x32_bf16 v[126:129], v[164:167], v[180:183], v[126:129]
	v_mfma_f32_16x16x32_bf16 v[122:125], v[172:175], v[180:183], v[122:125]
	v_mfma_f32_16x16x32_bf16 v[118:121], v[164:167], v[188:191], v[118:121]
	v_mfma_f32_16x16x32_bf16 v[114:117], v[172:175], v[188:191], v[114:117]
	v_mfma_f32_16x16x32_bf16 v[110:113], v[164:167], v[196:199], v[110:113]
	v_mfma_f32_16x16x32_bf16 v[106:109], v[172:175], v[196:199], v[106:109]
	v_mfma_f32_16x16x32_bf16 v[102:105], v[164:167], v[222:225], v[102:105]
	v_mfma_f32_16x16x32_bf16 v[98:101], v[172:175], v[222:225], v[98:101]
	v_mfma_f32_16x16x32_bf16 v[126:129], v[168:171], v[184:187], v[126:129]
	v_mfma_f32_16x16x32_bf16 v[122:125], v[176:179], v[184:187], v[122:125]
	v_mfma_f32_16x16x32_bf16 v[118:121], v[168:171], v[192:195], v[118:121]
	v_mfma_f32_16x16x32_bf16 v[114:117], v[176:179], v[192:195], v[114:117]
	v_mfma_f32_16x16x32_bf16 v[110:113], v[168:171], v[200:203], v[110:113]
	v_mfma_f32_16x16x32_bf16 v[106:109], v[176:179], v[200:203], v[106:109]
	v_mfma_f32_16x16x32_bf16 v[102:105], v[168:171], v[232:235], v[102:105]
	v_mfma_f32_16x16x32_bf16 v[98:101], v[176:179], v[232:235], v[98:101]
	s_setprio 0
	s_barrier
	v_readfirstlane_b32 s1, v155
	v_lshl_add_u64 v[228:229], v[216:217], 0, s[28:29]
	s_mov_b32 m0, s1
	v_readfirstlane_b32 s1, v156
	ds_read_b128 v[236:239], v148 offset:49152
	ds_read_b128 v[240:243], v148 offset:50176
	ds_read_b128 v[244:247], v148 offset:51200
	ds_read_b128 v[248:251], v148 offset:52224
	global_load_lds_dwordx4 v[228:229], off
	v_lshl_add_u64 v[228:229], v[218:219], 0, s[28:29]
	s_mov_b32 m0, s1
	s_nop 0
	global_load_lds_dwordx4 v[228:229], off
	s_waitcnt vmcnt(10)
	s_barrier
	s_waitcnt lgkmcnt(0)
	s_setprio 1
	s_waitcnt lgkmcnt(0)
	v_mfma_f32_16x16x32_bf16 v[94:97], v[236:239], v[180:183], v[94:97]
	v_mfma_f32_16x16x32_bf16 v[90:93], v[244:247], v[180:183], v[90:93]
	v_mfma_f32_16x16x32_bf16 v[86:89], v[236:239], v[188:191], v[86:89]
	v_mfma_f32_16x16x32_bf16 v[82:85], v[244:247], v[188:191], v[82:85]
	v_mfma_f32_16x16x32_bf16 v[78:81], v[236:239], v[196:199], v[78:81]
	v_mfma_f32_16x16x32_bf16 v[74:77], v[244:247], v[196:199], v[74:77]
	v_mfma_f32_16x16x32_bf16 v[70:73], v[236:239], v[222:225], v[70:73]
	v_mfma_f32_16x16x32_bf16 v[66:69], v[244:247], v[222:225], v[66:69]
	v_mfma_f32_16x16x32_bf16 v[94:97], v[240:243], v[184:187], v[94:97]
	v_mfma_f32_16x16x32_bf16 v[90:93], v[248:251], v[184:187], v[90:93]
	v_mfma_f32_16x16x32_bf16 v[86:89], v[240:243], v[192:195], v[86:89]
	v_mfma_f32_16x16x32_bf16 v[82:85], v[248:251], v[192:195], v[82:85]
	v_mfma_f32_16x16x32_bf16 v[78:81], v[240:243], v[200:203], v[78:81]
	v_mfma_f32_16x16x32_bf16 v[74:77], v[248:251], v[200:203], v[74:77]
	v_mfma_f32_16x16x32_bf16 v[70:73], v[240:243], v[232:235], v[70:73]
	v_mfma_f32_16x16x32_bf16 v[66:69], v[248:251], v[232:235], v[66:69]
	s_setprio 0
	v_readfirstlane_b32 s1, v157
	v_lshl_add_u64 v[204:205], v[204:205], 0, s[28:29]
	s_mov_b32 m0, s1
	v_readfirstlane_b32 s1, v158
	s_barrier
	ds_read_b128 v[180:183], v147 offset:49152
	ds_read_b128 v[184:187], v147 offset:50176
	ds_read_b128 v[188:191], v147 offset:51200
	ds_read_b128 v[192:195], v147 offset:52224
	ds_read_b128 v[196:199], v147 offset:53248
	ds_read_b128 v[200:203], v147 offset:54272
	ds_read_b128 v[222:225], v147 offset:55296
	ds_read_b128 v[232:235], v147 offset:56320
	global_load_lds_dwordx4 v[204:205], off
	v_lshl_add_u64 v[204:205], v[210:211], 0, s[28:29]
	s_mov_b32 m0, s1
	s_nop 0
	global_load_lds_dwordx4 v[204:205], off
	s_barrier
	s_waitcnt lgkmcnt(0)
	s_setprio 1
	s_waitcnt lgkmcnt(0)
	v_mfma_f32_16x16x32_bf16 v[62:65], v[164:167], v[180:183], v[62:65]
	v_mfma_f32_16x16x32_bf16 v[58:61], v[172:175], v[180:183], v[58:61]
	v_mfma_f32_16x16x32_bf16 v[54:57], v[164:167], v[188:191], v[54:57]
	v_mfma_f32_16x16x32_bf16 v[50:53], v[172:175], v[188:191], v[50:53]
	v_mfma_f32_16x16x32_bf16 v[46:49], v[164:167], v[196:199], v[46:49]
	v_mfma_f32_16x16x32_bf16 v[42:45], v[172:175], v[196:199], v[42:45]
	v_mfma_f32_16x16x32_bf16 v[38:41], v[164:167], v[222:225], v[38:41]
	v_mfma_f32_16x16x32_bf16 v[34:37], v[172:175], v[222:225], v[34:37]
	v_mfma_f32_16x16x32_bf16 v[62:65], v[168:171], v[184:187], v[62:65]
	v_mfma_f32_16x16x32_bf16 v[58:61], v[176:179], v[184:187], v[58:61]
	v_mfma_f32_16x16x32_bf16 v[54:57], v[168:171], v[192:195], v[54:57]
	v_mfma_f32_16x16x32_bf16 v[50:53], v[176:179], v[192:195], v[50:53]
	v_mfma_f32_16x16x32_bf16 v[46:49], v[168:171], v[200:203], v[46:49]
	v_mfma_f32_16x16x32_bf16 v[42:45], v[176:179], v[200:203], v[42:45]
	v_mfma_f32_16x16x32_bf16 v[38:41], v[168:171], v[232:235], v[38:41]
	v_mfma_f32_16x16x32_bf16 v[34:37], v[176:179], v[232:235], v[34:37]
	s_setprio 0
	s_barrier
	v_readfirstlane_b32 s1, v159
	v_lshl_add_u64 v[164:165], v[216:217], 0, s[68:69]
	s_mov_b32 m0, s1
	v_readfirstlane_b32 s1, v160
	global_load_lds_dwordx4 v[164:165], off
	v_lshl_add_u64 v[164:165], v[218:219], 0, s[68:69]
	s_mov_b32 m0, s1
	s_nop 0
	global_load_lds_dwordx4 v[164:165], off
	s_waitcnt vmcnt(10)
	s_barrier
	s_setprio 1
	v_mfma_f32_16x16x32_bf16 v[30:33], v[236:239], v[180:183], v[30:33]
	v_mfma_f32_16x16x32_bf16 v[26:29], v[244:247], v[180:183], v[26:29]
	v_mfma_f32_16x16x32_bf16 v[22:25], v[236:239], v[188:191], v[22:25]
	v_mfma_f32_16x16x32_bf16 v[18:21], v[244:247], v[188:191], v[18:21]
	v_mfma_f32_16x16x32_bf16 v[14:17], v[236:239], v[196:199], v[14:17]
	v_mfma_f32_16x16x32_bf16 v[10:13], v[244:247], v[196:199], v[10:13]
	v_mfma_f32_16x16x32_bf16 v[6:9], v[236:239], v[222:225], v[6:9]
	v_mfma_f32_16x16x32_bf16 v[2:5], v[244:247], v[222:225], v[2:5]
	v_mfma_f32_16x16x32_bf16 v[30:33], v[240:243], v[184:187], v[30:33]
	v_mfma_f32_16x16x32_bf16 v[26:29], v[248:251], v[184:187], v[26:29]
	v_mfma_f32_16x16x32_bf16 v[22:25], v[240:243], v[192:195], v[22:25]
	v_mfma_f32_16x16x32_bf16 v[18:21], v[248:251], v[192:195], v[18:21]
	v_mfma_f32_16x16x32_bf16 v[14:17], v[240:243], v[200:203], v[14:17]
	v_mfma_f32_16x16x32_bf16 v[10:13], v[248:251], v[200:203], v[10:13]
	v_mfma_f32_16x16x32_bf16 v[6:9], v[240:243], v[232:235], v[6:9]
	v_mfma_f32_16x16x32_bf16 v[2:5], v[248:251], v[232:235], v[2:5]
	s_setprio 0
	s_add_i32 s0, s0, 2
	s_add_u32 s10, s10, 0x100
	s_addc_u32 s11, s11, 0
	s_cmpk_lt_u32 s0, 0x54
	s_barrier
	s_cbranch_scc1 .LBB0_761
	s_add_u32 s0, s8, 0x162b80
	s_addc_u32 s1, s9, 0
	v_readfirstlane_b32 s8, v161
	v_lshl_add_u64 v[158:159], s[0:1], 0, v[0:1]
	s_mov_b32 m0, s8
	v_lshl_add_u64 v[130:131], s[0:1], 0, v[130:131]
	v_readfirstlane_b32 s0, v162
	ds_read_b128 v[132:135], v148
	ds_read_b128 v[136:139], v148 offset:1024
	ds_read_b128 v[150:153], v148 offset:2048
	ds_read_b128 v[154:157], v148 offset:3072
	ds_read_b128 v[164:167], v147
	ds_read_b128 v[168:171], v147 offset:1024
	ds_read_b128 v[172:175], v147 offset:2048
	ds_read_b128 v[176:179], v147 offset:3072
	ds_read_b128 v[180:183], v147 offset:4096
	ds_read_b128 v[184:187], v147 offset:5120
	ds_read_b128 v[188:191], v147 offset:6144
	ds_read_b128 v[192:195], v147 offset:7168
	global_load_lds_dwordx4 v[158:159], off
	s_mov_b32 m0, s0
	s_nop 0
	global_load_lds_dwordx4 v[130:131], off
	s_barrier
	s_waitcnt lgkmcnt(0)
	s_setprio 1
	s_waitcnt lgkmcnt(0)
	v_mfma_f32_16x16x32_bf16 v[122:125], v[150:153], v[164:167], v[122:125]
	v_mfma_f32_16x16x32_bf16 v[118:121], v[132:135], v[172:175], v[118:121]
	v_mfma_f32_16x16x32_bf16 v[114:117], v[150:153], v[172:175], v[114:117]
	v_mfma_f32_16x16x32_bf16 v[102:105], v[132:135], v[188:191], v[102:105]
	v_mfma_f32_16x16x32_bf16 v[98:101], v[150:153], v[188:191], v[98:101]
	v_mfma_f32_16x16x32_bf16 v[126:129], v[132:135], v[164:167], v[126:129]
	v_mfma_f32_16x16x32_bf16 v[122:125], v[154:157], v[168:171], v[122:125]
	v_mfma_f32_16x16x32_bf16 v[118:121], v[136:139], v[176:179], v[118:121]
	v_mfma_f32_16x16x32_bf16 v[114:117], v[154:157], v[176:179], v[114:117]
	v_mfma_f32_16x16x32_bf16 v[110:113], v[132:135], v[180:183], v[110:113]
	v_mfma_f32_16x16x32_bf16 v[106:109], v[150:153], v[180:183], v[106:109]
	v_mfma_f32_16x16x32_bf16 v[102:105], v[136:139], v[192:195], v[102:105]
	v_mfma_f32_16x16x32_bf16 v[98:101], v[154:157], v[192:195], v[98:101]
	v_mfma_f32_16x16x32_bf16 v[126:129], v[136:139], v[168:171], v[126:129]
	v_mfma_f32_16x16x32_bf16 v[158:161], v[136:139], v[184:187], v[110:113]
	v_mfma_f32_16x16x32_bf16 v[196:199], v[154:157], v[184:187], v[106:109]
	s_setprio 0
	s_barrier
	ds_read_b128 v[106:109], v148 offset:16384
	ds_read_b128 v[110:113], v148 offset:17408
	ds_read_b128 v[200:203], v148 offset:18432
	ds_read_b128 v[222:225], v148 offset:19456
	s_barrier
	s_waitcnt lgkmcnt(0)
	s_setprio 1
	s_waitcnt lgkmcnt(3)
	v_mfma_f32_16x16x32_bf16 v[86:89], v[106:109], v[172:175], v[86:89]
	s_waitcnt lgkmcnt(1)
	v_mfma_f32_16x16x32_bf16 v[82:85], v[200:203], v[172:175], v[82:85]
	v_mfma_f32_16x16x32_bf16 v[70:73], v[106:109], v[188:191], v[70:73]
	v_mfma_f32_16x16x32_bf16 v[66:69], v[200:203], v[188:191], v[66:69]
	v_mfma_f32_16x16x32_bf16 v[94:97], v[106:109], v[164:167], v[94:97]
	v_mfma_f32_16x16x32_bf16 v[90:93], v[200:203], v[164:167], v[90:93]
	v_mfma_f32_16x16x32_bf16 v[86:89], v[110:113], v[176:179], v[86:89]
	s_waitcnt lgkmcnt(0)
	v_mfma_f32_16x16x32_bf16 v[82:85], v[222:225], v[176:179], v[82:85]
	v_mfma_f32_16x16x32_bf16 v[78:81], v[106:109], v[180:183], v[78:81]
	v_mfma_f32_16x16x32_bf16 v[74:77], v[200:203], v[180:183], v[74:77]
	v_mfma_f32_16x16x32_bf16 v[70:73], v[110:113], v[192:195], v[70:73]
	v_mfma_f32_16x16x32_bf16 v[66:69], v[222:225], v[192:195], v[66:69]
	v_mfma_f32_16x16x32_bf16 v[232:235], v[110:113], v[168:171], v[94:97]
	v_mfma_f32_16x16x32_bf16 v[162:165], v[222:225], v[168:171], v[90:93]
	v_mfma_f32_16x16x32_bf16 v[166:169], v[110:113], v[184:187], v[78:81]
	v_mfma_f32_16x16x32_bf16 v[170:173], v[222:225], v[184:187], v[74:77]
	s_setprio 0
	s_barrier
	s_nop 0
	ds_read_b128 v[74:77], v147 offset:16384
	ds_read_b128 v[78:81], v147 offset:17408
	ds_read_b128 v[90:93], v147 offset:18432
	ds_read_b128 v[94:97], v147 offset:19456
	ds_read_b128 v[174:177], v147 offset:20480
	ds_read_b128 v[178:181], v147 offset:21504
	ds_read_b128 v[182:185], v147 offset:22528
	ds_read_b128 v[186:189], v147 offset:23552
	s_waitcnt vmcnt(4)
	s_barrier
	s_waitcnt lgkmcnt(0)
	s_setprio 1
	s_waitcnt lgkmcnt(7)
	v_mfma_f32_16x16x32_bf16 v[62:65], v[132:135], v[74:77], v[62:65]
	v_mfma_f32_16x16x32_bf16 v[58:61], v[150:153], v[74:77], v[58:61]
	s_waitcnt lgkmcnt(5)
	v_mfma_f32_16x16x32_bf16 v[54:57], v[132:135], v[90:93], v[54:57]
	v_mfma_f32_16x16x32_bf16 v[50:53], v[150:153], v[90:93], v[50:53]
	s_waitcnt lgkmcnt(1)
	v_mfma_f32_16x16x32_bf16 v[38:41], v[132:135], v[182:185], v[38:41]
	v_mfma_f32_16x16x32_bf16 v[34:37], v[150:153], v[182:185], v[34:37]
	v_mfma_f32_16x16x32_bf16 v[62:65], v[136:139], v[78:81], v[62:65]
	v_mfma_f32_16x16x32_bf16 v[58:61], v[154:157], v[78:81], v[58:61]
	v_mfma_f32_16x16x32_bf16 v[54:57], v[136:139], v[94:97], v[54:57]
	v_mfma_f32_16x16x32_bf16 v[50:53], v[154:157], v[94:97], v[50:53]
	v_mfma_f32_16x16x32_bf16 v[46:49], v[132:135], v[174:177], v[46:49]
	v_mfma_f32_16x16x32_bf16 v[42:45], v[150:153], v[174:177], v[42:45]
	s_waitcnt lgkmcnt(0)
	v_mfma_f32_16x16x32_bf16 v[38:41], v[136:139], v[186:189], v[38:41]
	v_mfma_f32_16x16x32_bf16 v[34:37], v[154:157], v[186:189], v[34:37]
	v_mfma_f32_16x16x32_bf16 v[190:193], v[136:139], v[178:181], v[46:49]
	v_mfma_f32_16x16x32_bf16 v[236:239], v[154:157], v[178:181], v[42:45]
	s_setprio 0
	s_setprio 1
	v_mfma_f32_16x16x32_bf16 v[22:25], v[106:109], v[90:93], v[22:25]
	v_mfma_f32_16x16x32_bf16 v[18:21], v[200:203], v[90:93], v[18:21]
	v_mfma_f32_16x16x32_bf16 v[6:9], v[106:109], v[182:185], v[6:9]
	v_mfma_f32_16x16x32_bf16 v[2:5], v[200:203], v[182:185], v[2:5]
	v_mfma_f32_16x16x32_bf16 v[30:33], v[106:109], v[74:77], v[30:33]
	v_mfma_f32_16x16x32_bf16 v[26:29], v[200:203], v[74:77], v[26:29]
	v_mfma_f32_16x16x32_bf16 v[22:25], v[110:113], v[94:97], v[22:25]
	v_mfma_f32_16x16x32_bf16 v[18:21], v[222:225], v[94:97], v[18:21]
	v_mfma_f32_16x16x32_bf16 v[14:17], v[106:109], v[174:177], v[14:17]
	v_mfma_f32_16x16x32_bf16 v[10:13], v[200:203], v[174:177], v[10:13]
	v_mfma_f32_16x16x32_bf16 v[6:9], v[110:113], v[186:189], v[6:9]
	v_mfma_f32_16x16x32_bf16 v[2:5], v[222:225], v[186:189], v[2:5]
	v_mfma_f32_16x16x32_bf16 v[134:137], v[110:113], v[78:81], v[30:33]
	v_mfma_f32_16x16x32_bf16 v[150:153], v[222:225], v[78:81], v[26:29]
	v_mfma_f32_16x16x32_bf16 v[154:157], v[110:113], v[178:181], v[14:17]
	v_mfma_f32_16x16x32_bf16 v[174:177], v[222:225], v[178:181], v[10:13]
	s_setprio 0
	s_barrier
	s_nop 0
	ds_read_b128 v[10:13], v148 offset:32768
	ds_read_b128 v[14:17], v148 offset:33792
	ds_read_b128 v[178:181], v148 offset:34816
	ds_read_b128 v[182:185], v148 offset:35840
	ds_read_b128 v[26:29], v147 offset:32768
	ds_read_b128 v[30:33], v147 offset:33792
	ds_read_b128 v[42:45], v147 offset:34816
	ds_read_b128 v[46:49], v147 offset:35840
	ds_read_b128 v[186:189], v147 offset:36864
	ds_read_b128 v[200:203], v147 offset:37888
	ds_read_b128 v[222:225], v147 offset:38912
	ds_read_b128 v[240:243], v147 offset:39936
	s_waitcnt vmcnt(2)
	s_barrier
	s_waitcnt lgkmcnt(0)
	s_setprio 1
	s_waitcnt lgkmcnt(7)
	v_mfma_f32_16x16x32_bf16 v[74:77], v[10:13], v[26:29], v[126:129]
	s_waitcnt lgkmcnt(6)
	v_mfma_f32_16x16x32_bf16 v[130:133], v[14:17], v[30:33], v[74:77]
	v_mfma_f32_16x16x32_bf16 v[74:77], v[178:181], v[26:29], v[122:125]
	v_mfma_f32_16x16x32_bf16 v[122:125], v[182:185], v[30:33], v[74:77]
	s_waitcnt lgkmcnt(5)
	v_mfma_f32_16x16x32_bf16 v[74:77], v[10:13], v[42:45], v[118:121]
	s_waitcnt lgkmcnt(4)
	v_mfma_f32_16x16x32_bf16 v[110:113], v[14:17], v[46:49], v[74:77]
	v_mfma_f32_16x16x32_bf16 v[74:77], v[178:181], v[42:45], v[114:117]
	v_mfma_f32_16x16x32_bf16 v[106:109], v[182:185], v[46:49], v[74:77]
	s_waitcnt lgkmcnt(3)
	v_mfma_f32_16x16x32_bf16 v[74:77], v[10:13], v[186:189], v[158:161]
	s_waitcnt lgkmcnt(2)
	v_mfma_f32_16x16x32_bf16 v[94:97], v[14:17], v[200:203], v[74:77]
	v_mfma_f32_16x16x32_bf16 v[74:77], v[178:181], v[186:189], v[196:199]
	v_mfma_f32_16x16x32_bf16 v[90:93], v[182:185], v[200:203], v[74:77]
	s_waitcnt lgkmcnt(1)
	v_mfma_f32_16x16x32_bf16 v[74:77], v[10:13], v[222:225], v[102:105]
	s_waitcnt lgkmcnt(0)
	v_mfma_f32_16x16x32_bf16 v[78:81], v[14:17], v[240:243], v[74:77]
	v_mfma_f32_16x16x32_bf16 v[74:77], v[178:181], v[222:225], v[98:101]
	v_mfma_f32_16x16x32_bf16 v[74:77], v[182:185], v[240:243], v[74:77]
	s_setprio 0
	s_barrier
	ds_read_b128 v[126:129], v148 offset:49152
	ds_read_b128 v[158:161], v148 offset:50176
	ds_read_b128 v[194:197], v148 offset:51200
	ds_read_b128 v[244:247], v148 offset:52224
	s_waitcnt vmcnt(0)
	s_barrier
	s_waitcnt lgkmcnt(0)
	s_setprio 1
	s_waitcnt lgkmcnt(3)
	v_mfma_f32_16x16x32_bf16 v[98:101], v[126:129], v[26:29], v[232:235]
	s_waitcnt lgkmcnt(1)
	v_mfma_f32_16x16x32_bf16 v[26:29], v[194:197], v[26:29], v[162:165]
	s_waitcnt lgkmcnt(0)
	v_mfma_f32_16x16x32_bf16 v[114:117], v[244:247], v[30:33], v[26:29]
	v_mfma_f32_16x16x32_bf16 v[26:29], v[126:129], v[42:45], v[86:89]
	v_mfma_f32_16x16x32_bf16 v[102:105], v[158:161], v[46:49], v[26:29]
	v_mfma_f32_16x16x32_bf16 v[26:29], v[194:197], v[42:45], v[82:85]
	v_mfma_f32_16x16x32_bf16 v[118:121], v[158:161], v[30:33], v[98:101]
	v_mfma_f32_16x16x32_bf16 v[98:101], v[244:247], v[46:49], v[26:29]
	v_mfma_f32_16x16x32_bf16 v[26:29], v[126:129], v[186:189], v[166:169]
	v_mfma_f32_16x16x32_bf16 v[86:89], v[158:161], v[200:203], v[26:29]
	v_mfma_f32_16x16x32_bf16 v[26:29], v[194:197], v[186:189], v[170:173]
	v_mfma_f32_16x16x32_bf16 v[82:85], v[244:247], v[200:203], v[26:29]
	v_mfma_f32_16x16x32_bf16 v[26:29], v[126:129], v[222:225], v[70:73]
	v_mfma_f32_16x16x32_bf16 v[70:73], v[158:161], v[240:243], v[26:29]
	v_mfma_f32_16x16x32_bf16 v[26:29], v[194:197], v[222:225], v[66:69]
	v_mfma_f32_16x16x32_bf16 v[66:69], v[244:247], v[240:243], v[26:29]
	s_setprio 0
	s_barrier
	ds_read_b128 v[162:165], v147 offset:49152
	ds_read_b128 v[166:169], v147 offset:50176
	ds_read_b128 v[170:173], v147 offset:51200
	ds_read_b128 v[186:189], v147 offset:52224
	ds_read_b128 v[198:201], v147 offset:53248
	ds_read_b128 v[202:205], v147 offset:54272
	ds_read_b128 v[222:225], v147 offset:55296
	ds_read_b128 v[146:149], v147 offset:56320
	s_barrier
	s_waitcnt lgkmcnt(0)
	s_setprio 1
	s_waitcnt lgkmcnt(7)
	v_mfma_f32_16x16x32_bf16 v[26:29], v[10:13], v[162:165], v[62:65]
	s_waitcnt lgkmcnt(6)
	v_mfma_f32_16x16x32_bf16 v[62:65], v[14:17], v[166:169], v[26:29]
	v_mfma_f32_16x16x32_bf16 v[26:29], v[178:181], v[162:165], v[58:61]
	v_mfma_f32_16x16x32_bf16 v[58:61], v[182:185], v[166:169], v[26:29]
	s_waitcnt lgkmcnt(5)
	v_mfma_f32_16x16x32_bf16 v[26:29], v[10:13], v[170:173], v[54:57]
	s_waitcnt lgkmcnt(4)
	v_mfma_f32_16x16x32_bf16 v[46:49], v[14:17], v[186:189], v[26:29]
	v_mfma_f32_16x16x32_bf16 v[26:29], v[178:181], v[170:173], v[50:53]
	v_mfma_f32_16x16x32_bf16 v[42:45], v[182:185], v[186:189], v[26:29]
	s_waitcnt lgkmcnt(3)
	v_mfma_f32_16x16x32_bf16 v[26:29], v[10:13], v[198:201], v[190:193]
	s_waitcnt lgkmcnt(1)
	v_mfma_f32_16x16x32_bf16 v[10:13], v[10:13], v[222:225], v[38:41]
	v_mfma_f32_16x16x32_bf16 v[30:33], v[14:17], v[202:205], v[26:29]
	v_mfma_f32_16x16x32_bf16 v[26:29], v[178:181], v[198:201], v[236:239]
	s_waitcnt lgkmcnt(0)
	v_mfma_f32_16x16x32_bf16 v[14:17], v[14:17], v[146:149], v[10:13]
	v_mfma_f32_16x16x32_bf16 v[10:13], v[178:181], v[222:225], v[34:37]
	v_mfma_f32_16x16x32_bf16 v[26:29], v[182:185], v[202:205], v[26:29]
	v_mfma_f32_16x16x32_bf16 v[10:13], v[182:185], v[146:149], v[10:13]
	s_setprio 0
	s_setprio 1
	v_mfma_f32_16x16x32_bf16 v[34:37], v[126:129], v[162:165], v[134:137]
	v_mfma_f32_16x16x32_bf16 v[54:57], v[158:161], v[166:169], v[34:37]
	v_mfma_f32_16x16x32_bf16 v[34:37], v[194:197], v[162:165], v[150:153]
	v_mfma_f32_16x16x32_bf16 v[18:21], v[194:197], v[170:173], v[18:21]
	v_mfma_f32_16x16x32_bf16 v[50:53], v[244:247], v[166:169], v[34:37]
	v_mfma_f32_16x16x32_bf16 v[22:25], v[126:129], v[170:173], v[22:25]
	v_mfma_f32_16x16x32_bf16 v[34:37], v[244:247], v[186:189], v[18:21]
	v_mfma_f32_16x16x32_bf16 v[18:21], v[126:129], v[198:201], v[154:157]
	v_mfma_f32_16x16x32_bf16 v[38:41], v[158:161], v[186:189], v[22:25]
	v_mfma_f32_16x16x32_bf16 v[22:25], v[158:161], v[202:205], v[18:21]
	v_mfma_f32_16x16x32_bf16 v[18:21], v[194:197], v[198:201], v[174:177]
	v_mfma_f32_16x16x32_bf16 v[6:9], v[126:129], v[222:225], v[6:9]
	v_mfma_f32_16x16x32_bf16 v[2:5], v[194:197], v[222:225], v[2:5]
	v_mfma_f32_16x16x32_bf16 v[18:21], v[244:247], v[202:205], v[18:21]
	v_mfma_f32_16x16x32_bf16 v[6:9], v[158:161], v[146:149], v[6:9]
	v_mfma_f32_16x16x32_bf16 v[2:5], v[244:247], v[146:149], v[2:5]
	s_setprio 0
	s_movk_i32 s0, 0x100
	v_cmp_gt_u32_e32 vcc, s0, v140
	s_barrier
	s_and_saveexec_b64 s[0:1], vcc
	s_cbranch_execz .LBB0_764
	s_barrier
